# P1: wave owns 64 contiguous out columns (B-panel row permutation), epilogue stores full 128B lines via DPP row exchange
# speedup vs baseline: 1.0344x; 1.0176x over previous
; #define PG8_STAGE(bufoff, gbase, voff) do { _Pragma("unroll") for (int _i = 0; _i < 2; ++_i) \
;         __builtin_amdgcn_global_load_lds((const unsigned*)((const char*)(gbase) + (voff)[_i]), (PG8_LAS unsigned*)(lds + (bufoff) + ldsw + _i * 8192), 16, 0, 0); } while (0)
; #define PG8_WAIT_V(n) asm volatile("s_waitcnt vmcnt(" #n ")" ::: "memory")
; #define PG8_BAR __builtin_amdgcn_s_barrier()
; template <class Epi, class Sched>
; __device__ __forceinline__ void gemm_phase(PG8_LAS unsigned char* lds, const Gemm g, const Sched& S, const Epi& E) {
;     ...
;     const int tid = tid_, wid = __builtin_amdgcn_readfirstlane(tid >> 6), lane = tid & 63, wr = wid >> 2, wc = wid & 3, fr = lane & 15, fq = lane >> 4;
;     const int K = g.K, nt = K / BK;
;     unsigned voffA[2], voffB[2];
; #pragma unroll
;     for (int i = 0; i < 2; ++i) { int R, C; stage_rc(tid * 16 + i * 8192, R, C); const int Rb = (R & ~31) + perm32(R & 31);
;         voffA[i] = (unsigned)(R * g.lda + C) * 2u; voffB[i] = (unsigned)(Rb * g.ldb + C) * 2u; }
;     const size_t kstep = (size_t)(BK * 2);
;     const size_t hstepA = (size_t)HALF * g.lda * 2, hstepB = (size_t)HALF * g.ldb * 2;
;     const unsigned ldsw = (unsigned)wid * 1024u;
;     const int aoff = lds_byte(wr * 64 + fr, fq * 8), boff = lds_byte(wc * 32 + fr, fq * 8);
;     ...
;     Unit cur, nxt; int ui = 0;
;     if (!S.next(0, cur)) return;
;     f32x4 acc[2][2][4][2];
; #pragma unroll
;     for (int a = 0; a < 2; ++a)
; #pragma unroll
;         for (int b = 0; b < 2; ++b)
; #pragma unroll
;             for (int m = 0; m < 4; ++m)
; #pragma unroll
;                 for (int n = 0; n < 2; ++n) acc[a][b][m][n] = (f32x4){0.f, 0.f, 0.f, 0.f};
;     bf16x8 At[4][2], B0[2][2], B1[2][2];
;     const char* cA = (const char*)cur.A; const char* cB = (const char*)cur.B;
;     PG8_STAGE(PG8_SB(0, 0), cB, voffB); PG8_STAGE(PG8_SB(0, 1), cB + hstepB, voffB); PG8_STAGE(PG8_SA(0, 0), cA, voffA); PG8_STAGE(PG8_SA(0, 1), cA + hstepA, voffA);
;     if (wr == 1) PG8_BAR;
;     PG8_WAIT_V(2); PG8_BAR;
;     PG8_STAGE(PG8_SB(1, 0), cB + kstep, voffB); PG8_STAGE(PG8_SA(1, 0), cA + kstep, voffA); PG8_STAGE(PG8_SB(1, 1), cB + hstepB + kstep, voffB);
;     PG8_WAIT_V(6); PG8_BAR;
.LBB0_152:
	s_andn2_b64 vcc, exec, s[8:9]
	s_lshl_b32 s76, s95, 14
	s_cbranch_vccnz .LBB0_350
	v_ashrrev_i32_e32 v0, 31, v10
	v_lshrrev_b32_e32 v0, 26, v0
	v_add_u32_e32 v0, v10, v0
	v_ashrrev_i32_e32 v11, 6, v0
	v_bfe_i32 v0, v10, 27, 1
	v_lshlrev_b32_e32 v2, 4, v10
	v_lshrrev_b32_e32 v0, 22, v0
	v_add_u32_e32 v0, v2, v0
	v_and_b32_e32 v0, 0xfffffc00, v0
	v_sub_u32_e32 v0, v2, v0
	v_lshrrev_b32_e32 v3, 4, v0
	v_bitop3_b32 v0, v3, v0, 32 bitop3:0x6c
	v_ashrrev_i32_e32 v4, 31, v0
	v_lshrrev_b32_e32 v4, 26, v4
	v_add_u32_e32 v4, v0, v4
	v_lshlrev_b32_e32 v3, 3, v11
	v_ashrrev_i32_e32 v12, 6, v4
	v_and_b32_e32 v4, 0xc0, v4
	v_and_b32_e32 v3, -16, v3
	v_sub_u32_e32 v0, v0, v4
	v_add_u32_e32 v3, v12, v3
	v_ashrrev_i16_sdwa v0, v230, sext(v0) dst_sel:DWORD dst_unused:UNUSED_PAD src0_sel:DWORD src1_sel:BYTE_0
	v_lshlrev_b32_e32 v5, 5, v11
	v_bfe_i32 v13, v0, 0, 16
	v_lshlrev_b32_e32 v0, 1, v3
	v_lshrrev_b32_e32 v4, 2, v3
	v_and_b32_e32 v6, 3, v12
	s_mov_b32 s8, 0x1fffe0
	v_and_b32_e32 v5, 32, v5
	v_and_b32_e32 v0, 24, v0
	v_and_b32_e32 v4, 4, v4
	v_and_or_b32 v6, v3, s8, v6
	v_or3_b32 v0, v6, v4, v0
	v_add_lshl_u32 v4, v5, v13, 1
	v_add_u32_e32 v2, 0x2000, v2
	v_lshl_add_u32 v146, v3, 11, v4
	v_ashrrev_i32_e32 v3, 31, v2
	v_lshrrev_b32_e32 v3, 22, v3
	v_add_u32_e32 v3, v2, v3
	v_ashrrev_i32_e32 v14, 10, v3
	v_mul_i32_i24_e32 v3, 0x400, v14
	v_sub_u32_e32 v2, v2, v3
	v_lshrrev_b32_e32 v3, 4, v2
	v_bitop3_b32 v2, v3, v2, 32 bitop3:0x6c
	v_lshl_add_u32 v0, v0, 11, v4
	v_ashrrev_i32_e32 v4, 31, v2
	v_lshrrev_b32_e32 v4, 26, v4
	v_add_u32_e32 v4, v2, v4
	v_lshlrev_b32_e32 v3, 3, v14
	v_ashrrev_i32_e32 v15, 6, v4
	v_and_b32_e32 v4, 0xc0, v4
	s_ashr_i32 s18, s2, 6
	v_and_b32_e32 v3, -16, v3
	v_sub_u32_e32 v2, v2, v4
	v_add_u32_e32 v3, v15, v3
	v_ashrrev_i16_sdwa v2, v230, sext(v2) dst_sel:DWORD dst_unused:UNUSED_PAD src0_sel:DWORD src1_sel:BYTE_0
	s_lshl_b32 s59, s18, 10
	v_lshlrev_b32_e32 v5, 5, v14
	v_bfe_i32 v16, v2, 0, 16
	v_lshlrev_b32_e32 v2, 1, v3
	v_lshrrev_b32_e32 v4, 2, v3
	v_and_b32_e32 v6, 3, v15
	s_add_i32 s60, s59, 0
	v_and_b32_e32 v5, 32, v5
	v_and_b32_e32 v2, 24, v2
	v_and_b32_e32 v4, 4, v4
	v_and_or_b32 v6, v3, s8, v6
	s_add_i32 m0, s60, 0x10000
	v_or3_b32 v2, v6, v4, v2
	v_add_lshl_u32 v4, v5, v16, 1
	s_ashr_i32 s14, s2, 8
	s_lshl_b32 s99, s14, 16
	v_add_u32_e32 v0, s99, v0
	global_load_lds_dwordx4 v0, s[52:53]
	s_add_i32 m0, s60, 0x12000
	v_lshl_add_u32 v150, v2, 11, v4
	s_add_i32 s99, s99, 0x20000
	v_add_u32_e32 v150, s99, v150
	s_add_u32 s8, s52, 0x10000
	global_load_lds_dwordx4 v150, s[52:53]
	s_addc_u32 s9, s53, 0
	s_add_i32 m0, s60, 0x14000
	s_add_i32 s61, s60, 0x2000
	global_load_lds_dwordx4 v0, s[8:9]
	s_add_i32 m0, s60, 0x16000
	v_lshl_add_u32 v148, v3, 11, v4
	global_load_lds_dwordx4 v150, s[8:9]
	s_mov_b32 m0, s60
	s_add_u32 s8, s6, 0x40000
	global_load_lds_dwordx4 v146, s[6:7]
	s_mov_b32 m0, s61
	s_addc_u32 s9, s7, 0
	s_add_i32 s62, s60, 0x4000
	global_load_lds_dwordx4 v148, s[6:7]
	s_mov_b32 m0, s62
	s_add_i32 s63, s60, 0x6000
	global_load_lds_dwordx4 v146, s[8:9]
	s_mov_b32 m0, s63
	v_mov_b32_e32 v151, v1
	global_load_lds_dwordx4 v148, s[8:9]
	s_load_dwordx2 s[8:9], s[4:5], 0x80
	v_mov_b32_e32 v147, v1
	v_mov_b32_e32 v149, v1
	s_cmp_eq_u32 s14, 1
	v_lshl_add_u64 v[8:9], s[52:53], 0, v[0:1]
	v_lshl_add_u64 v[6:7], s[52:53], 0, v[150:151]
	v_lshl_add_u64 v[2:3], s[6:7], 0, v[146:147]
	s_cselect_b64 s[12:13], -1, 0
	s_cmp_lg_u32 s14, 1
	v_lshl_add_u64 v[4:5], s[6:7], 0, v[148:149]
	s_cbranch_scc1 .LBB0_155
	s_barrier
.LBB0_155:
	s_and_b32 s4, s18, 3
	s_add_i32 m0, s60, 0x18000
	v_lshl_add_u64 v[8:9], v[8:9], 0, s[20:21]
	s_lshl_b32 s64, s14, 6
	s_lshl_b32 s14, s14, 13
	s_lshl_b32 s65, s4, 5
	s_lshl_b32 s15, s4, 12
	s_waitcnt vmcnt(2)
	s_barrier
	global_load_lds_dwordx4 v[8:9], off
	v_lshl_add_u64 v[6:7], v[6:7], 0, s[20:21]
	s_add_i32 m0, s60, 0x1a000
	s_add_i32 s66, s60, 0x8000
	s_add_i32 s67, s60, 0xa000
	global_load_lds_dwordx4 v[6:7], off
	v_lshl_add_u64 v[2:3], v[2:3], 0, s[20:21]
	s_mov_b32 m0, s66
	s_add_u32 s4, s52, 0x10080
	global_load_lds_dwordx4 v[2:3], off
	v_lshl_add_u64 v[2:3], v[4:5], 0, s[20:21]
	s_mov_b32 m0, s67
	s_addc_u32 s5, s53, 0
	global_load_lds_dwordx4 v[2:3], off
	s_add_i32 m0, s60, 0x1c000
	v_lshl_add_u64 v[2:3], s[4:5], 0, v[0:1]
	global_load_lds_dwordx4 v[2:3], off
	v_lshl_add_u64 v[2:3], s[4:5], 0, v[150:151]
	s_add_i32 m0, s60, 0x1e000
	v_bfe_u32 v167, v10, 4, 2
	global_load_lds_dwordx4 v[2:3], off
	v_and_b32_e32 v166, 15, v10
	v_lshlrev_b32_e32 v2, 4, v167
	v_lshlrev_b32_e32 v3, 2, v10
	v_lshl_or_b32 v2, v166, 6, v2
	v_and_b32_e32 v3, 32, v3
	v_bitop3_b32 v4, v2, s14, v3 bitop3:0xde
	v_bitop3_b32 v168, v2, s15, v3 bitop3:0xde
	v_lshlrev_b32_e32 v2, 14, v11
	v_and_b32_e32 v2, 0xffff8000, v2
	v_lshl_add_u32 v2, v12, 11, v2
	v_and_b32_e32 v3, 1, v11
	v_lshl_or_b32 v2, v3, 6, v2
	v_lshl_add_u32 v152, v13, 1, v2
	v_lshlrev_b32_e32 v2, 14, v14
	v_and_b32_e32 v2, 0xffff8000, v2
	s_waitcnt vmcnt(6)
	v_lshl_add_u32 v2, v15, 11, v2
	v_and_b32_e32 v3, 1, v14
	s_cmpk_lt_u32 s2, 0x100
	v_lshl_or_b32 v2, v3, 6, v2
	s_cselect_b64 s[14:15], -1, 0
	s_bfe_u32 s68, s18, 0x10001
	s_bfe_u32 s69, s2, 0x10006
	s_ashr_i32 s70, s97, 31
	s_ashr_i32 s71, s96, 31
	v_mov_b32_e32 v153, v1
	v_lshl_add_u32 v154, v16, 1, v2
	v_mov_b32_e32 v155, v1
	s_mov_b32 s72, 0
	v_add_u32_e32 v169, 0, v4
	s_lshl_b32 s73, s65, 2
	s_mov_b64 s[44:45], s[52:53]
	s_mov_b64 s[42:43], s[6:7]
	s_barrier
	s_branch .LBB0_158

; #define PG8_STAGE(bufoff, gbase, voff) do { _Pragma("unroll") for (int _i = 0; _i < 2; ++_i) \
;         __builtin_amdgcn_global_load_lds((const unsigned*)((const char*)(gbase) + (voff)[_i]), (PG8_LAS unsigned*)(lds + (bufoff) + ldsw + _i * 8192), 16, 0, 0); } while (0)
; #define PG8_LDA(dst, b, h) do { _Pragma("unroll") for (int m = 0; m < 4; ++m) _Pragma("unroll") for (int k = 0; k < 2; ++k) dst[m][k] = *(const PG8_LAS bf16x8*)(lds + PG8_SA(b, h) + aoff + m * 2048 + k * 1024); } while (0)
; #define PG8_LDB(dst, b, h) do { _Pragma("unroll") for (int n = 0; n < 2; ++n) _Pragma("unroll") for (int k = 0; k < 2; ++k) dst[n][k] = *(const PG8_LAS bf16x8*)(lds + PG8_SB(b, h) + boff + n * 2048 + k * 1024); } while (0)
; #define PG8_MMA(ai, bj, At, Bt) do { __builtin_amdgcn_s_setprio(1); _Pragma("unroll") for (int m = 0; m < 4; ++m) _Pragma("unroll") for (int n = 0; n < 2; ++n) _Pragma("unroll") for (int k = 0; k < 2; ++k) \
;         acc[ai][bj][m][n] = __builtin_amdgcn_mfma_f32_16x16x32_bf16(Bt[n][k], At[m][k], acc[ai][bj][m][n], 0, 0, 0); __builtin_amdgcn_s_setprio(0); } while (0)
; template <class Epi, class Sched>
; __device__ __forceinline__ void gemm_phase(PG8_LAS unsigned char* lds, const Gemm g, const Sched& S, const Epi& E) {
;     ...
;         for (int t = 0; t < nt; t += 2) {
;             const bool last = (t == nt - 2);
;             const char* a1 = cA + (size_t)(t + 1) * kstep;
;             const char* a2 = last ? nA : cA + (size_t)(t + 2) * kstep; const char* b2 = last ? nB : cB + (size_t)(t + 2) * kstep;
;             const char* a3 = a2 + kstep; const char* b3 = b2 + kstep;
;             PG8_LDB(B0, 0, 0); PG8_LDB(B1, 0, 1); PG8_SCHED; PG8_LDA(At, 0, 0); PG8_STAGE(PG8_SA(1, 1), a1 + hstepA, voffA);
;             PG8_WAIT_V(8); PG8_WAIT_L(0); PG8_BAR; PG8_MMA(0, 0, At, B0); PG8_MMA(0, 1, At, B1); PG8_BAR; PG8_SCHED;
;             PG8_LDA(At, 0, 1); PG8_STAGE(PG8_SB(0, 0), b2, voffB); PG8_STAGE(PG8_SB(0, 1), b2 + hstepB, voffB); PG8_STAGE(PG8_SA(0, 0), a2, voffA);
;             PG8_WAIT_V(8); PG8_WAIT_L(0); PG8_BAR; PG8_MMA(1, 0, At, B0); PG8_MMA(1, 1, At, B1); PG8_BAR; PG8_SCHED;
;             PG8_LDB(B0, 1, 0); PG8_LDB(B1, 1, 1); PG8_SCHED; PG8_LDA(At, 1, 0); PG8_STAGE(PG8_SA(0, 1), a2 + hstepA, voffA);
;             PG8_WAIT_V(8); PG8_WAIT_L(0); PG8_BAR; PG8_MMA(0, 0, At, B0); PG8_MMA(0, 1, At, B1); PG8_BAR; PG8_SCHED;
.LBB0_161:
	s_add_u32 s41, s6, 0xfffc0080
	s_addc_u32 s49, s7, -1
	s_add_i32 s57, 0, 0x10000
	s_cmp_eq_u32 s39, 12
	s_cselect_b32 s55, s43, s49
	s_cselect_b32 s54, s42, s41
	s_cselect_b32 s53, s45, s18
	s_cselect_b32 s52, s44, s2
	s_add_i32 s41, 0, 0x14000
	v_add_u32_e32 v142, s57, v168
	v_add_u32_e32 v164, s41, v168
	ds_read_b128 v[130:133], v142
	ds_read_b128 v[134:137], v142 offset:1024
	ds_read_b128 v[138:141], v142 offset:2048
	ds_read_b128 v[142:145], v142 offset:3072
	ds_read_b128 v[156:159], v164
	ds_read_b128 v[160:163], v164 offset:1024
	ds_read_b128 v[170:173], v164 offset:2048
	ds_read_b128 v[174:177], v164 offset:3072
	v_lshl_add_u64 v[164:165], s[6:7], 0, v[152:153]
	s_add_i32 m0, s60, 0xc000
	ds_read_b128 v[178:181], v169
	ds_read_b128 v[182:185], v169 offset:1024
	ds_read_b128 v[186:189], v169 offset:2048
	ds_read_b128 v[190:193], v169 offset:3072
	ds_read_b128 v[202:205], v169 offset:4096
	ds_read_b128 v[206:209], v169 offset:5120
	ds_read_b128 v[210:213], v169 offset:6144
	ds_read_b128 v[214:217], v169 offset:7168
	global_load_lds_dwordx4 v[164:165], off
	v_lshl_add_u64 v[164:165], s[6:7], 0, v[154:155]
	s_add_i32 m0, s60, 0xe000
	s_nop 0
	global_load_lds_dwordx4 v[164:165], off
	s_waitcnt vmcnt(8)
	s_waitcnt lgkmcnt(0)
	s_barrier
	s_setprio 1
	s_waitcnt lgkmcnt(0)
	v_mfma_f32_16x16x32_bf16 v[126:129], v[130:133], v[178:181], v[126:129]
	v_mfma_f32_16x16x32_bf16 v[122:125], v[138:141], v[178:181], v[122:125]
	v_mfma_f32_16x16x32_bf16 v[118:121], v[130:133], v[186:189], v[118:121]
	v_mfma_f32_16x16x32_bf16 v[114:117], v[138:141], v[186:189], v[114:117]
	v_mfma_f32_16x16x32_bf16 v[110:113], v[130:133], v[202:205], v[110:113]
	v_mfma_f32_16x16x32_bf16 v[106:109], v[138:141], v[202:205], v[106:109]
	v_mfma_f32_16x16x32_bf16 v[102:105], v[130:133], v[210:213], v[102:105]
	v_mfma_f32_16x16x32_bf16 v[98:101], v[138:141], v[210:213], v[98:101]
	v_mfma_f32_16x16x32_bf16 v[126:129], v[134:137], v[182:185], v[126:129]
	v_mfma_f32_16x16x32_bf16 v[122:125], v[142:145], v[182:185], v[122:125]
	v_mfma_f32_16x16x32_bf16 v[118:121], v[134:137], v[190:193], v[118:121]
	v_mfma_f32_16x16x32_bf16 v[114:117], v[142:145], v[190:193], v[114:117]
	v_mfma_f32_16x16x32_bf16 v[110:113], v[134:137], v[206:209], v[110:113]
	v_mfma_f32_16x16x32_bf16 v[106:109], v[142:145], v[206:209], v[106:109]
	v_mfma_f32_16x16x32_bf16 v[102:105], v[134:137], v[214:217], v[102:105]
	v_mfma_f32_16x16x32_bf16 v[98:101], v[142:145], v[214:217], v[98:101]
	s_setprio 0
	s_setprio 1
	v_mfma_f32_16x16x32_bf16 v[62:65], v[156:159], v[178:181], v[62:65]
	v_mfma_f32_16x16x32_bf16 v[58:61], v[170:173], v[178:181], v[58:61]
	v_mfma_f32_16x16x32_bf16 v[54:57], v[156:159], v[186:189], v[54:57]
	v_mfma_f32_16x16x32_bf16 v[50:53], v[170:173], v[186:189], v[50:53]
	v_mfma_f32_16x16x32_bf16 v[46:49], v[156:159], v[202:205], v[46:49]
	v_mfma_f32_16x16x32_bf16 v[42:45], v[170:173], v[202:205], v[42:45]
	v_mfma_f32_16x16x32_bf16 v[38:41], v[156:159], v[210:213], v[38:41]
	v_mfma_f32_16x16x32_bf16 v[34:37], v[170:173], v[210:213], v[34:37]
	v_mfma_f32_16x16x32_bf16 v[62:65], v[160:163], v[182:185], v[62:65]
	v_mfma_f32_16x16x32_bf16 v[58:61], v[174:177], v[182:185], v[58:61]
	v_mfma_f32_16x16x32_bf16 v[54:57], v[160:163], v[190:193], v[54:57]
	v_mfma_f32_16x16x32_bf16 v[50:53], v[174:177], v[190:193], v[50:53]
	v_mfma_f32_16x16x32_bf16 v[46:49], v[160:163], v[206:209], v[46:49]
	v_mfma_f32_16x16x32_bf16 v[42:45], v[174:177], v[206:209], v[42:45]
	v_mfma_f32_16x16x32_bf16 v[38:41], v[160:163], v[214:217], v[38:41]
	v_mfma_f32_16x16x32_bf16 v[34:37], v[174:177], v[214:217], v[34:37]
	s_setprio 0
	s_barrier
	s_add_i32 s49, s57, s59
	v_lshl_add_u64 v[164:165], s[52:53], 0, v[0:1]
	s_mov_b32 m0, s49
	ds_read_b128 v[178:181], v169 offset:16384
	ds_read_b128 v[182:185], v169 offset:17408
	ds_read_b128 v[186:189], v169 offset:18432
	ds_read_b128 v[190:193], v169 offset:19456
	ds_read_b128 v[202:205], v169 offset:20480
	ds_read_b128 v[206:209], v169 offset:21504
	ds_read_b128 v[210:213], v169 offset:22528
	ds_read_b128 v[214:217], v169 offset:23552
	global_load_lds_dwordx4 v[164:165], off
	s_add_i32 m0, s49, 0x2000
	s_add_u32 s74, s52, 0x10000
	v_lshl_add_u64 v[194:195], s[52:53], 0, v[150:151]
	s_addc_u32 s75, s53, 0
	s_add_i32 s41, s41, s59
	global_load_lds_dwordx4 v[194:195], off
	v_lshl_add_u64 v[196:197], s[74:75], 0, v[0:1]
	s_mov_b32 m0, s41
	v_lshl_add_u64 v[218:219], s[54:55], 0, v[148:149]
	global_load_lds_dwordx4 v[196:197], off
	v_lshl_add_u64 v[196:197], s[74:75], 0, v[150:151]
	s_add_i32 m0, s41, 0x2000
	s_nop 0
	global_load_lds_dwordx4 v[196:197], off
	v_lshl_add_u64 v[196:197], s[54:55], 0, v[146:147]
	s_mov_b32 m0, s60
	s_nop 0
	global_load_lds_dwordx4 v[196:197], off
	s_mov_b32 m0, s61
	s_nop 0
	global_load_lds_dwordx4 v[218:219], off
	s_waitcnt vmcnt(8)
	s_waitcnt lgkmcnt(0)
	s_barrier
; #define PG8_STAGE(bufoff, gbase, voff) do { _Pragma("unroll") for (int _i = 0; _i < 2; ++_i) \
;         __builtin_amdgcn_global_load_lds((const unsigned*)((const char*)(gbase) + (voff)[_i]), (PG8_LAS unsigned*)(lds + (bufoff) + ldsw + _i * 8192), 16, 0, 0); } while (0)
; #define PG8_LDA(dst, b, h) do { _Pragma("unroll") for (int m = 0; m < 4; ++m) _Pragma("unroll") for (int k = 0; k < 2; ++k) dst[m][k] = *(const PG8_LAS bf16x8*)(lds + PG8_SA(b, h) + aoff + m * 2048 + k * 1024); } while (0)
; #define PG8_LDB(dst, b, h) do { _Pragma("unroll") for (int n = 0; n < 2; ++n) _Pragma("unroll") for (int k = 0; k < 2; ++k) dst[n][k] = *(const PG8_LAS bf16x8*)(lds + PG8_SB(b, h) + boff + n * 2048 + k * 1024); } while (0)
; #define PG8_MMA(ai, bj, At, Bt) do { __builtin_amdgcn_s_setprio(1); _Pragma("unroll") for (int m = 0; m < 4; ++m) _Pragma("unroll") for (int n = 0; n < 2; ++n) _Pragma("unroll") for (int k = 0; k < 2; ++k) \
;         acc[ai][bj][m][n] = __builtin_amdgcn_mfma_f32_16x16x32_bf16(Bt[n][k], At[m][k], acc[ai][bj][m][n], 0, 0, 0); __builtin_amdgcn_s_setprio(0); } while (0)
; #define PG8_WAIT_V(n) asm volatile("s_waitcnt vmcnt(" #n ")" ::: "memory")
; #define PG8_WAIT_L(n) asm volatile("s_waitcnt lgkmcnt(" #n ")" ::: "memory")
; #define PG8_BAR __builtin_amdgcn_s_barrier()
; #define PG8_SCHED __builtin_amdgcn_sched_barrier(0)
; template <class Epi, class Sched>
; __device__ __forceinline__ void gemm_phase(PG8_LAS unsigned char* lds, const Gemm g, const Sched& S, const Epi& E) {
;     ...
;             PG8_LDA(At, 0, 1); PG8_STAGE(PG8_SB(0, 0), b2, voffB); PG8_STAGE(PG8_SB(0, 1), b2 + hstepB, voffB); PG8_STAGE(PG8_SA(0, 0), a2, voffA);
;             PG8_WAIT_V(8); PG8_WAIT_L(0); PG8_BAR; PG8_MMA(1, 0, At, B0); PG8_MMA(1, 1, At, B1); PG8_BAR; PG8_SCHED;
;             PG8_LDB(B0, 1, 0); PG8_LDB(B1, 1, 1); PG8_SCHED; PG8_LDA(At, 1, 0); PG8_STAGE(PG8_SA(0, 1), a2 + hstepA, voffA);
;             PG8_WAIT_V(8); PG8_WAIT_L(0); PG8_BAR; PG8_MMA(0, 0, At, B0); PG8_MMA(0, 1, At, B1); PG8_BAR; PG8_SCHED;
;             PG8_LDA(At, 1, 1); PG8_STAGE(PG8_SB(1, 0), b3, voffB); PG8_STAGE(PG8_SB(1, 1), b3 + hstepB, voffB); PG8_STAGE(PG8_SA(1, 0), a3, voffA);
	s_setprio 1
	s_waitcnt lgkmcnt(0)
	v_mfma_f32_16x16x32_bf16 v[94:97], v[130:133], v[178:181], v[94:97]
	v_mfma_f32_16x16x32_bf16 v[90:93], v[138:141], v[178:181], v[90:93]
	v_mfma_f32_16x16x32_bf16 v[86:89], v[130:133], v[186:189], v[86:89]
	v_mfma_f32_16x16x32_bf16 v[82:85], v[138:141], v[186:189], v[82:85]
	v_mfma_f32_16x16x32_bf16 v[78:81], v[130:133], v[202:205], v[78:81]
	v_mfma_f32_16x16x32_bf16 v[74:77], v[138:141], v[202:205], v[74:77]
	v_mfma_f32_16x16x32_bf16 v[70:73], v[130:133], v[210:213], v[70:73]
	v_mfma_f32_16x16x32_bf16 v[66:69], v[138:141], v[210:213], v[66:69]
	v_mfma_f32_16x16x32_bf16 v[94:97], v[134:137], v[182:185], v[94:97]
	v_mfma_f32_16x16x32_bf16 v[90:93], v[142:145], v[182:185], v[90:93]
	v_mfma_f32_16x16x32_bf16 v[86:89], v[134:137], v[190:193], v[86:89]
	v_mfma_f32_16x16x32_bf16 v[82:85], v[142:145], v[190:193], v[82:85]
	v_mfma_f32_16x16x32_bf16 v[78:81], v[134:137], v[206:209], v[78:81]
	v_mfma_f32_16x16x32_bf16 v[74:77], v[142:145], v[206:209], v[74:77]
	v_mfma_f32_16x16x32_bf16 v[70:73], v[134:137], v[214:217], v[70:73]
	v_mfma_f32_16x16x32_bf16 v[66:69], v[142:145], v[214:217], v[66:69]
	s_setprio 0
	s_setprio 1
	v_mfma_f32_16x16x32_bf16 v[30:33], v[156:159], v[178:181], v[30:33]
	v_mfma_f32_16x16x32_bf16 v[26:29], v[170:173], v[178:181], v[26:29]
	v_mfma_f32_16x16x32_bf16 v[22:25], v[156:159], v[186:189], v[22:25]
	v_mfma_f32_16x16x32_bf16 v[18:21], v[170:173], v[186:189], v[18:21]
	v_mfma_f32_16x16x32_bf16 v[14:17], v[156:159], v[202:205], v[14:17]
	v_mfma_f32_16x16x32_bf16 v[10:13], v[170:173], v[202:205], v[10:13]
	v_mfma_f32_16x16x32_bf16 v[6:9], v[156:159], v[210:213], v[6:9]
	v_mfma_f32_16x16x32_bf16 v[2:5], v[170:173], v[210:213], v[2:5]
	v_mfma_f32_16x16x32_bf16 v[30:33], v[160:163], v[182:185], v[30:33]
	v_mfma_f32_16x16x32_bf16 v[26:29], v[174:177], v[182:185], v[26:29]
	v_mfma_f32_16x16x32_bf16 v[22:25], v[160:163], v[190:193], v[22:25]
	v_mfma_f32_16x16x32_bf16 v[18:21], v[174:177], v[190:193], v[18:21]
	v_mfma_f32_16x16x32_bf16 v[14:17], v[160:163], v[206:209], v[14:17]
	v_mfma_f32_16x16x32_bf16 v[10:13], v[174:177], v[206:209], v[10:13]
	v_mfma_f32_16x16x32_bf16 v[6:9], v[160:163], v[214:217], v[6:9]
	v_mfma_f32_16x16x32_bf16 v[2:5], v[174:177], v[214:217], v[2:5]
	s_setprio 0
	s_barrier
	s_add_i32 s41, 0, 0x18000
	s_add_i32 s49, 0, 0x1c000
	v_add_u32_e32 v142, s41, v168
	v_add_u32_e32 v174, s49, v168
	ds_read_b128 v[130:133], v142
	ds_read_b128 v[134:137], v142 offset:1024
	ds_read_b128 v[138:141], v142 offset:2048
	ds_read_b128 v[142:145], v142 offset:3072
	ds_read_b128 v[156:159], v174
	ds_read_b128 v[160:163], v174 offset:1024
	ds_read_b128 v[170:173], v174 offset:2048
	ds_read_b128 v[174:177], v174 offset:3072
	s_add_u32 s54, s54, 0x40000
	s_addc_u32 s55, s55, 0
	s_mov_b32 m0, s62
	v_lshl_add_u64 v[220:221], s[54:55], 0, v[146:147]
	ds_read_b128 v[178:181], v169 offset:32768
	ds_read_b128 v[182:185], v169 offset:33792
	ds_read_b128 v[186:189], v169 offset:34816
	ds_read_b128 v[190:193], v169 offset:35840
	ds_read_b128 v[202:205], v169 offset:36864
	ds_read_b128 v[206:209], v169 offset:37888
	ds_read_b128 v[210:213], v169 offset:38912
	ds_read_b128 v[214:217], v169 offset:39936
	global_load_lds_dwordx4 v[220:221], off
	v_lshl_add_u64 v[220:221], s[54:55], 0, v[148:149]
	s_mov_b32 m0, s63
	s_nop 0
	global_load_lds_dwordx4 v[220:221], off
	s_waitcnt vmcnt(8)
	s_waitcnt lgkmcnt(0)
	s_barrier
	s_setprio 1
	s_waitcnt lgkmcnt(0)
	v_mfma_f32_16x16x32_bf16 v[126:129], v[130:133], v[178:181], v[126:129]
	v_mfma_f32_16x16x32_bf16 v[122:125], v[138:141], v[178:181], v[122:125]
	v_mfma_f32_16x16x32_bf16 v[118:121], v[130:133], v[186:189], v[118:121]
	v_mfma_f32_16x16x32_bf16 v[114:117], v[138:141], v[186:189], v[114:117]
	v_mfma_f32_16x16x32_bf16 v[110:113], v[130:133], v[202:205], v[110:113]
	v_mfma_f32_16x16x32_bf16 v[106:109], v[138:141], v[202:205], v[106:109]
	v_mfma_f32_16x16x32_bf16 v[102:105], v[130:133], v[210:213], v[102:105]
	v_mfma_f32_16x16x32_bf16 v[98:101], v[138:141], v[210:213], v[98:101]
	v_mfma_f32_16x16x32_bf16 v[126:129], v[134:137], v[182:185], v[126:129]
	v_mfma_f32_16x16x32_bf16 v[122:125], v[142:145], v[182:185], v[122:125]
	v_mfma_f32_16x16x32_bf16 v[118:121], v[134:137], v[190:193], v[118:121]
	v_mfma_f32_16x16x32_bf16 v[114:117], v[142:145], v[190:193], v[114:117]
	v_mfma_f32_16x16x32_bf16 v[110:113], v[134:137], v[206:209], v[110:113]
	v_mfma_f32_16x16x32_bf16 v[106:109], v[142:145], v[206:209], v[106:109]
	v_mfma_f32_16x16x32_bf16 v[102:105], v[134:137], v[214:217], v[102:105]
	v_mfma_f32_16x16x32_bf16 v[98:101], v[142:145], v[214:217], v[98:101]
	s_setprio 0
	s_setprio 1
	v_mfma_f32_16x16x32_bf16 v[62:65], v[156:159], v[178:181], v[62:65]
	v_mfma_f32_16x16x32_bf16 v[58:61], v[170:173], v[178:181], v[58:61]
	v_mfma_f32_16x16x32_bf16 v[54:57], v[156:159], v[186:189], v[54:57]
	v_mfma_f32_16x16x32_bf16 v[50:53], v[170:173], v[186:189], v[50:53]
	v_mfma_f32_16x16x32_bf16 v[46:49], v[156:159], v[202:205], v[46:49]
	v_mfma_f32_16x16x32_bf16 v[42:45], v[170:173], v[202:205], v[42:45]
	v_mfma_f32_16x16x32_bf16 v[38:41], v[156:159], v[210:213], v[38:41]
	v_mfma_f32_16x16x32_bf16 v[34:37], v[170:173], v[210:213], v[34:37]
	v_mfma_f32_16x16x32_bf16 v[62:65], v[160:163], v[182:185], v[62:65]
	v_mfma_f32_16x16x32_bf16 v[58:61], v[174:177], v[182:185], v[58:61]
	v_mfma_f32_16x16x32_bf16 v[54:57], v[160:163], v[190:193], v[54:57]
	v_mfma_f32_16x16x32_bf16 v[50:53], v[174:177], v[190:193], v[50:53]
	v_mfma_f32_16x16x32_bf16 v[46:49], v[160:163], v[206:209], v[46:49]
	v_mfma_f32_16x16x32_bf16 v[42:45], v[174:177], v[206:209], v[42:45]
	v_mfma_f32_16x16x32_bf16 v[38:41], v[160:163], v[214:217], v[38:41]
	v_mfma_f32_16x16x32_bf16 v[34:37], v[174:177], v[214:217], v[34:37]
	s_setprio 0
	s_barrier
; #define PG8_STAGE(bufoff, gbase, voff) do { _Pragma("unroll") for (int _i = 0; _i < 2; ++_i) \
;         __builtin_amdgcn_global_load_lds((const unsigned*)((const char*)(gbase) + (voff)[_i]), (PG8_LAS unsigned*)(lds + (bufoff) + ldsw + _i * 8192), 16, 0, 0); } while (0)
; #define PG8_LDA(dst, b, h) do { _Pragma("unroll") for (int m = 0; m < 4; ++m) _Pragma("unroll") for (int k = 0; k < 2; ++k) dst[m][k] = *(const PG8_LAS bf16x8*)(lds + PG8_SA(b, h) + aoff + m * 2048 + k * 1024); } while (0)
; #define PG8_LDB(dst, b, h) do { _Pragma("unroll") for (int n = 0; n < 2; ++n) _Pragma("unroll") for (int k = 0; k < 2; ++k) dst[n][k] = *(const PG8_LAS bf16x8*)(lds + PG8_SB(b, h) + boff + n * 2048 + k * 1024); } while (0)
; #define PG8_MMA(ai, bj, At, Bt) do { __builtin_amdgcn_s_setprio(1); _Pragma("unroll") for (int m = 0; m < 4; ++m) _Pragma("unroll") for (int n = 0; n < 2; ++n) _Pragma("unroll") for (int k = 0; k < 2; ++k) \
;         acc[ai][bj][m][n] = __builtin_amdgcn_mfma_f32_16x16x32_bf16(Bt[n][k], At[m][k], acc[ai][bj][m][n], 0, 0, 0); __builtin_amdgcn_s_setprio(0); } while (0)
; #define PG8_WAIT_V(n) asm volatile("s_waitcnt vmcnt(" #n ")" ::: "memory")
; #define PG8_WAIT_L(n) asm volatile("s_waitcnt lgkmcnt(" #n ")" ::: "memory")
; #define PG8_BAR __builtin_amdgcn_s_barrier()
; #define PG8_SCHED __builtin_amdgcn_sched_barrier(0)
; template <class Epi, class Sched>
; __device__ __forceinline__ void gemm_phase(PG8_LAS unsigned char* lds, const Gemm g, const Sched& S, const Epi& E) {
;     ...
;             PG8_LDB(B0, 1, 0); PG8_LDB(B1, 1, 1); PG8_SCHED; PG8_LDA(At, 1, 0); PG8_STAGE(PG8_SA(0, 1), a2 + hstepA, voffA);
;             PG8_WAIT_V(8); PG8_WAIT_L(0); PG8_BAR; PG8_MMA(0, 0, At, B0); PG8_MMA(0, 1, At, B1); PG8_BAR; PG8_SCHED;
;             PG8_LDA(At, 1, 1); PG8_STAGE(PG8_SB(1, 0), b3, voffB); PG8_STAGE(PG8_SB(1, 1), b3 + hstepB, voffB); PG8_STAGE(PG8_SA(1, 0), a3, voffA);
;             PG8_WAIT_V(8); PG8_WAIT_L(0); PG8_BAR; PG8_MMA(1, 0, At, B0); PG8_MMA(1, 1, At, B1); PG8_BAR; PG8_SCHED;
;         }
	s_add_i32 s41, s41, s59
	v_lshl_add_u64 v[164:165], v[164:165], 0, s[20:21]
	s_mov_b32 m0, s41
	ds_read_b128 v[178:181], v169 offset:49152
	ds_read_b128 v[182:185], v169 offset:50176
	ds_read_b128 v[186:189], v169 offset:51200
	ds_read_b128 v[190:193], v169 offset:52224
	ds_read_b128 v[202:205], v169 offset:53248
	ds_read_b128 v[206:209], v169 offset:54272
	ds_read_b128 v[210:213], v169 offset:55296
	ds_read_b128 v[214:217], v169 offset:56320
	global_load_lds_dwordx4 v[164:165], off
	s_add_i32 m0, s41, 0x2000
	s_add_u32 s52, s52, 0x10080
	v_lshl_add_u64 v[164:165], v[194:195], 0, s[20:21]
	s_addc_u32 s53, s53, 0
	s_add_i32 s41, s49, s59
	global_load_lds_dwordx4 v[164:165], off
	v_lshl_add_u64 v[164:165], s[52:53], 0, v[0:1]
	s_mov_b32 m0, s41
	s_nop 0
	global_load_lds_dwordx4 v[164:165], off
	v_lshl_add_u64 v[164:165], s[52:53], 0, v[150:151]
	s_add_i32 m0, s41, 0x2000
	s_nop 0
	global_load_lds_dwordx4 v[164:165], off
	v_lshl_add_u64 v[164:165], v[196:197], 0, s[20:21]
	s_mov_b32 m0, s66
	s_nop 0
	global_load_lds_dwordx4 v[164:165], off
	v_lshl_add_u64 v[164:165], v[218:219], 0, s[20:21]
	s_mov_b32 m0, s67
	s_nop 0
	global_load_lds_dwordx4 v[164:165], off
	s_waitcnt vmcnt(8)
	s_waitcnt lgkmcnt(0)
	s_barrier
	s_setprio 1
	s_waitcnt lgkmcnt(0)
	v_mfma_f32_16x16x32_bf16 v[94:97], v[130:133], v[178:181], v[94:97]
	v_mfma_f32_16x16x32_bf16 v[90:93], v[138:141], v[178:181], v[90:93]
	v_mfma_f32_16x16x32_bf16 v[86:89], v[130:133], v[186:189], v[86:89]
	v_mfma_f32_16x16x32_bf16 v[82:85], v[138:141], v[186:189], v[82:85]
	v_mfma_f32_16x16x32_bf16 v[78:81], v[130:133], v[202:205], v[78:81]
	v_mfma_f32_16x16x32_bf16 v[74:77], v[138:141], v[202:205], v[74:77]
	v_mfma_f32_16x16x32_bf16 v[70:73], v[130:133], v[210:213], v[70:73]
	v_mfma_f32_16x16x32_bf16 v[66:69], v[138:141], v[210:213], v[66:69]
	v_mfma_f32_16x16x32_bf16 v[94:97], v[134:137], v[182:185], v[94:97]
	v_mfma_f32_16x16x32_bf16 v[90:93], v[142:145], v[182:185], v[90:93]
	v_mfma_f32_16x16x32_bf16 v[86:89], v[134:137], v[190:193], v[86:89]
	v_mfma_f32_16x16x32_bf16 v[82:85], v[142:145], v[190:193], v[82:85]
	v_mfma_f32_16x16x32_bf16 v[78:81], v[134:137], v[206:209], v[78:81]
	v_mfma_f32_16x16x32_bf16 v[74:77], v[142:145], v[206:209], v[74:77]
	v_mfma_f32_16x16x32_bf16 v[70:73], v[134:137], v[214:217], v[70:73]
	v_mfma_f32_16x16x32_bf16 v[66:69], v[142:145], v[214:217], v[66:69]
	s_setprio 0
	s_setprio 1
	v_mfma_f32_16x16x32_bf16 v[30:33], v[156:159], v[178:181], v[30:33]
	v_mfma_f32_16x16x32_bf16 v[26:29], v[170:173], v[178:181], v[26:29]
	v_mfma_f32_16x16x32_bf16 v[22:25], v[156:159], v[186:189], v[22:25]
	v_mfma_f32_16x16x32_bf16 v[18:21], v[170:173], v[186:189], v[18:21]
	v_mfma_f32_16x16x32_bf16 v[14:17], v[156:159], v[202:205], v[14:17]
	v_mfma_f32_16x16x32_bf16 v[10:13], v[170:173], v[202:205], v[10:13]
	v_mfma_f32_16x16x32_bf16 v[6:9], v[156:159], v[210:213], v[6:9]
	v_mfma_f32_16x16x32_bf16 v[2:5], v[170:173], v[210:213], v[2:5]
	v_mfma_f32_16x16x32_bf16 v[30:33], v[160:163], v[182:185], v[30:33]
	v_mfma_f32_16x16x32_bf16 v[26:29], v[174:177], v[182:185], v[26:29]
	v_mfma_f32_16x16x32_bf16 v[22:25], v[160:163], v[190:193], v[22:25]
	v_mfma_f32_16x16x32_bf16 v[18:21], v[174:177], v[190:193], v[18:21]
	v_mfma_f32_16x16x32_bf16 v[14:17], v[160:163], v[206:209], v[14:17]
	v_mfma_f32_16x16x32_bf16 v[10:13], v[174:177], v[206:209], v[10:13]
	v_mfma_f32_16x16x32_bf16 v[6:9], v[160:163], v[214:217], v[6:9]
	v_mfma_f32_16x16x32_bf16 v[2:5], v[174:177], v[214:217], v[2:5]
	s_setprio 0
	s_barrier
	s_add_i32 s39, s39, 2
	s_add_u32 s6, s6, 0x100
	s_addc_u32 s7, s7, 0
	s_add_u32 s2, s2, 0x100
	s_addc_u32 s18, s18, 0
	s_cmp_gt_u32 s39, 13
	s_cbranch_scc0 .LBB0_161
	s_and_b64 vcc, exec, s[14:15]
	s_cbranch_vccz .LBB0_164
	s_barrier

;     __device__ __forceinline__ void operator()(f32x4 (&acc)[2][2][4][2], const Unit& u, int wr, int wc, int fr, int fq) const {
;     ...
;         const int pn = u.pn;
;         {
;             const int kind = ((pn >= 4 && pn < 8) || (pn >= 20 && pn < 24) || (pn >= 28 && pn < 32)) ? 1 : (pn >= 8 && pn < 12) ? 2 : (pn >= 32) ? 3 : 0;
;             bf16_t* base = u.O + (size_t)(wr * 64 + fr) * LDZ + wc * 32 + 8 * fq;
;             f32x4 bv[2][2];
; #pragma unroll
;             for (int bj = 0; bj < 2; ++bj)
; #pragma unroll
;                 for (int n = 0; n < 2; ++n) bv[bj][n] = (kind == 3) ? *(const f32x4*)(b_merge + (pn * 256 - 8192) + wc * 32 + 8 * fq + bj * HALF + 4 * n) : (f32x4){0.f, 0.f, 0.f, 0.f};
; #pragma unroll
;             for (int ai = 0; ai < 2; ++ai)
; #pragma unroll
;                 for (int m = 0; m < 4; ++m) { bf16_t* rowp = base + (size_t)(ai * HALF + m * 16) * LDZ;
.LBB0_174:
	v_and_b32_e32 v138, 7, v166
	v_add_u32_e32 v138, s64, v138
	v_lshlrev_b32_e32 v138, 11, v138
	v_lshrrev_b32_e32 v139, 3, v166
	v_lshl_add_u32 v138, v139, 6, v138
	v_lshl_add_u32 v138, v167, 4, v138
	s_lshl_b32 s2, s65, 2
	v_add_u32_e32 v138, s2, v138
	v_add_u32_e32 v139, 0x4000, v138
	s_cmp_lg_u32 s39, 3
	s_cbranch_scc1 .Lepi1_nob
	s_lshl_b32 s6, s56, 10
	s_add_u32 s6, s8, s6
	s_addc_u32 s7, s9, 0
	s_lshl_b32 s2, s65, 3
	s_add_u32 s6, s6, s2
	s_addc_u32 s7, s7, 0
	s_add_u32 s6, s6, 0xffff8000
	s_addc_u32 s7, s7, -1
	v_lshlrev_b32_e32 v141, 5, v167
	global_load_dwordx4 v[222:225], v141, s[6:7]
	global_load_dwordx4 v[226:229], v141, s[6:7] offset:16
	global_load_dwordx4 v[238:241], v141, s[6:7] offset:128
	global_load_dwordx4 v[242:245], v141, s[6:7] offset:144
	s_waitcnt vmcnt(0)
	s_branch .Lepi1_k3

; __device__ __forceinline__ float sigm(float x) { return __builtin_amdgcn_rcpf(1.f + __expf(-x)); }
; __device__ __forceinline__ u32x4 pack8(const f32x4 v0, const f32x4 v1) { u32x4 w; w.x = cvt_pk_bf16(v0[0], v0[1]); w.y = cvt_pk_bf16(v0[2], v0[3]); w.z = cvt_pk_bf16(v1[0], v1[1]); w.w = cvt_pk_bf16(v1[2], v1[3]); return w; }
;     __device__ __forceinline__ void operator()(f32x4 (&acc)[2][2][4][2], const Unit& u, int wr, int wc, int fr, int fq) const {
;     ...
;             for (int ai = 0; ai < 2; ++ai)
; #pragma unroll
;                 for (int m = 0; m < 4; ++m) { bf16_t* rowp = base + (size_t)(ai * HALF + m * 16) * LDZ;
; #pragma unroll
;                     for (int bj = 0; bj < 2; ++bj) { f32x4 v0 = acc[ai][bj][m][0], v1 = acc[ai][bj][m][1];
;                         if (kind == 1) {
; #pragma unroll
;                             for (int e = 0; e < 4; ++e) { v0[e] = v0[e] * sigm(v0[e]); v1[e] = v1[e] * sigm(v1[e]); } }
;                         else if (kind == 2) { v0 = v0 * (0.125f * LOG2E); v1 = v1 * (0.125f * LOG2E); }
;                         else if (kind == 3) {
; #pragma unroll
;                             for (int e = 0; e < 4; ++e) { v0[e] = sigm(v0[e] + bv[bj][0][e]); v1[e] = sigm(v1[e] + bv[bj][1][e]); } }
;                         __builtin_nontemporal_store(pack8(v0, v1), (u32x4*)(rowp + bj * HALF)); } }
.Lepi1_k0:
	s_mov_b64 s[6:7], s[50:51]
	v_cvt_pk_bf16_f32 v130, v126, v127
	v_cvt_pk_bf16_f32 v131, v128, v129
	v_cvt_pk_bf16_f32 v132, v122, v123
	v_cvt_pk_bf16_f32 v133, v124, v125
	v_cvt_pk_bf16_f32 v134, v62, v63
	v_cvt_pk_bf16_f32 v135, v64, v65
	v_cvt_pk_bf16_f32 v136, v58, v59
	v_cvt_pk_bf16_f32 v137, v60, v61
	v_mov_b32_e32 v140, v134
	v_mov_b32_e32 v141, v135
	v_mov_b32_e32 v142, v136
	v_mov_b32_e32 v143, v137
	v_mov_b32_dpp v134, v130 row_ror:8 row_mask:0xf bank_mask:0x3
	v_mov_b32_dpp v135, v131 row_ror:8 row_mask:0xf bank_mask:0x3
	v_mov_b32_dpp v136, v132 row_ror:8 row_mask:0xf bank_mask:0x3
	v_mov_b32_dpp v137, v133 row_ror:8 row_mask:0xf bank_mask:0x3
	v_mov_b32_dpp v130, v140 row_ror:8 row_mask:0xf bank_mask:0xc
	v_mov_b32_dpp v131, v141 row_ror:8 row_mask:0xf bank_mask:0xc
	v_mov_b32_dpp v132, v142 row_ror:8 row_mask:0xf bank_mask:0xc
	v_mov_b32_dpp v133, v143 row_ror:8 row_mask:0xf bank_mask:0xc
	global_store_dwordx4 v138, v[130:133], s[6:7] nt
	global_store_dwordx4 v139, v[134:137], s[6:7] nt
	s_add_u32 s6, s6, 0x8000
	s_addc_u32 s7, s7, 0
	v_cvt_pk_bf16_f32 v156, v118, v119
	v_cvt_pk_bf16_f32 v157, v120, v121
	v_cvt_pk_bf16_f32 v158, v114, v115
	v_cvt_pk_bf16_f32 v159, v116, v117
	v_cvt_pk_bf16_f32 v160, v54, v55
	v_cvt_pk_bf16_f32 v161, v56, v57
	v_cvt_pk_bf16_f32 v162, v50, v51
	v_cvt_pk_bf16_f32 v163, v52, v53
	v_mov_b32_e32 v188, v160
	v_mov_b32_e32 v189, v161
	v_mov_b32_e32 v190, v162
	v_mov_b32_e32 v191, v163
	v_mov_b32_dpp v160, v156 row_ror:8 row_mask:0xf bank_mask:0x3
	v_mov_b32_dpp v161, v157 row_ror:8 row_mask:0xf bank_mask:0x3
	v_mov_b32_dpp v162, v158 row_ror:8 row_mask:0xf bank_mask:0x3
	v_mov_b32_dpp v163, v159 row_ror:8 row_mask:0xf bank_mask:0x3
	v_mov_b32_dpp v156, v188 row_ror:8 row_mask:0xf bank_mask:0xc
	v_mov_b32_dpp v157, v189 row_ror:8 row_mask:0xf bank_mask:0xc
	v_mov_b32_dpp v158, v190 row_ror:8 row_mask:0xf bank_mask:0xc
	v_mov_b32_dpp v159, v191 row_ror:8 row_mask:0xf bank_mask:0xc
	global_store_dwordx4 v138, v[156:159], s[6:7] nt
	global_store_dwordx4 v139, v[160:163], s[6:7] nt
	s_add_u32 s6, s6, 0x8000
	s_addc_u32 s7, s7, 0
	v_cvt_pk_bf16_f32 v130, v110, v111
	v_cvt_pk_bf16_f32 v131, v112, v113
	v_cvt_pk_bf16_f32 v132, v106, v107
	v_cvt_pk_bf16_f32 v133, v108, v109
	v_cvt_pk_bf16_f32 v134, v46, v47
	v_cvt_pk_bf16_f32 v135, v48, v49
	v_cvt_pk_bf16_f32 v136, v42, v43
	v_cvt_pk_bf16_f32 v137, v44, v45
	v_mov_b32_e32 v140, v134
	v_mov_b32_e32 v141, v135
	v_mov_b32_e32 v142, v136
	v_mov_b32_e32 v143, v137
	v_mov_b32_dpp v134, v130 row_ror:8 row_mask:0xf bank_mask:0x3
	v_mov_b32_dpp v135, v131 row_ror:8 row_mask:0xf bank_mask:0x3
	v_mov_b32_dpp v136, v132 row_ror:8 row_mask:0xf bank_mask:0x3
	v_mov_b32_dpp v137, v133 row_ror:8 row_mask:0xf bank_mask:0x3
	v_mov_b32_dpp v130, v140 row_ror:8 row_mask:0xf bank_mask:0xc
	v_mov_b32_dpp v131, v141 row_ror:8 row_mask:0xf bank_mask:0xc
	v_mov_b32_dpp v132, v142 row_ror:8 row_mask:0xf bank_mask:0xc
	v_mov_b32_dpp v133, v143 row_ror:8 row_mask:0xf bank_mask:0xc
	global_store_dwordx4 v138, v[130:133], s[6:7] nt
	global_store_dwordx4 v139, v[134:137], s[6:7] nt
	s_add_u32 s6, s6, 0x8000
	s_addc_u32 s7, s7, 0
	v_cvt_pk_bf16_f32 v156, v102, v103
	v_cvt_pk_bf16_f32 v157, v104, v105
	v_cvt_pk_bf16_f32 v158, v98, v99
	v_cvt_pk_bf16_f32 v159, v100, v101
	v_cvt_pk_bf16_f32 v160, v38, v39
	v_cvt_pk_bf16_f32 v161, v40, v41
	v_cvt_pk_bf16_f32 v162, v34, v35
	v_cvt_pk_bf16_f32 v163, v36, v37
	v_mov_b32_e32 v188, v160
	v_mov_b32_e32 v189, v161
	v_mov_b32_e32 v190, v162
	v_mov_b32_e32 v191, v163
	v_mov_b32_dpp v160, v156 row_ror:8 row_mask:0xf bank_mask:0x3
	v_mov_b32_dpp v161, v157 row_ror:8 row_mask:0xf bank_mask:0x3
	v_mov_b32_dpp v162, v158 row_ror:8 row_mask:0xf bank_mask:0x3
	v_mov_b32_dpp v163, v159 row_ror:8 row_mask:0xf bank_mask:0x3
	v_mov_b32_dpp v156, v188 row_ror:8 row_mask:0xf bank_mask:0xc
	v_mov_b32_dpp v157, v189 row_ror:8 row_mask:0xf bank_mask:0xc
	v_mov_b32_dpp v158, v190 row_ror:8 row_mask:0xf bank_mask:0xc
	v_mov_b32_dpp v159, v191 row_ror:8 row_mask:0xf bank_mask:0xc
	global_store_dwordx4 v138, v[156:159], s[6:7] nt
	global_store_dwordx4 v139, v[160:163], s[6:7] nt
	s_add_u32 s6, s6, 0x28000
	s_addc_u32 s7, s7, 0
	v_cvt_pk_bf16_f32 v130, v94, v95
	v_cvt_pk_bf16_f32 v131, v96, v97
	v_cvt_pk_bf16_f32 v132, v90, v91
	v_cvt_pk_bf16_f32 v133, v92, v93
	v_cvt_pk_bf16_f32 v134, v30, v31
	v_cvt_pk_bf16_f32 v135, v32, v33
	v_cvt_pk_bf16_f32 v136, v26, v27
	v_cvt_pk_bf16_f32 v137, v28, v29
	v_mov_b32_e32 v140, v134
	v_mov_b32_e32 v141, v135
	v_mov_b32_e32 v142, v136
	v_mov_b32_e32 v143, v137
	v_mov_b32_dpp v134, v130 row_ror:8 row_mask:0xf bank_mask:0x3
	v_mov_b32_dpp v135, v131 row_ror:8 row_mask:0xf bank_mask:0x3
	v_mov_b32_dpp v136, v132 row_ror:8 row_mask:0xf bank_mask:0x3
	v_mov_b32_dpp v137, v133 row_ror:8 row_mask:0xf bank_mask:0x3
	v_mov_b32_dpp v130, v140 row_ror:8 row_mask:0xf bank_mask:0xc
	v_mov_b32_dpp v131, v141 row_ror:8 row_mask:0xf bank_mask:0xc
	v_mov_b32_dpp v132, v142 row_ror:8 row_mask:0xf bank_mask:0xc
	v_mov_b32_dpp v133, v143 row_ror:8 row_mask:0xf bank_mask:0xc
	global_store_dwordx4 v138, v[130:133], s[6:7] nt
	global_store_dwordx4 v139, v[134:137], s[6:7] nt
	s_add_u32 s6, s6, 0x8000
	s_addc_u32 s7, s7, 0
	v_cvt_pk_bf16_f32 v156, v86, v87
	v_cvt_pk_bf16_f32 v157, v88, v89
	v_cvt_pk_bf16_f32 v158, v82, v83
	v_cvt_pk_bf16_f32 v159, v84, v85
	v_cvt_pk_bf16_f32 v160, v22, v23
	v_cvt_pk_bf16_f32 v161, v24, v25
	v_cvt_pk_bf16_f32 v162, v18, v19
	v_cvt_pk_bf16_f32 v163, v20, v21
	v_mov_b32_e32 v188, v160
	v_mov_b32_e32 v189, v161
	v_mov_b32_e32 v190, v162
	v_mov_b32_e32 v191, v163
	v_mov_b32_dpp v160, v156 row_ror:8 row_mask:0xf bank_mask:0x3
; __device__ __forceinline__ float sigm(float x) { return __builtin_amdgcn_rcpf(1.f + __expf(-x)); }
; __device__ __forceinline__ u32x4 pack8(const f32x4 v0, const f32x4 v1) { u32x4 w; w.x = cvt_pk_bf16(v0[0], v0[1]); w.y = cvt_pk_bf16(v0[2], v0[3]); w.z = cvt_pk_bf16(v1[0], v1[1]); w.w = cvt_pk_bf16(v1[2], v1[3]); return w; }
;     __device__ __forceinline__ void operator()(f32x4 (&acc)[2][2][4][2], const Unit& u, int wr, int wc, int fr, int fq) const {
;     ...
;             for (int ai = 0; ai < 2; ++ai)
; #pragma unroll
;                 for (int m = 0; m < 4; ++m) { bf16_t* rowp = base + (size_t)(ai * HALF + m * 16) * LDZ;
; #pragma unroll
;                     for (int bj = 0; bj < 2; ++bj) { f32x4 v0 = acc[ai][bj][m][0], v1 = acc[ai][bj][m][1];
;                         if (kind == 1) {
; #pragma unroll
;                             for (int e = 0; e < 4; ++e) { v0[e] = v0[e] * sigm(v0[e]); v1[e] = v1[e] * sigm(v1[e]); } }
;                         else if (kind == 2) { v0 = v0 * (0.125f * LOG2E); v1 = v1 * (0.125f * LOG2E); }
;                         else if (kind == 3) {
; #pragma unroll
;                             for (int e = 0; e < 4; ++e) { v0[e] = sigm(v0[e] + bv[bj][0][e]); v1[e] = sigm(v1[e] + bv[bj][1][e]); } }
;                         __builtin_nontemporal_store(pack8(v0, v1), (u32x4*)(rowp + bj * HALF)); } }
	v_mov_b32_dpp v161, v157 row_ror:8 row_mask:0xf bank_mask:0x3
	v_mov_b32_dpp v162, v158 row_ror:8 row_mask:0xf bank_mask:0x3
	v_mov_b32_dpp v163, v159 row_ror:8 row_mask:0xf bank_mask:0x3
	v_mov_b32_dpp v156, v188 row_ror:8 row_mask:0xf bank_mask:0xc
	v_mov_b32_dpp v157, v189 row_ror:8 row_mask:0xf bank_mask:0xc
	v_mov_b32_dpp v158, v190 row_ror:8 row_mask:0xf bank_mask:0xc
	v_mov_b32_dpp v159, v191 row_ror:8 row_mask:0xf bank_mask:0xc
	global_store_dwordx4 v138, v[156:159], s[6:7] nt
	global_store_dwordx4 v139, v[160:163], s[6:7] nt
	s_add_u32 s6, s6, 0x8000
	s_addc_u32 s7, s7, 0
	v_cvt_pk_bf16_f32 v130, v78, v79
	v_cvt_pk_bf16_f32 v131, v80, v81
	v_cvt_pk_bf16_f32 v132, v74, v75
	v_cvt_pk_bf16_f32 v133, v76, v77
	v_cvt_pk_bf16_f32 v134, v14, v15
	v_cvt_pk_bf16_f32 v135, v16, v17
	v_cvt_pk_bf16_f32 v136, v10, v11
	v_cvt_pk_bf16_f32 v137, v12, v13
	v_mov_b32_e32 v140, v134
	v_mov_b32_e32 v141, v135
	v_mov_b32_e32 v142, v136
	v_mov_b32_e32 v143, v137
	v_mov_b32_dpp v134, v130 row_ror:8 row_mask:0xf bank_mask:0x3
	v_mov_b32_dpp v135, v131 row_ror:8 row_mask:0xf bank_mask:0x3
	v_mov_b32_dpp v136, v132 row_ror:8 row_mask:0xf bank_mask:0x3
	v_mov_b32_dpp v137, v133 row_ror:8 row_mask:0xf bank_mask:0x3
	v_mov_b32_dpp v130, v140 row_ror:8 row_mask:0xf bank_mask:0xc
	v_mov_b32_dpp v131, v141 row_ror:8 row_mask:0xf bank_mask:0xc
	v_mov_b32_dpp v132, v142 row_ror:8 row_mask:0xf bank_mask:0xc
	v_mov_b32_dpp v133, v143 row_ror:8 row_mask:0xf bank_mask:0xc
	global_store_dwordx4 v138, v[130:133], s[6:7] nt
	global_store_dwordx4 v139, v[134:137], s[6:7] nt
	s_add_u32 s6, s6, 0x8000
	s_addc_u32 s7, s7, 0
	v_cvt_pk_bf16_f32 v156, v70, v71
	v_cvt_pk_bf16_f32 v157, v72, v73
	v_cvt_pk_bf16_f32 v158, v66, v67
	v_cvt_pk_bf16_f32 v159, v68, v69
	v_cvt_pk_bf16_f32 v160, v6, v7
	v_cvt_pk_bf16_f32 v161, v8, v9
	v_cvt_pk_bf16_f32 v162, v2, v3
	v_cvt_pk_bf16_f32 v163, v4, v5
	v_mov_b32_e32 v188, v160
	v_mov_b32_e32 v189, v161
	v_mov_b32_e32 v190, v162
	v_mov_b32_e32 v191, v163
	v_mov_b32_dpp v160, v156 row_ror:8 row_mask:0xf bank_mask:0x3
	v_mov_b32_dpp v161, v157 row_ror:8 row_mask:0xf bank_mask:0x3
	v_mov_b32_dpp v162, v158 row_ror:8 row_mask:0xf bank_mask:0x3
	v_mov_b32_dpp v163, v159 row_ror:8 row_mask:0xf bank_mask:0x3
	v_mov_b32_dpp v156, v188 row_ror:8 row_mask:0xf bank_mask:0xc
	v_mov_b32_dpp v157, v189 row_ror:8 row_mask:0xf bank_mask:0xc
	v_mov_b32_dpp v158, v190 row_ror:8 row_mask:0xf bank_mask:0xc
	v_mov_b32_dpp v159, v191 row_ror:8 row_mask:0xf bank_mask:0xc
	global_store_dwordx4 v138, v[156:159], s[6:7] nt
	global_store_dwordx4 v139, v[160:163], s[6:7] nt
	s_branch .Lepi1_done
.Lepi1_k1:
	s_mov_b64 s[6:7], s[50:51]
	v_pk_mul_f32 v[172:173], v[126:127], s[24:25] op_sel_hi:[1,0]
	v_pk_mul_f32 v[174:175], v[128:129], s[24:25] op_sel_hi:[1,0]
	v_pk_mul_f32 v[176:177], v[122:123], s[24:25] op_sel_hi:[1,0]
	v_pk_mul_f32 v[178:179], v[124:125], s[24:25] op_sel_hi:[1,0]
	v_exp_f32_e32 v172, v172
	v_exp_f32_e32 v173, v173
	v_exp_f32_e32 v174, v174
	v_exp_f32_e32 v175, v175
	v_exp_f32_e32 v176, v176
	v_exp_f32_e32 v177, v177
	v_exp_f32_e32 v178, v178
	v_exp_f32_e32 v179, v179
	v_pk_add_f32 v[172:173], v[172:173], 1.0 op_sel_hi:[1,0]
	v_pk_add_f32 v[174:175], v[174:175], 1.0 op_sel_hi:[1,0]
	v_pk_add_f32 v[176:177], v[176:177], 1.0 op_sel_hi:[1,0]
	v_pk_add_f32 v[178:179], v[178:179], 1.0 op_sel_hi:[1,0]
	v_rcp_f32_e32 v172, v172
	v_rcp_f32_e32 v173, v173
	v_rcp_f32_e32 v174, v174
	v_rcp_f32_e32 v175, v175
	v_rcp_f32_e32 v176, v176
	v_rcp_f32_e32 v177, v177
	v_rcp_f32_e32 v178, v178
	v_rcp_f32_e32 v179, v179
	v_pk_mul_f32 v[172:173], v[126:127], v[172:173]
	v_pk_mul_f32 v[174:175], v[128:129], v[174:175]
	v_pk_mul_f32 v[176:177], v[122:123], v[176:177]
	v_pk_mul_f32 v[178:179], v[124:125], v[178:179]
	v_pk_mul_f32 v[180:181], v[62:63], s[24:25] op_sel_hi:[1,0]
	v_pk_mul_f32 v[182:183], v[64:65], s[24:25] op_sel_hi:[1,0]
	v_pk_mul_f32 v[184:185], v[58:59], s[24:25] op_sel_hi:[1,0]
	v_pk_mul_f32 v[186:187], v[60:61], s[24:25] op_sel_hi:[1,0]
	v_exp_f32_e32 v180, v180
	v_exp_f32_e32 v181, v181
	v_exp_f32_e32 v182, v182
	v_exp_f32_e32 v183, v183
	v_exp_f32_e32 v184, v184
	v_exp_f32_e32 v185, v185
	v_exp_f32_e32 v186, v186
	v_exp_f32_e32 v187, v187
	v_pk_add_f32 v[180:181], v[180:181], 1.0 op_sel_hi:[1,0]
	v_pk_add_f32 v[182:183], v[182:183], 1.0 op_sel_hi:[1,0]
	v_pk_add_f32 v[184:185], v[184:185], 1.0 op_sel_hi:[1,0]
	v_pk_add_f32 v[186:187], v[186:187], 1.0 op_sel_hi:[1,0]
	v_rcp_f32_e32 v180, v180
	v_rcp_f32_e32 v181, v181
	v_rcp_f32_e32 v182, v182
	v_rcp_f32_e32 v183, v183
	v_rcp_f32_e32 v184, v184
	v_rcp_f32_e32 v185, v185
	v_rcp_f32_e32 v186, v186
	v_rcp_f32_e32 v187, v187
	v_pk_mul_f32 v[180:181], v[62:63], v[180:181]
	v_pk_mul_f32 v[182:183], v[64:65], v[182:183]
	v_pk_mul_f32 v[184:185], v[58:59], v[184:185]
	v_pk_mul_f32 v[186:187], v[60:61], v[186:187]
	v_cvt_pk_bf16_f32 v130, v172, v173
	v_cvt_pk_bf16_f32 v131, v174, v175
	v_cvt_pk_bf16_f32 v132, v176, v177
	v_cvt_pk_bf16_f32 v133, v178, v179
	v_cvt_pk_bf16_f32 v134, v180, v181
	v_cvt_pk_bf16_f32 v135, v182, v183
	v_cvt_pk_bf16_f32 v136, v184, v185
	v_cvt_pk_bf16_f32 v137, v186, v187
	v_mov_b32_e32 v140, v134
	v_mov_b32_e32 v141, v135
	v_mov_b32_e32 v142, v136
	v_mov_b32_e32 v143, v137
	v_mov_b32_dpp v134, v130 row_ror:8 row_mask:0xf bank_mask:0x3
	v_mov_b32_dpp v135, v131 row_ror:8 row_mask:0xf bank_mask:0x3
	v_mov_b32_dpp v136, v132 row_ror:8 row_mask:0xf bank_mask:0x3
	v_mov_b32_dpp v137, v133 row_ror:8 row_mask:0xf bank_mask:0x3
	v_mov_b32_dpp v130, v140 row_ror:8 row_mask:0xf bank_mask:0xc
	v_mov_b32_dpp v131, v141 row_ror:8 row_mask:0xf bank_mask:0xc
	v_mov_b32_dpp v132, v142 row_ror:8 row_mask:0xf bank_mask:0xc
; __device__ __forceinline__ float sigm(float x) { return __builtin_amdgcn_rcpf(1.f + __expf(-x)); }
; __device__ __forceinline__ u32x4 pack8(const f32x4 v0, const f32x4 v1) { u32x4 w; w.x = cvt_pk_bf16(v0[0], v0[1]); w.y = cvt_pk_bf16(v0[2], v0[3]); w.z = cvt_pk_bf16(v1[0], v1[1]); w.w = cvt_pk_bf16(v1[2], v1[3]); return w; }
;     __device__ __forceinline__ void operator()(f32x4 (&acc)[2][2][4][2], const Unit& u, int wr, int wc, int fr, int fq) const {
;     ...
;             for (int ai = 0; ai < 2; ++ai)
; #pragma unroll
;                 for (int m = 0; m < 4; ++m) { bf16_t* rowp = base + (size_t)(ai * HALF + m * 16) * LDZ;
; #pragma unroll
;                     for (int bj = 0; bj < 2; ++bj) { f32x4 v0 = acc[ai][bj][m][0], v1 = acc[ai][bj][m][1];
;                         if (kind == 1) {
; #pragma unroll
;                             for (int e = 0; e < 4; ++e) { v0[e] = v0[e] * sigm(v0[e]); v1[e] = v1[e] * sigm(v1[e]); } }
;                         else if (kind == 2) { v0 = v0 * (0.125f * LOG2E); v1 = v1 * (0.125f * LOG2E); }
;                         else if (kind == 3) {
; #pragma unroll
;                             for (int e = 0; e < 4; ++e) { v0[e] = sigm(v0[e] + bv[bj][0][e]); v1[e] = sigm(v1[e] + bv[bj][1][e]); } }
;                         __builtin_nontemporal_store(pack8(v0, v1), (u32x4*)(rowp + bj * HALF)); } }
	v_mov_b32_dpp v133, v143 row_ror:8 row_mask:0xf bank_mask:0xc
	global_store_dwordx4 v138, v[130:133], s[6:7] nt
	global_store_dwordx4 v139, v[134:137], s[6:7] nt
	s_add_u32 s6, s6, 0x8000
	s_addc_u32 s7, s7, 0
	v_pk_mul_f32 v[206:207], v[118:119], s[24:25] op_sel_hi:[1,0]
	v_pk_mul_f32 v[208:209], v[120:121], s[24:25] op_sel_hi:[1,0]
	v_pk_mul_f32 v[210:211], v[114:115], s[24:25] op_sel_hi:[1,0]
	v_pk_mul_f32 v[212:213], v[116:117], s[24:25] op_sel_hi:[1,0]
	v_exp_f32_e32 v206, v206
	v_exp_f32_e32 v207, v207
	v_exp_f32_e32 v208, v208
	v_exp_f32_e32 v209, v209
	v_exp_f32_e32 v210, v210
	v_exp_f32_e32 v211, v211
	v_exp_f32_e32 v212, v212
	v_exp_f32_e32 v213, v213
	v_pk_add_f32 v[206:207], v[206:207], 1.0 op_sel_hi:[1,0]
	v_pk_add_f32 v[208:209], v[208:209], 1.0 op_sel_hi:[1,0]
	v_pk_add_f32 v[210:211], v[210:211], 1.0 op_sel_hi:[1,0]
	v_pk_add_f32 v[212:213], v[212:213], 1.0 op_sel_hi:[1,0]
	v_rcp_f32_e32 v206, v206
	v_rcp_f32_e32 v207, v207
	v_rcp_f32_e32 v208, v208
	v_rcp_f32_e32 v209, v209
	v_rcp_f32_e32 v210, v210
	v_rcp_f32_e32 v211, v211
	v_rcp_f32_e32 v212, v212
	v_rcp_f32_e32 v213, v213
	v_pk_mul_f32 v[206:207], v[118:119], v[206:207]
	v_pk_mul_f32 v[208:209], v[120:121], v[208:209]
	v_pk_mul_f32 v[210:211], v[114:115], v[210:211]
	v_pk_mul_f32 v[212:213], v[116:117], v[212:213]
	v_pk_mul_f32 v[214:215], v[54:55], s[24:25] op_sel_hi:[1,0]
	v_pk_mul_f32 v[216:217], v[56:57], s[24:25] op_sel_hi:[1,0]
	v_pk_mul_f32 v[218:219], v[50:51], s[24:25] op_sel_hi:[1,0]
	v_pk_mul_f32 v[220:221], v[52:53], s[24:25] op_sel_hi:[1,0]
	v_exp_f32_e32 v214, v214
	v_exp_f32_e32 v215, v215
	v_exp_f32_e32 v216, v216
	v_exp_f32_e32 v217, v217
	v_exp_f32_e32 v218, v218
	v_exp_f32_e32 v219, v219
	v_exp_f32_e32 v220, v220
	v_exp_f32_e32 v221, v221
	v_pk_add_f32 v[214:215], v[214:215], 1.0 op_sel_hi:[1,0]
	v_pk_add_f32 v[216:217], v[216:217], 1.0 op_sel_hi:[1,0]
	v_pk_add_f32 v[218:219], v[218:219], 1.0 op_sel_hi:[1,0]
	v_pk_add_f32 v[220:221], v[220:221], 1.0 op_sel_hi:[1,0]
	v_rcp_f32_e32 v214, v214
	v_rcp_f32_e32 v215, v215
	v_rcp_f32_e32 v216, v216
	v_rcp_f32_e32 v217, v217
	v_rcp_f32_e32 v218, v218
	v_rcp_f32_e32 v219, v219
	v_rcp_f32_e32 v220, v220
	v_rcp_f32_e32 v221, v221
	v_pk_mul_f32 v[214:215], v[54:55], v[214:215]
	v_pk_mul_f32 v[216:217], v[56:57], v[216:217]
	v_pk_mul_f32 v[218:219], v[50:51], v[218:219]
	v_pk_mul_f32 v[220:221], v[52:53], v[220:221]
	v_cvt_pk_bf16_f32 v156, v206, v207
	v_cvt_pk_bf16_f32 v157, v208, v209
	v_cvt_pk_bf16_f32 v158, v210, v211
	v_cvt_pk_bf16_f32 v159, v212, v213
	v_cvt_pk_bf16_f32 v160, v214, v215
	v_cvt_pk_bf16_f32 v161, v216, v217
	v_cvt_pk_bf16_f32 v162, v218, v219
	v_cvt_pk_bf16_f32 v163, v220, v221
	v_mov_b32_e32 v188, v160
	v_mov_b32_e32 v189, v161
	v_mov_b32_e32 v190, v162
	v_mov_b32_e32 v191, v163
	v_mov_b32_dpp v160, v156 row_ror:8 row_mask:0xf bank_mask:0x3
	v_mov_b32_dpp v161, v157 row_ror:8 row_mask:0xf bank_mask:0x3
	v_mov_b32_dpp v162, v158 row_ror:8 row_mask:0xf bank_mask:0x3
	v_mov_b32_dpp v163, v159 row_ror:8 row_mask:0xf bank_mask:0x3
	v_mov_b32_dpp v156, v188 row_ror:8 row_mask:0xf bank_mask:0xc
	v_mov_b32_dpp v157, v189 row_ror:8 row_mask:0xf bank_mask:0xc
	v_mov_b32_dpp v158, v190 row_ror:8 row_mask:0xf bank_mask:0xc
	v_mov_b32_dpp v159, v191 row_ror:8 row_mask:0xf bank_mask:0xc
	global_store_dwordx4 v138, v[156:159], s[6:7] nt
	global_store_dwordx4 v139, v[160:163], s[6:7] nt
	s_add_u32 s6, s6, 0x8000
	s_addc_u32 s7, s7, 0
	v_pk_mul_f32 v[172:173], v[110:111], s[24:25] op_sel_hi:[1,0]
	v_pk_mul_f32 v[174:175], v[112:113], s[24:25] op_sel_hi:[1,0]
	v_pk_mul_f32 v[176:177], v[106:107], s[24:25] op_sel_hi:[1,0]
	v_pk_mul_f32 v[178:179], v[108:109], s[24:25] op_sel_hi:[1,0]
	v_exp_f32_e32 v172, v172
	v_exp_f32_e32 v173, v173
	v_exp_f32_e32 v174, v174
	v_exp_f32_e32 v175, v175
	v_exp_f32_e32 v176, v176
	v_exp_f32_e32 v177, v177
	v_exp_f32_e32 v178, v178
	v_exp_f32_e32 v179, v179
	v_pk_add_f32 v[172:173], v[172:173], 1.0 op_sel_hi:[1,0]
	v_pk_add_f32 v[174:175], v[174:175], 1.0 op_sel_hi:[1,0]
	v_pk_add_f32 v[176:177], v[176:177], 1.0 op_sel_hi:[1,0]
	v_pk_add_f32 v[178:179], v[178:179], 1.0 op_sel_hi:[1,0]
	v_rcp_f32_e32 v172, v172
	v_rcp_f32_e32 v173, v173
	v_rcp_f32_e32 v174, v174
	v_rcp_f32_e32 v175, v175
	v_rcp_f32_e32 v176, v176
	v_rcp_f32_e32 v177, v177
	v_rcp_f32_e32 v178, v178
	v_rcp_f32_e32 v179, v179
	v_pk_mul_f32 v[172:173], v[110:111], v[172:173]
	v_pk_mul_f32 v[174:175], v[112:113], v[174:175]
	v_pk_mul_f32 v[176:177], v[106:107], v[176:177]
	v_pk_mul_f32 v[178:179], v[108:109], v[178:179]
	v_pk_mul_f32 v[180:181], v[46:47], s[24:25] op_sel_hi:[1,0]
	v_pk_mul_f32 v[182:183], v[48:49], s[24:25] op_sel_hi:[1,0]
	v_pk_mul_f32 v[184:185], v[42:43], s[24:25] op_sel_hi:[1,0]
	v_pk_mul_f32 v[186:187], v[44:45], s[24:25] op_sel_hi:[1,0]
	v_exp_f32_e32 v180, v180
	v_exp_f32_e32 v181, v181
	v_exp_f32_e32 v182, v182
	v_exp_f32_e32 v183, v183
	v_exp_f32_e32 v184, v184
	v_exp_f32_e32 v185, v185
	v_exp_f32_e32 v186, v186
	v_exp_f32_e32 v187, v187
	v_pk_add_f32 v[180:181], v[180:181], 1.0 op_sel_hi:[1,0]
	v_pk_add_f32 v[182:183], v[182:183], 1.0 op_sel_hi:[1,0]
	v_pk_add_f32 v[184:185], v[184:185], 1.0 op_sel_hi:[1,0]
	v_pk_add_f32 v[186:187], v[186:187], 1.0 op_sel_hi:[1,0]
	v_rcp_f32_e32 v180, v180
	v_rcp_f32_e32 v181, v181
	v_rcp_f32_e32 v182, v182
	v_rcp_f32_e32 v183, v183
	v_rcp_f32_e32 v184, v184
	v_rcp_f32_e32 v185, v185
	v_rcp_f32_e32 v186, v186
	v_rcp_f32_e32 v187, v187
	v_pk_mul_f32 v[180:181], v[46:47], v[180:181]
	v_pk_mul_f32 v[182:183], v[48:49], v[182:183]
	v_pk_mul_f32 v[184:185], v[42:43], v[184:185]
	v_pk_mul_f32 v[186:187], v[44:45], v[186:187]
	v_cvt_pk_bf16_f32 v130, v172, v173
; __device__ __forceinline__ float sigm(float x) { return __builtin_amdgcn_rcpf(1.f + __expf(-x)); }
; __device__ __forceinline__ u32x4 pack8(const f32x4 v0, const f32x4 v1) { u32x4 w; w.x = cvt_pk_bf16(v0[0], v0[1]); w.y = cvt_pk_bf16(v0[2], v0[3]); w.z = cvt_pk_bf16(v1[0], v1[1]); w.w = cvt_pk_bf16(v1[2], v1[3]); return w; }
;     __device__ __forceinline__ void operator()(f32x4 (&acc)[2][2][4][2], const Unit& u, int wr, int wc, int fr, int fq) const {
;     ...
;             for (int ai = 0; ai < 2; ++ai)
; #pragma unroll
;                 for (int m = 0; m < 4; ++m) { bf16_t* rowp = base + (size_t)(ai * HALF + m * 16) * LDZ;
; #pragma unroll
;                     for (int bj = 0; bj < 2; ++bj) { f32x4 v0 = acc[ai][bj][m][0], v1 = acc[ai][bj][m][1];
;                         if (kind == 1) {
; #pragma unroll
;                             for (int e = 0; e < 4; ++e) { v0[e] = v0[e] * sigm(v0[e]); v1[e] = v1[e] * sigm(v1[e]); } }
;                         else if (kind == 2) { v0 = v0 * (0.125f * LOG2E); v1 = v1 * (0.125f * LOG2E); }
;                         else if (kind == 3) {
; #pragma unroll
;                             for (int e = 0; e < 4; ++e) { v0[e] = sigm(v0[e] + bv[bj][0][e]); v1[e] = sigm(v1[e] + bv[bj][1][e]); } }
;                         __builtin_nontemporal_store(pack8(v0, v1), (u32x4*)(rowp + bj * HALF)); } }
	v_cvt_pk_bf16_f32 v131, v174, v175
	v_cvt_pk_bf16_f32 v132, v176, v177
	v_cvt_pk_bf16_f32 v133, v178, v179
	v_cvt_pk_bf16_f32 v134, v180, v181
	v_cvt_pk_bf16_f32 v135, v182, v183
	v_cvt_pk_bf16_f32 v136, v184, v185
	v_cvt_pk_bf16_f32 v137, v186, v187
	v_mov_b32_e32 v140, v134
	v_mov_b32_e32 v141, v135
	v_mov_b32_e32 v142, v136
	v_mov_b32_e32 v143, v137
	v_mov_b32_dpp v134, v130 row_ror:8 row_mask:0xf bank_mask:0x3
	v_mov_b32_dpp v135, v131 row_ror:8 row_mask:0xf bank_mask:0x3
	v_mov_b32_dpp v136, v132 row_ror:8 row_mask:0xf bank_mask:0x3
	v_mov_b32_dpp v137, v133 row_ror:8 row_mask:0xf bank_mask:0x3
	v_mov_b32_dpp v130, v140 row_ror:8 row_mask:0xf bank_mask:0xc
	v_mov_b32_dpp v131, v141 row_ror:8 row_mask:0xf bank_mask:0xc
	v_mov_b32_dpp v132, v142 row_ror:8 row_mask:0xf bank_mask:0xc
	v_mov_b32_dpp v133, v143 row_ror:8 row_mask:0xf bank_mask:0xc
	global_store_dwordx4 v138, v[130:133], s[6:7] nt
	global_store_dwordx4 v139, v[134:137], s[6:7] nt
	s_add_u32 s6, s6, 0x8000
	s_addc_u32 s7, s7, 0
	v_pk_mul_f32 v[206:207], v[102:103], s[24:25] op_sel_hi:[1,0]
	v_pk_mul_f32 v[208:209], v[104:105], s[24:25] op_sel_hi:[1,0]
	v_pk_mul_f32 v[210:211], v[98:99], s[24:25] op_sel_hi:[1,0]
	v_pk_mul_f32 v[212:213], v[100:101], s[24:25] op_sel_hi:[1,0]
	v_exp_f32_e32 v206, v206
	v_exp_f32_e32 v207, v207
	v_exp_f32_e32 v208, v208
	v_exp_f32_e32 v209, v209
	v_exp_f32_e32 v210, v210
	v_exp_f32_e32 v211, v211
	v_exp_f32_e32 v212, v212
	v_exp_f32_e32 v213, v213
	v_pk_add_f32 v[206:207], v[206:207], 1.0 op_sel_hi:[1,0]
	v_pk_add_f32 v[208:209], v[208:209], 1.0 op_sel_hi:[1,0]
	v_pk_add_f32 v[210:211], v[210:211], 1.0 op_sel_hi:[1,0]
	v_pk_add_f32 v[212:213], v[212:213], 1.0 op_sel_hi:[1,0]
	v_rcp_f32_e32 v206, v206
	v_rcp_f32_e32 v207, v207
	v_rcp_f32_e32 v208, v208
	v_rcp_f32_e32 v209, v209
	v_rcp_f32_e32 v210, v210
	v_rcp_f32_e32 v211, v211
	v_rcp_f32_e32 v212, v212
	v_rcp_f32_e32 v213, v213
	v_pk_mul_f32 v[206:207], v[102:103], v[206:207]
	v_pk_mul_f32 v[208:209], v[104:105], v[208:209]
	v_pk_mul_f32 v[210:211], v[98:99], v[210:211]
	v_pk_mul_f32 v[212:213], v[100:101], v[212:213]
	v_pk_mul_f32 v[214:215], v[38:39], s[24:25] op_sel_hi:[1,0]
	v_pk_mul_f32 v[216:217], v[40:41], s[24:25] op_sel_hi:[1,0]
	v_pk_mul_f32 v[218:219], v[34:35], s[24:25] op_sel_hi:[1,0]
	v_pk_mul_f32 v[220:221], v[36:37], s[24:25] op_sel_hi:[1,0]
	v_exp_f32_e32 v214, v214
	v_exp_f32_e32 v215, v215
	v_exp_f32_e32 v216, v216
	v_exp_f32_e32 v217, v217
	v_exp_f32_e32 v218, v218
	v_exp_f32_e32 v219, v219
	v_exp_f32_e32 v220, v220
	v_exp_f32_e32 v221, v221
	v_pk_add_f32 v[214:215], v[214:215], 1.0 op_sel_hi:[1,0]
	v_pk_add_f32 v[216:217], v[216:217], 1.0 op_sel_hi:[1,0]
	v_pk_add_f32 v[218:219], v[218:219], 1.0 op_sel_hi:[1,0]
	v_pk_add_f32 v[220:221], v[220:221], 1.0 op_sel_hi:[1,0]
	v_rcp_f32_e32 v214, v214
	v_rcp_f32_e32 v215, v215
	v_rcp_f32_e32 v216, v216
	v_rcp_f32_e32 v217, v217
	v_rcp_f32_e32 v218, v218
	v_rcp_f32_e32 v219, v219
	v_rcp_f32_e32 v220, v220
	v_rcp_f32_e32 v221, v221
	v_pk_mul_f32 v[214:215], v[38:39], v[214:215]
	v_pk_mul_f32 v[216:217], v[40:41], v[216:217]
	v_pk_mul_f32 v[218:219], v[34:35], v[218:219]
	v_pk_mul_f32 v[220:221], v[36:37], v[220:221]
	v_cvt_pk_bf16_f32 v156, v206, v207
	v_cvt_pk_bf16_f32 v157, v208, v209
	v_cvt_pk_bf16_f32 v158, v210, v211
	v_cvt_pk_bf16_f32 v159, v212, v213
	v_cvt_pk_bf16_f32 v160, v214, v215
	v_cvt_pk_bf16_f32 v161, v216, v217
	v_cvt_pk_bf16_f32 v162, v218, v219
	v_cvt_pk_bf16_f32 v163, v220, v221
	v_mov_b32_e32 v188, v160
	v_mov_b32_e32 v189, v161
	v_mov_b32_e32 v190, v162
	v_mov_b32_e32 v191, v163
	v_mov_b32_dpp v160, v156 row_ror:8 row_mask:0xf bank_mask:0x3
	v_mov_b32_dpp v161, v157 row_ror:8 row_mask:0xf bank_mask:0x3
	v_mov_b32_dpp v162, v158 row_ror:8 row_mask:0xf bank_mask:0x3
	v_mov_b32_dpp v163, v159 row_ror:8 row_mask:0xf bank_mask:0x3
	v_mov_b32_dpp v156, v188 row_ror:8 row_mask:0xf bank_mask:0xc
	v_mov_b32_dpp v157, v189 row_ror:8 row_mask:0xf bank_mask:0xc
	v_mov_b32_dpp v158, v190 row_ror:8 row_mask:0xf bank_mask:0xc
	v_mov_b32_dpp v159, v191 row_ror:8 row_mask:0xf bank_mask:0xc
	global_store_dwordx4 v138, v[156:159], s[6:7] nt
	global_store_dwordx4 v139, v[160:163], s[6:7] nt
	s_add_u32 s6, s6, 0x28000
	s_addc_u32 s7, s7, 0
	v_pk_mul_f32 v[172:173], v[94:95], s[24:25] op_sel_hi:[1,0]
	v_pk_mul_f32 v[174:175], v[96:97], s[24:25] op_sel_hi:[1,0]
	v_pk_mul_f32 v[176:177], v[90:91], s[24:25] op_sel_hi:[1,0]
	v_pk_mul_f32 v[178:179], v[92:93], s[24:25] op_sel_hi:[1,0]
	v_exp_f32_e32 v172, v172
	v_exp_f32_e32 v173, v173
	v_exp_f32_e32 v174, v174
	v_exp_f32_e32 v175, v175
	v_exp_f32_e32 v176, v176
	v_exp_f32_e32 v177, v177
	v_exp_f32_e32 v178, v178
	v_exp_f32_e32 v179, v179
	v_pk_add_f32 v[172:173], v[172:173], 1.0 op_sel_hi:[1,0]
	v_pk_add_f32 v[174:175], v[174:175], 1.0 op_sel_hi:[1,0]
	v_pk_add_f32 v[176:177], v[176:177], 1.0 op_sel_hi:[1,0]
	v_pk_add_f32 v[178:179], v[178:179], 1.0 op_sel_hi:[1,0]
	v_rcp_f32_e32 v172, v172
	v_rcp_f32_e32 v173, v173
	v_rcp_f32_e32 v174, v174
	v_rcp_f32_e32 v175, v175
	v_rcp_f32_e32 v176, v176
	v_rcp_f32_e32 v177, v177
	v_rcp_f32_e32 v178, v178
	v_rcp_f32_e32 v179, v179
	v_pk_mul_f32 v[172:173], v[94:95], v[172:173]
	v_pk_mul_f32 v[174:175], v[96:97], v[174:175]
	v_pk_mul_f32 v[176:177], v[90:91], v[176:177]
	v_pk_mul_f32 v[178:179], v[92:93], v[178:179]
	v_pk_mul_f32 v[180:181], v[30:31], s[24:25] op_sel_hi:[1,0]
	v_pk_mul_f32 v[182:183], v[32:33], s[24:25] op_sel_hi:[1,0]
	v_pk_mul_f32 v[184:185], v[26:27], s[24:25] op_sel_hi:[1,0]
	v_pk_mul_f32 v[186:187], v[28:29], s[24:25] op_sel_hi:[1,0]
	v_exp_f32_e32 v180, v180
	v_exp_f32_e32 v181, v181
	v_exp_f32_e32 v182, v182
; __device__ __forceinline__ float sigm(float x) { return __builtin_amdgcn_rcpf(1.f + __expf(-x)); }
; __device__ __forceinline__ u32x4 pack8(const f32x4 v0, const f32x4 v1) { u32x4 w; w.x = cvt_pk_bf16(v0[0], v0[1]); w.y = cvt_pk_bf16(v0[2], v0[3]); w.z = cvt_pk_bf16(v1[0], v1[1]); w.w = cvt_pk_bf16(v1[2], v1[3]); return w; }
;     __device__ __forceinline__ void operator()(f32x4 (&acc)[2][2][4][2], const Unit& u, int wr, int wc, int fr, int fq) const {
;     ...
;             for (int ai = 0; ai < 2; ++ai)
; #pragma unroll
;                 for (int m = 0; m < 4; ++m) { bf16_t* rowp = base + (size_t)(ai * HALF + m * 16) * LDZ;
; #pragma unroll
;                     for (int bj = 0; bj < 2; ++bj) { f32x4 v0 = acc[ai][bj][m][0], v1 = acc[ai][bj][m][1];
;                         if (kind == 1) {
; #pragma unroll
;                             for (int e = 0; e < 4; ++e) { v0[e] = v0[e] * sigm(v0[e]); v1[e] = v1[e] * sigm(v1[e]); } }
;                         else if (kind == 2) { v0 = v0 * (0.125f * LOG2E); v1 = v1 * (0.125f * LOG2E); }
;                         else if (kind == 3) {
; #pragma unroll
;                             for (int e = 0; e < 4; ++e) { v0[e] = sigm(v0[e] + bv[bj][0][e]); v1[e] = sigm(v1[e] + bv[bj][1][e]); } }
;                         __builtin_nontemporal_store(pack8(v0, v1), (u32x4*)(rowp + bj * HALF)); } }
	v_exp_f32_e32 v183, v183
	v_exp_f32_e32 v184, v184
	v_exp_f32_e32 v185, v185
	v_exp_f32_e32 v186, v186
	v_exp_f32_e32 v187, v187
	v_pk_add_f32 v[180:181], v[180:181], 1.0 op_sel_hi:[1,0]
	v_pk_add_f32 v[182:183], v[182:183], 1.0 op_sel_hi:[1,0]
	v_pk_add_f32 v[184:185], v[184:185], 1.0 op_sel_hi:[1,0]
	v_pk_add_f32 v[186:187], v[186:187], 1.0 op_sel_hi:[1,0]
	v_rcp_f32_e32 v180, v180
	v_rcp_f32_e32 v181, v181
	v_rcp_f32_e32 v182, v182
	v_rcp_f32_e32 v183, v183
	v_rcp_f32_e32 v184, v184
	v_rcp_f32_e32 v185, v185
	v_rcp_f32_e32 v186, v186
	v_rcp_f32_e32 v187, v187
	v_pk_mul_f32 v[180:181], v[30:31], v[180:181]
	v_pk_mul_f32 v[182:183], v[32:33], v[182:183]
	v_pk_mul_f32 v[184:185], v[26:27], v[184:185]
	v_pk_mul_f32 v[186:187], v[28:29], v[186:187]
	v_cvt_pk_bf16_f32 v130, v172, v173
	v_cvt_pk_bf16_f32 v131, v174, v175
	v_cvt_pk_bf16_f32 v132, v176, v177
	v_cvt_pk_bf16_f32 v133, v178, v179
	v_cvt_pk_bf16_f32 v134, v180, v181
	v_cvt_pk_bf16_f32 v135, v182, v183
	v_cvt_pk_bf16_f32 v136, v184, v185
	v_cvt_pk_bf16_f32 v137, v186, v187
	v_mov_b32_e32 v140, v134
	v_mov_b32_e32 v141, v135
	v_mov_b32_e32 v142, v136
	v_mov_b32_e32 v143, v137
	v_mov_b32_dpp v134, v130 row_ror:8 row_mask:0xf bank_mask:0x3
	v_mov_b32_dpp v135, v131 row_ror:8 row_mask:0xf bank_mask:0x3
	v_mov_b32_dpp v136, v132 row_ror:8 row_mask:0xf bank_mask:0x3
	v_mov_b32_dpp v137, v133 row_ror:8 row_mask:0xf bank_mask:0x3
	v_mov_b32_dpp v130, v140 row_ror:8 row_mask:0xf bank_mask:0xc
	v_mov_b32_dpp v131, v141 row_ror:8 row_mask:0xf bank_mask:0xc
	v_mov_b32_dpp v132, v142 row_ror:8 row_mask:0xf bank_mask:0xc
	v_mov_b32_dpp v133, v143 row_ror:8 row_mask:0xf bank_mask:0xc
	global_store_dwordx4 v138, v[130:133], s[6:7] nt
	global_store_dwordx4 v139, v[134:137], s[6:7] nt
	s_add_u32 s6, s6, 0x8000
	s_addc_u32 s7, s7, 0
	v_pk_mul_f32 v[206:207], v[86:87], s[24:25] op_sel_hi:[1,0]
	v_pk_mul_f32 v[208:209], v[88:89], s[24:25] op_sel_hi:[1,0]
	v_pk_mul_f32 v[210:211], v[82:83], s[24:25] op_sel_hi:[1,0]
	v_pk_mul_f32 v[212:213], v[84:85], s[24:25] op_sel_hi:[1,0]
	v_exp_f32_e32 v206, v206
	v_exp_f32_e32 v207, v207
	v_exp_f32_e32 v208, v208
	v_exp_f32_e32 v209, v209
	v_exp_f32_e32 v210, v210
	v_exp_f32_e32 v211, v211
	v_exp_f32_e32 v212, v212
	v_exp_f32_e32 v213, v213
	v_pk_add_f32 v[206:207], v[206:207], 1.0 op_sel_hi:[1,0]
	v_pk_add_f32 v[208:209], v[208:209], 1.0 op_sel_hi:[1,0]
	v_pk_add_f32 v[210:211], v[210:211], 1.0 op_sel_hi:[1,0]
	v_pk_add_f32 v[212:213], v[212:213], 1.0 op_sel_hi:[1,0]
	v_rcp_f32_e32 v206, v206
	v_rcp_f32_e32 v207, v207
	v_rcp_f32_e32 v208, v208
	v_rcp_f32_e32 v209, v209
	v_rcp_f32_e32 v210, v210
	v_rcp_f32_e32 v211, v211
	v_rcp_f32_e32 v212, v212
	v_rcp_f32_e32 v213, v213
	v_pk_mul_f32 v[206:207], v[86:87], v[206:207]
	v_pk_mul_f32 v[208:209], v[88:89], v[208:209]
	v_pk_mul_f32 v[210:211], v[82:83], v[210:211]
	v_pk_mul_f32 v[212:213], v[84:85], v[212:213]
	v_pk_mul_f32 v[214:215], v[22:23], s[24:25] op_sel_hi:[1,0]
	v_pk_mul_f32 v[216:217], v[24:25], s[24:25] op_sel_hi:[1,0]
	v_pk_mul_f32 v[218:219], v[18:19], s[24:25] op_sel_hi:[1,0]
	v_pk_mul_f32 v[220:221], v[20:21], s[24:25] op_sel_hi:[1,0]
	v_exp_f32_e32 v214, v214
	v_exp_f32_e32 v215, v215
	v_exp_f32_e32 v216, v216
	v_exp_f32_e32 v217, v217
	v_exp_f32_e32 v218, v218
	v_exp_f32_e32 v219, v219
	v_exp_f32_e32 v220, v220
	v_exp_f32_e32 v221, v221
	v_pk_add_f32 v[214:215], v[214:215], 1.0 op_sel_hi:[1,0]
	v_pk_add_f32 v[216:217], v[216:217], 1.0 op_sel_hi:[1,0]
	v_pk_add_f32 v[218:219], v[218:219], 1.0 op_sel_hi:[1,0]
	v_pk_add_f32 v[220:221], v[220:221], 1.0 op_sel_hi:[1,0]
	v_rcp_f32_e32 v214, v214
	v_rcp_f32_e32 v215, v215
	v_rcp_f32_e32 v216, v216
	v_rcp_f32_e32 v217, v217
	v_rcp_f32_e32 v218, v218
	v_rcp_f32_e32 v219, v219
	v_rcp_f32_e32 v220, v220
	v_rcp_f32_e32 v221, v221
	v_pk_mul_f32 v[214:215], v[22:23], v[214:215]
	v_pk_mul_f32 v[216:217], v[24:25], v[216:217]
	v_pk_mul_f32 v[218:219], v[18:19], v[218:219]
	v_pk_mul_f32 v[220:221], v[20:21], v[220:221]
	v_cvt_pk_bf16_f32 v156, v206, v207
	v_cvt_pk_bf16_f32 v157, v208, v209
	v_cvt_pk_bf16_f32 v158, v210, v211
	v_cvt_pk_bf16_f32 v159, v212, v213
	v_cvt_pk_bf16_f32 v160, v214, v215
	v_cvt_pk_bf16_f32 v161, v216, v217
	v_cvt_pk_bf16_f32 v162, v218, v219
	v_cvt_pk_bf16_f32 v163, v220, v221
	v_mov_b32_e32 v188, v160
	v_mov_b32_e32 v189, v161
	v_mov_b32_e32 v190, v162
	v_mov_b32_e32 v191, v163
	v_mov_b32_dpp v160, v156 row_ror:8 row_mask:0xf bank_mask:0x3
	v_mov_b32_dpp v161, v157 row_ror:8 row_mask:0xf bank_mask:0x3
	v_mov_b32_dpp v162, v158 row_ror:8 row_mask:0xf bank_mask:0x3
	v_mov_b32_dpp v163, v159 row_ror:8 row_mask:0xf bank_mask:0x3
	v_mov_b32_dpp v156, v188 row_ror:8 row_mask:0xf bank_mask:0xc
	v_mov_b32_dpp v157, v189 row_ror:8 row_mask:0xf bank_mask:0xc
	v_mov_b32_dpp v158, v190 row_ror:8 row_mask:0xf bank_mask:0xc
	v_mov_b32_dpp v159, v191 row_ror:8 row_mask:0xf bank_mask:0xc
	global_store_dwordx4 v138, v[156:159], s[6:7] nt
	global_store_dwordx4 v139, v[160:163], s[6:7] nt
	s_add_u32 s6, s6, 0x8000
	s_addc_u32 s7, s7, 0
	v_pk_mul_f32 v[172:173], v[78:79], s[24:25] op_sel_hi:[1,0]
	v_pk_mul_f32 v[174:175], v[80:81], s[24:25] op_sel_hi:[1,0]
	v_pk_mul_f32 v[176:177], v[74:75], s[24:25] op_sel_hi:[1,0]
	v_pk_mul_f32 v[178:179], v[76:77], s[24:25] op_sel_hi:[1,0]
	v_exp_f32_e32 v172, v172
	v_exp_f32_e32 v173, v173
	v_exp_f32_e32 v174, v174
	v_exp_f32_e32 v175, v175
	v_exp_f32_e32 v176, v176
	v_exp_f32_e32 v177, v177
	v_exp_f32_e32 v178, v178
	v_exp_f32_e32 v179, v179
	v_pk_add_f32 v[172:173], v[172:173], 1.0 op_sel_hi:[1,0]
	v_pk_add_f32 v[174:175], v[174:175], 1.0 op_sel_hi:[1,0]
	v_pk_add_f32 v[176:177], v[176:177], 1.0 op_sel_hi:[1,0]
; __device__ __forceinline__ float sigm(float x) { return __builtin_amdgcn_rcpf(1.f + __expf(-x)); }
; __device__ __forceinline__ u32x4 pack8(const f32x4 v0, const f32x4 v1) { u32x4 w; w.x = cvt_pk_bf16(v0[0], v0[1]); w.y = cvt_pk_bf16(v0[2], v0[3]); w.z = cvt_pk_bf16(v1[0], v1[1]); w.w = cvt_pk_bf16(v1[2], v1[3]); return w; }
;     __device__ __forceinline__ void operator()(f32x4 (&acc)[2][2][4][2], const Unit& u, int wr, int wc, int fr, int fq) const {
;     ...
; #pragma unroll
;             for (int ai = 0; ai < 2; ++ai)
; #pragma unroll
;                 for (int m = 0; m < 4; ++m) { bf16_t* rowp = base + (size_t)(ai * HALF + m * 16) * LDZ;
; #pragma unroll
;                     for (int bj = 0; bj < 2; ++bj) { f32x4 v0 = acc[ai][bj][m][0], v1 = acc[ai][bj][m][1];
;                         if (kind == 1) {
; #pragma unroll
;                             for (int e = 0; e < 4; ++e) { v0[e] = v0[e] * sigm(v0[e]); v1[e] = v1[e] * sigm(v1[e]); } }
;                         else if (kind == 2) { v0 = v0 * (0.125f * LOG2E); v1 = v1 * (0.125f * LOG2E); }
;                         else if (kind == 3) {
; #pragma unroll
;                             for (int e = 0; e < 4; ++e) { v0[e] = sigm(v0[e] + bv[bj][0][e]); v1[e] = sigm(v1[e] + bv[bj][1][e]); } }
;                         __builtin_nontemporal_store(pack8(v0, v1), (u32x4*)(rowp + bj * HALF)); } }
	v_pk_add_f32 v[178:179], v[178:179], 1.0 op_sel_hi:[1,0]
	v_rcp_f32_e32 v172, v172
	v_rcp_f32_e32 v173, v173
	v_rcp_f32_e32 v174, v174
	v_rcp_f32_e32 v175, v175
	v_rcp_f32_e32 v176, v176
	v_rcp_f32_e32 v177, v177
	v_rcp_f32_e32 v178, v178
	v_rcp_f32_e32 v179, v179
	v_pk_mul_f32 v[172:173], v[78:79], v[172:173]
	v_pk_mul_f32 v[174:175], v[80:81], v[174:175]
	v_pk_mul_f32 v[176:177], v[74:75], v[176:177]
	v_pk_mul_f32 v[178:179], v[76:77], v[178:179]
	v_pk_mul_f32 v[180:181], v[14:15], s[24:25] op_sel_hi:[1,0]
	v_pk_mul_f32 v[182:183], v[16:17], s[24:25] op_sel_hi:[1,0]
	v_pk_mul_f32 v[184:185], v[10:11], s[24:25] op_sel_hi:[1,0]
	v_pk_mul_f32 v[186:187], v[12:13], s[24:25] op_sel_hi:[1,0]
	v_exp_f32_e32 v180, v180
	v_exp_f32_e32 v181, v181
	v_exp_f32_e32 v182, v182
	v_exp_f32_e32 v183, v183
	v_exp_f32_e32 v184, v184
	v_exp_f32_e32 v185, v185
	v_exp_f32_e32 v186, v186
	v_exp_f32_e32 v187, v187
	v_pk_add_f32 v[180:181], v[180:181], 1.0 op_sel_hi:[1,0]
	v_pk_add_f32 v[182:183], v[182:183], 1.0 op_sel_hi:[1,0]
	v_pk_add_f32 v[184:185], v[184:185], 1.0 op_sel_hi:[1,0]
	v_pk_add_f32 v[186:187], v[186:187], 1.0 op_sel_hi:[1,0]
	v_rcp_f32_e32 v180, v180
	v_rcp_f32_e32 v181, v181
	v_rcp_f32_e32 v182, v182
	v_rcp_f32_e32 v183, v183
	v_rcp_f32_e32 v184, v184
	v_rcp_f32_e32 v185, v185
	v_rcp_f32_e32 v186, v186
	v_rcp_f32_e32 v187, v187
	v_pk_mul_f32 v[180:181], v[14:15], v[180:181]
	v_pk_mul_f32 v[182:183], v[16:17], v[182:183]
	v_pk_mul_f32 v[184:185], v[10:11], v[184:185]
	v_pk_mul_f32 v[186:187], v[12:13], v[186:187]
	v_cvt_pk_bf16_f32 v130, v172, v173
	v_cvt_pk_bf16_f32 v131, v174, v175
	v_cvt_pk_bf16_f32 v132, v176, v177
	v_cvt_pk_bf16_f32 v133, v178, v179
	v_cvt_pk_bf16_f32 v134, v180, v181
	v_cvt_pk_bf16_f32 v135, v182, v183
	v_cvt_pk_bf16_f32 v136, v184, v185
	v_cvt_pk_bf16_f32 v137, v186, v187
	v_mov_b32_e32 v140, v134
	v_mov_b32_e32 v141, v135
	v_mov_b32_e32 v142, v136
	v_mov_b32_e32 v143, v137
	v_mov_b32_dpp v134, v130 row_ror:8 row_mask:0xf bank_mask:0x3
	v_mov_b32_dpp v135, v131 row_ror:8 row_mask:0xf bank_mask:0x3
	v_mov_b32_dpp v136, v132 row_ror:8 row_mask:0xf bank_mask:0x3
	v_mov_b32_dpp v137, v133 row_ror:8 row_mask:0xf bank_mask:0x3
	v_mov_b32_dpp v130, v140 row_ror:8 row_mask:0xf bank_mask:0xc
	v_mov_b32_dpp v131, v141 row_ror:8 row_mask:0xf bank_mask:0xc
	v_mov_b32_dpp v132, v142 row_ror:8 row_mask:0xf bank_mask:0xc
	v_mov_b32_dpp v133, v143 row_ror:8 row_mask:0xf bank_mask:0xc
	global_store_dwordx4 v138, v[130:133], s[6:7] nt
	global_store_dwordx4 v139, v[134:137], s[6:7] nt
	s_add_u32 s6, s6, 0x8000
	s_addc_u32 s7, s7, 0
	v_pk_mul_f32 v[206:207], v[70:71], s[24:25] op_sel_hi:[1,0]
	v_pk_mul_f32 v[208:209], v[72:73], s[24:25] op_sel_hi:[1,0]
	v_pk_mul_f32 v[210:211], v[66:67], s[24:25] op_sel_hi:[1,0]
	v_pk_mul_f32 v[212:213], v[68:69], s[24:25] op_sel_hi:[1,0]
	v_exp_f32_e32 v206, v206
	v_exp_f32_e32 v207, v207
	v_exp_f32_e32 v208, v208
	v_exp_f32_e32 v209, v209
	v_exp_f32_e32 v210, v210
	v_exp_f32_e32 v211, v211
	v_exp_f32_e32 v212, v212
	v_exp_f32_e32 v213, v213
	v_pk_add_f32 v[206:207], v[206:207], 1.0 op_sel_hi:[1,0]
	v_pk_add_f32 v[208:209], v[208:209], 1.0 op_sel_hi:[1,0]
	v_pk_add_f32 v[210:211], v[210:211], 1.0 op_sel_hi:[1,0]
	v_pk_add_f32 v[212:213], v[212:213], 1.0 op_sel_hi:[1,0]
	v_rcp_f32_e32 v206, v206
	v_rcp_f32_e32 v207, v207
	v_rcp_f32_e32 v208, v208
	v_rcp_f32_e32 v209, v209
	v_rcp_f32_e32 v210, v210
	v_rcp_f32_e32 v211, v211
	v_rcp_f32_e32 v212, v212
	v_rcp_f32_e32 v213, v213
	v_pk_mul_f32 v[206:207], v[70:71], v[206:207]
	v_pk_mul_f32 v[208:209], v[72:73], v[208:209]
	v_pk_mul_f32 v[210:211], v[66:67], v[210:211]
	v_pk_mul_f32 v[212:213], v[68:69], v[212:213]
	v_pk_mul_f32 v[214:215], v[6:7], s[24:25] op_sel_hi:[1,0]
	v_pk_mul_f32 v[216:217], v[8:9], s[24:25] op_sel_hi:[1,0]
	v_pk_mul_f32 v[218:219], v[2:3], s[24:25] op_sel_hi:[1,0]
	v_pk_mul_f32 v[220:221], v[4:5], s[24:25] op_sel_hi:[1,0]
	v_exp_f32_e32 v214, v214
	v_exp_f32_e32 v215, v215
	v_exp_f32_e32 v216, v216
	v_exp_f32_e32 v217, v217
	v_exp_f32_e32 v218, v218
	v_exp_f32_e32 v219, v219
	v_exp_f32_e32 v220, v220
	v_exp_f32_e32 v221, v221
	v_pk_add_f32 v[214:215], v[214:215], 1.0 op_sel_hi:[1,0]
	v_pk_add_f32 v[216:217], v[216:217], 1.0 op_sel_hi:[1,0]
	v_pk_add_f32 v[218:219], v[218:219], 1.0 op_sel_hi:[1,0]
	v_pk_add_f32 v[220:221], v[220:221], 1.0 op_sel_hi:[1,0]
	v_rcp_f32_e32 v214, v214
	v_rcp_f32_e32 v215, v215
	v_rcp_f32_e32 v216, v216
	v_rcp_f32_e32 v217, v217
	v_rcp_f32_e32 v218, v218
	v_rcp_f32_e32 v219, v219
	v_rcp_f32_e32 v220, v220
	v_rcp_f32_e32 v221, v221
	v_pk_mul_f32 v[214:215], v[6:7], v[214:215]
	v_pk_mul_f32 v[216:217], v[8:9], v[216:217]
	v_pk_mul_f32 v[218:219], v[2:3], v[218:219]
	v_pk_mul_f32 v[220:221], v[4:5], v[220:221]
	v_cvt_pk_bf16_f32 v156, v206, v207
	v_cvt_pk_bf16_f32 v157, v208, v209
	v_cvt_pk_bf16_f32 v158, v210, v211
	v_cvt_pk_bf16_f32 v159, v212, v213
	v_cvt_pk_bf16_f32 v160, v214, v215
	v_cvt_pk_bf16_f32 v161, v216, v217
	v_cvt_pk_bf16_f32 v162, v218, v219
	v_cvt_pk_bf16_f32 v163, v220, v221
	v_mov_b32_e32 v188, v160
	v_mov_b32_e32 v189, v161
	v_mov_b32_e32 v190, v162
	v_mov_b32_e32 v191, v163
	v_mov_b32_dpp v160, v156 row_ror:8 row_mask:0xf bank_mask:0x3
	v_mov_b32_dpp v161, v157 row_ror:8 row_mask:0xf bank_mask:0x3
	v_mov_b32_dpp v162, v158 row_ror:8 row_mask:0xf bank_mask:0x3
	v_mov_b32_dpp v163, v159 row_ror:8 row_mask:0xf bank_mask:0x3
	v_mov_b32_dpp v156, v188 row_ror:8 row_mask:0xf bank_mask:0xc
	v_mov_b32_dpp v157, v189 row_ror:8 row_mask:0xf bank_mask:0xc
	v_mov_b32_dpp v158, v190 row_ror:8 row_mask:0xf bank_mask:0xc
	v_mov_b32_dpp v159, v191 row_ror:8 row_mask:0xf bank_mask:0xc
	global_store_dwordx4 v138, v[156:159], s[6:7] nt
	global_store_dwordx4 v139, v[160:163], s[6:7] nt
	s_branch .Lepi1_done
; __device__ __forceinline__ float sigm(float x) { return __builtin_amdgcn_rcpf(1.f + __expf(-x)); }
; __device__ __forceinline__ u32x4 pack8(const f32x4 v0, const f32x4 v1) { u32x4 w; w.x = cvt_pk_bf16(v0[0], v0[1]); w.y = cvt_pk_bf16(v0[2], v0[3]); w.z = cvt_pk_bf16(v1[0], v1[1]); w.w = cvt_pk_bf16(v1[2], v1[3]); return w; }
;     __device__ __forceinline__ void operator()(f32x4 (&acc)[2][2][4][2], const Unit& u, int wr, int wc, int fr, int fq) const {
;     ...
; #pragma unroll
;             for (int ai = 0; ai < 2; ++ai)
; #pragma unroll
;                 for (int m = 0; m < 4; ++m) { bf16_t* rowp = base + (size_t)(ai * HALF + m * 16) * LDZ;
; #pragma unroll
;                     for (int bj = 0; bj < 2; ++bj) { f32x4 v0 = acc[ai][bj][m][0], v1 = acc[ai][bj][m][1];
;                         if (kind == 1) {
; #pragma unroll
;                             for (int e = 0; e < 4; ++e) { v0[e] = v0[e] * sigm(v0[e]); v1[e] = v1[e] * sigm(v1[e]); } }
;                         else if (kind == 2) { v0 = v0 * (0.125f * LOG2E); v1 = v1 * (0.125f * LOG2E); }
;                         else if (kind == 3) {
; #pragma unroll
;                             for (int e = 0; e < 4; ++e) { v0[e] = sigm(v0[e] + bv[bj][0][e]); v1[e] = sigm(v1[e] + bv[bj][1][e]); } }
;                         __builtin_nontemporal_store(pack8(v0, v1), (u32x4*)(rowp + bj * HALF)); } }
.Lepi1_k2:
	s_mov_b64 s[6:7], s[50:51]
	v_pk_mul_f32 v[172:173], v[126:127], s[26:27] op_sel_hi:[1,0]
	v_pk_mul_f32 v[174:175], v[128:129], s[26:27] op_sel_hi:[1,0]
	v_pk_mul_f32 v[176:177], v[122:123], s[26:27] op_sel_hi:[1,0]
	v_pk_mul_f32 v[178:179], v[124:125], s[26:27] op_sel_hi:[1,0]
	v_pk_mul_f32 v[180:181], v[62:63], s[26:27] op_sel_hi:[1,0]
	v_pk_mul_f32 v[182:183], v[64:65], s[26:27] op_sel_hi:[1,0]
	v_pk_mul_f32 v[184:185], v[58:59], s[26:27] op_sel_hi:[1,0]
	v_pk_mul_f32 v[186:187], v[60:61], s[26:27] op_sel_hi:[1,0]
	v_cvt_pk_bf16_f32 v130, v172, v173
	v_cvt_pk_bf16_f32 v131, v174, v175
	v_cvt_pk_bf16_f32 v132, v176, v177
	v_cvt_pk_bf16_f32 v133, v178, v179
	v_cvt_pk_bf16_f32 v134, v180, v181
	v_cvt_pk_bf16_f32 v135, v182, v183
	v_cvt_pk_bf16_f32 v136, v184, v185
	v_cvt_pk_bf16_f32 v137, v186, v187
	v_mov_b32_e32 v140, v134
	v_mov_b32_e32 v141, v135
	v_mov_b32_e32 v142, v136
	v_mov_b32_e32 v143, v137
	v_mov_b32_dpp v134, v130 row_ror:8 row_mask:0xf bank_mask:0x3
	v_mov_b32_dpp v135, v131 row_ror:8 row_mask:0xf bank_mask:0x3
	v_mov_b32_dpp v136, v132 row_ror:8 row_mask:0xf bank_mask:0x3
	v_mov_b32_dpp v137, v133 row_ror:8 row_mask:0xf bank_mask:0x3
	v_mov_b32_dpp v130, v140 row_ror:8 row_mask:0xf bank_mask:0xc
	v_mov_b32_dpp v131, v141 row_ror:8 row_mask:0xf bank_mask:0xc
	v_mov_b32_dpp v132, v142 row_ror:8 row_mask:0xf bank_mask:0xc
	v_mov_b32_dpp v133, v143 row_ror:8 row_mask:0xf bank_mask:0xc
	global_store_dwordx4 v138, v[130:133], s[6:7] nt
	global_store_dwordx4 v139, v[134:137], s[6:7] nt
	s_add_u32 s6, s6, 0x8000
	s_addc_u32 s7, s7, 0
	v_pk_mul_f32 v[206:207], v[118:119], s[26:27] op_sel_hi:[1,0]
	v_pk_mul_f32 v[208:209], v[120:121], s[26:27] op_sel_hi:[1,0]
	v_pk_mul_f32 v[210:211], v[114:115], s[26:27] op_sel_hi:[1,0]
	v_pk_mul_f32 v[212:213], v[116:117], s[26:27] op_sel_hi:[1,0]
	v_pk_mul_f32 v[214:215], v[54:55], s[26:27] op_sel_hi:[1,0]
	v_pk_mul_f32 v[216:217], v[56:57], s[26:27] op_sel_hi:[1,0]
	v_pk_mul_f32 v[218:219], v[50:51], s[26:27] op_sel_hi:[1,0]
	v_pk_mul_f32 v[220:221], v[52:53], s[26:27] op_sel_hi:[1,0]
	v_cvt_pk_bf16_f32 v156, v206, v207
	v_cvt_pk_bf16_f32 v157, v208, v209
	v_cvt_pk_bf16_f32 v158, v210, v211
	v_cvt_pk_bf16_f32 v159, v212, v213
	v_cvt_pk_bf16_f32 v160, v214, v215
	v_cvt_pk_bf16_f32 v161, v216, v217
	v_cvt_pk_bf16_f32 v162, v218, v219
	v_cvt_pk_bf16_f32 v163, v220, v221
	v_mov_b32_e32 v188, v160
	v_mov_b32_e32 v189, v161
	v_mov_b32_e32 v190, v162
	v_mov_b32_e32 v191, v163
	v_mov_b32_dpp v160, v156 row_ror:8 row_mask:0xf bank_mask:0x3
	v_mov_b32_dpp v161, v157 row_ror:8 row_mask:0xf bank_mask:0x3
	v_mov_b32_dpp v162, v158 row_ror:8 row_mask:0xf bank_mask:0x3
	v_mov_b32_dpp v163, v159 row_ror:8 row_mask:0xf bank_mask:0x3
	v_mov_b32_dpp v156, v188 row_ror:8 row_mask:0xf bank_mask:0xc
	v_mov_b32_dpp v157, v189 row_ror:8 row_mask:0xf bank_mask:0xc
	v_mov_b32_dpp v158, v190 row_ror:8 row_mask:0xf bank_mask:0xc
	v_mov_b32_dpp v159, v191 row_ror:8 row_mask:0xf bank_mask:0xc
	global_store_dwordx4 v138, v[156:159], s[6:7] nt
	global_store_dwordx4 v139, v[160:163], s[6:7] nt
	s_add_u32 s6, s6, 0x8000
	s_addc_u32 s7, s7, 0
	v_pk_mul_f32 v[172:173], v[110:111], s[26:27] op_sel_hi:[1,0]
	v_pk_mul_f32 v[174:175], v[112:113], s[26:27] op_sel_hi:[1,0]
	v_pk_mul_f32 v[176:177], v[106:107], s[26:27] op_sel_hi:[1,0]
	v_pk_mul_f32 v[178:179], v[108:109], s[26:27] op_sel_hi:[1,0]
	v_pk_mul_f32 v[180:181], v[46:47], s[26:27] op_sel_hi:[1,0]
	v_pk_mul_f32 v[182:183], v[48:49], s[26:27] op_sel_hi:[1,0]
	v_pk_mul_f32 v[184:185], v[42:43], s[26:27] op_sel_hi:[1,0]
	v_pk_mul_f32 v[186:187], v[44:45], s[26:27] op_sel_hi:[1,0]
	v_cvt_pk_bf16_f32 v130, v172, v173
	v_cvt_pk_bf16_f32 v131, v174, v175
	v_cvt_pk_bf16_f32 v132, v176, v177
	v_cvt_pk_bf16_f32 v133, v178, v179
	v_cvt_pk_bf16_f32 v134, v180, v181
	v_cvt_pk_bf16_f32 v135, v182, v183
	v_cvt_pk_bf16_f32 v136, v184, v185
	v_cvt_pk_bf16_f32 v137, v186, v187
	v_mov_b32_e32 v140, v134
	v_mov_b32_e32 v141, v135
	v_mov_b32_e32 v142, v136
	v_mov_b32_e32 v143, v137
	v_mov_b32_dpp v134, v130 row_ror:8 row_mask:0xf bank_mask:0x3
	v_mov_b32_dpp v135, v131 row_ror:8 row_mask:0xf bank_mask:0x3
	v_mov_b32_dpp v136, v132 row_ror:8 row_mask:0xf bank_mask:0x3
	v_mov_b32_dpp v137, v133 row_ror:8 row_mask:0xf bank_mask:0x3
	v_mov_b32_dpp v130, v140 row_ror:8 row_mask:0xf bank_mask:0xc
	v_mov_b32_dpp v131, v141 row_ror:8 row_mask:0xf bank_mask:0xc
	v_mov_b32_dpp v132, v142 row_ror:8 row_mask:0xf bank_mask:0xc
	v_mov_b32_dpp v133, v143 row_ror:8 row_mask:0xf bank_mask:0xc
	global_store_dwordx4 v138, v[130:133], s[6:7] nt
	global_store_dwordx4 v139, v[134:137], s[6:7] nt
	s_add_u32 s6, s6, 0x8000
	s_addc_u32 s7, s7, 0
	v_pk_mul_f32 v[206:207], v[102:103], s[26:27] op_sel_hi:[1,0]
	v_pk_mul_f32 v[208:209], v[104:105], s[26:27] op_sel_hi:[1,0]
	v_pk_mul_f32 v[210:211], v[98:99], s[26:27] op_sel_hi:[1,0]
	v_pk_mul_f32 v[212:213], v[100:101], s[26:27] op_sel_hi:[1,0]
	v_pk_mul_f32 v[214:215], v[38:39], s[26:27] op_sel_hi:[1,0]
	v_pk_mul_f32 v[216:217], v[40:41], s[26:27] op_sel_hi:[1,0]
	v_pk_mul_f32 v[218:219], v[34:35], s[26:27] op_sel_hi:[1,0]
	v_pk_mul_f32 v[220:221], v[36:37], s[26:27] op_sel_hi:[1,0]
	v_cvt_pk_bf16_f32 v156, v206, v207
	v_cvt_pk_bf16_f32 v157, v208, v209
	v_cvt_pk_bf16_f32 v158, v210, v211
	v_cvt_pk_bf16_f32 v159, v212, v213
	v_cvt_pk_bf16_f32 v160, v214, v215
	v_cvt_pk_bf16_f32 v161, v216, v217
	v_cvt_pk_bf16_f32 v162, v218, v219
	v_cvt_pk_bf16_f32 v163, v220, v221
	v_mov_b32_e32 v188, v160
	v_mov_b32_e32 v189, v161
	v_mov_b32_e32 v190, v162
	v_mov_b32_e32 v191, v163
	v_mov_b32_dpp v160, v156 row_ror:8 row_mask:0xf bank_mask:0x3
	v_mov_b32_dpp v161, v157 row_ror:8 row_mask:0xf bank_mask:0x3
; __device__ __forceinline__ float sigm(float x) { return __builtin_amdgcn_rcpf(1.f + __expf(-x)); }
; __device__ __forceinline__ u32x4 pack8(const f32x4 v0, const f32x4 v1) { u32x4 w; w.x = cvt_pk_bf16(v0[0], v0[1]); w.y = cvt_pk_bf16(v0[2], v0[3]); w.z = cvt_pk_bf16(v1[0], v1[1]); w.w = cvt_pk_bf16(v1[2], v1[3]); return w; }
;     __device__ __forceinline__ void operator()(f32x4 (&acc)[2][2][4][2], const Unit& u, int wr, int wc, int fr, int fq) const {
;     ...
; #pragma unroll
;             for (int ai = 0; ai < 2; ++ai)
; #pragma unroll
;                 for (int m = 0; m < 4; ++m) { bf16_t* rowp = base + (size_t)(ai * HALF + m * 16) * LDZ;
; #pragma unroll
;                     for (int bj = 0; bj < 2; ++bj) { f32x4 v0 = acc[ai][bj][m][0], v1 = acc[ai][bj][m][1];
;                         if (kind == 1) {
; #pragma unroll
;                             for (int e = 0; e < 4; ++e) { v0[e] = v0[e] * sigm(v0[e]); v1[e] = v1[e] * sigm(v1[e]); } }
;                         else if (kind == 2) { v0 = v0 * (0.125f * LOG2E); v1 = v1 * (0.125f * LOG2E); }
;                         else if (kind == 3) {
; #pragma unroll
;                             for (int e = 0; e < 4; ++e) { v0[e] = sigm(v0[e] + bv[bj][0][e]); v1[e] = sigm(v1[e] + bv[bj][1][e]); } }
;                         __builtin_nontemporal_store(pack8(v0, v1), (u32x4*)(rowp + bj * HALF)); } }
	v_mov_b32_dpp v162, v158 row_ror:8 row_mask:0xf bank_mask:0x3
	v_mov_b32_dpp v163, v159 row_ror:8 row_mask:0xf bank_mask:0x3
	v_mov_b32_dpp v156, v188 row_ror:8 row_mask:0xf bank_mask:0xc
	v_mov_b32_dpp v157, v189 row_ror:8 row_mask:0xf bank_mask:0xc
	v_mov_b32_dpp v158, v190 row_ror:8 row_mask:0xf bank_mask:0xc
	v_mov_b32_dpp v159, v191 row_ror:8 row_mask:0xf bank_mask:0xc
	global_store_dwordx4 v138, v[156:159], s[6:7] nt
	global_store_dwordx4 v139, v[160:163], s[6:7] nt
	s_add_u32 s6, s6, 0x28000
	s_addc_u32 s7, s7, 0
	v_pk_mul_f32 v[172:173], v[94:95], s[26:27] op_sel_hi:[1,0]
	v_pk_mul_f32 v[174:175], v[96:97], s[26:27] op_sel_hi:[1,0]
	v_pk_mul_f32 v[176:177], v[90:91], s[26:27] op_sel_hi:[1,0]
	v_pk_mul_f32 v[178:179], v[92:93], s[26:27] op_sel_hi:[1,0]
	v_pk_mul_f32 v[180:181], v[30:31], s[26:27] op_sel_hi:[1,0]
	v_pk_mul_f32 v[182:183], v[32:33], s[26:27] op_sel_hi:[1,0]
	v_pk_mul_f32 v[184:185], v[26:27], s[26:27] op_sel_hi:[1,0]
	v_pk_mul_f32 v[186:187], v[28:29], s[26:27] op_sel_hi:[1,0]
	v_cvt_pk_bf16_f32 v130, v172, v173
	v_cvt_pk_bf16_f32 v131, v174, v175
	v_cvt_pk_bf16_f32 v132, v176, v177
	v_cvt_pk_bf16_f32 v133, v178, v179
	v_cvt_pk_bf16_f32 v134, v180, v181
	v_cvt_pk_bf16_f32 v135, v182, v183
	v_cvt_pk_bf16_f32 v136, v184, v185
	v_cvt_pk_bf16_f32 v137, v186, v187
	v_mov_b32_e32 v140, v134
	v_mov_b32_e32 v141, v135
	v_mov_b32_e32 v142, v136
	v_mov_b32_e32 v143, v137
	v_mov_b32_dpp v134, v130 row_ror:8 row_mask:0xf bank_mask:0x3
	v_mov_b32_dpp v135, v131 row_ror:8 row_mask:0xf bank_mask:0x3
	v_mov_b32_dpp v136, v132 row_ror:8 row_mask:0xf bank_mask:0x3
	v_mov_b32_dpp v137, v133 row_ror:8 row_mask:0xf bank_mask:0x3
	v_mov_b32_dpp v130, v140 row_ror:8 row_mask:0xf bank_mask:0xc
	v_mov_b32_dpp v131, v141 row_ror:8 row_mask:0xf bank_mask:0xc
	v_mov_b32_dpp v132, v142 row_ror:8 row_mask:0xf bank_mask:0xc
	v_mov_b32_dpp v133, v143 row_ror:8 row_mask:0xf bank_mask:0xc
	global_store_dwordx4 v138, v[130:133], s[6:7] nt
	global_store_dwordx4 v139, v[134:137], s[6:7] nt
	s_add_u32 s6, s6, 0x8000
	s_addc_u32 s7, s7, 0
	v_pk_mul_f32 v[206:207], v[86:87], s[26:27] op_sel_hi:[1,0]
	v_pk_mul_f32 v[208:209], v[88:89], s[26:27] op_sel_hi:[1,0]
	v_pk_mul_f32 v[210:211], v[82:83], s[26:27] op_sel_hi:[1,0]
	v_pk_mul_f32 v[212:213], v[84:85], s[26:27] op_sel_hi:[1,0]
	v_pk_mul_f32 v[214:215], v[22:23], s[26:27] op_sel_hi:[1,0]
	v_pk_mul_f32 v[216:217], v[24:25], s[26:27] op_sel_hi:[1,0]
	v_pk_mul_f32 v[218:219], v[18:19], s[26:27] op_sel_hi:[1,0]
	v_pk_mul_f32 v[220:221], v[20:21], s[26:27] op_sel_hi:[1,0]
	v_cvt_pk_bf16_f32 v156, v206, v207
	v_cvt_pk_bf16_f32 v157, v208, v209
	v_cvt_pk_bf16_f32 v158, v210, v211
	v_cvt_pk_bf16_f32 v159, v212, v213
	v_cvt_pk_bf16_f32 v160, v214, v215
	v_cvt_pk_bf16_f32 v161, v216, v217
	v_cvt_pk_bf16_f32 v162, v218, v219
	v_cvt_pk_bf16_f32 v163, v220, v221
	v_mov_b32_e32 v188, v160
	v_mov_b32_e32 v189, v161
	v_mov_b32_e32 v190, v162
	v_mov_b32_e32 v191, v163
	v_mov_b32_dpp v160, v156 row_ror:8 row_mask:0xf bank_mask:0x3
	v_mov_b32_dpp v161, v157 row_ror:8 row_mask:0xf bank_mask:0x3
	v_mov_b32_dpp v162, v158 row_ror:8 row_mask:0xf bank_mask:0x3
	v_mov_b32_dpp v163, v159 row_ror:8 row_mask:0xf bank_mask:0x3
	v_mov_b32_dpp v156, v188 row_ror:8 row_mask:0xf bank_mask:0xc
	v_mov_b32_dpp v157, v189 row_ror:8 row_mask:0xf bank_mask:0xc
	v_mov_b32_dpp v158, v190 row_ror:8 row_mask:0xf bank_mask:0xc
	v_mov_b32_dpp v159, v191 row_ror:8 row_mask:0xf bank_mask:0xc
	global_store_dwordx4 v138, v[156:159], s[6:7] nt
	global_store_dwordx4 v139, v[160:163], s[6:7] nt
	s_add_u32 s6, s6, 0x8000
	s_addc_u32 s7, s7, 0
	v_pk_mul_f32 v[172:173], v[78:79], s[26:27] op_sel_hi:[1,0]
	v_pk_mul_f32 v[174:175], v[80:81], s[26:27] op_sel_hi:[1,0]
	v_pk_mul_f32 v[176:177], v[74:75], s[26:27] op_sel_hi:[1,0]
	v_pk_mul_f32 v[178:179], v[76:77], s[26:27] op_sel_hi:[1,0]
	v_pk_mul_f32 v[180:181], v[14:15], s[26:27] op_sel_hi:[1,0]
	v_pk_mul_f32 v[182:183], v[16:17], s[26:27] op_sel_hi:[1,0]
	v_pk_mul_f32 v[184:185], v[10:11], s[26:27] op_sel_hi:[1,0]
	v_pk_mul_f32 v[186:187], v[12:13], s[26:27] op_sel_hi:[1,0]
	v_cvt_pk_bf16_f32 v130, v172, v173
	v_cvt_pk_bf16_f32 v131, v174, v175
	v_cvt_pk_bf16_f32 v132, v176, v177
	v_cvt_pk_bf16_f32 v133, v178, v179
	v_cvt_pk_bf16_f32 v134, v180, v181
	v_cvt_pk_bf16_f32 v135, v182, v183
	v_cvt_pk_bf16_f32 v136, v184, v185
	v_cvt_pk_bf16_f32 v137, v186, v187
	v_mov_b32_e32 v140, v134
	v_mov_b32_e32 v141, v135
	v_mov_b32_e32 v142, v136
	v_mov_b32_e32 v143, v137
	v_mov_b32_dpp v134, v130 row_ror:8 row_mask:0xf bank_mask:0x3
	v_mov_b32_dpp v135, v131 row_ror:8 row_mask:0xf bank_mask:0x3
	v_mov_b32_dpp v136, v132 row_ror:8 row_mask:0xf bank_mask:0x3
	v_mov_b32_dpp v137, v133 row_ror:8 row_mask:0xf bank_mask:0x3
	v_mov_b32_dpp v130, v140 row_ror:8 row_mask:0xf bank_mask:0xc
	v_mov_b32_dpp v131, v141 row_ror:8 row_mask:0xf bank_mask:0xc
	v_mov_b32_dpp v132, v142 row_ror:8 row_mask:0xf bank_mask:0xc
	v_mov_b32_dpp v133, v143 row_ror:8 row_mask:0xf bank_mask:0xc
	global_store_dwordx4 v138, v[130:133], s[6:7] nt
	global_store_dwordx4 v139, v[134:137], s[6:7] nt
	s_add_u32 s6, s6, 0x8000
	s_addc_u32 s7, s7, 0
	v_pk_mul_f32 v[206:207], v[70:71], s[26:27] op_sel_hi:[1,0]
	v_pk_mul_f32 v[208:209], v[72:73], s[26:27] op_sel_hi:[1,0]
	v_pk_mul_f32 v[210:211], v[66:67], s[26:27] op_sel_hi:[1,0]
	v_pk_mul_f32 v[212:213], v[68:69], s[26:27] op_sel_hi:[1,0]
	v_pk_mul_f32 v[214:215], v[6:7], s[26:27] op_sel_hi:[1,0]
	v_pk_mul_f32 v[216:217], v[8:9], s[26:27] op_sel_hi:[1,0]
	v_pk_mul_f32 v[218:219], v[2:3], s[26:27] op_sel_hi:[1,0]
	v_pk_mul_f32 v[220:221], v[4:5], s[26:27] op_sel_hi:[1,0]
	v_cvt_pk_bf16_f32 v156, v206, v207
	v_cvt_pk_bf16_f32 v157, v208, v209
	v_cvt_pk_bf16_f32 v158, v210, v211
	v_cvt_pk_bf16_f32 v159, v212, v213
	v_cvt_pk_bf16_f32 v160, v214, v215
	v_cvt_pk_bf16_f32 v161, v216, v217
	v_cvt_pk_bf16_f32 v162, v218, v219
	v_cvt_pk_bf16_f32 v163, v220, v221
	v_mov_b32_e32 v188, v160
	v_mov_b32_e32 v189, v161
	v_mov_b32_e32 v190, v162
	v_mov_b32_e32 v191, v163
	v_mov_b32_dpp v160, v156 row_ror:8 row_mask:0xf bank_mask:0x3
	v_mov_b32_dpp v161, v157 row_ror:8 row_mask:0xf bank_mask:0x3
	v_mov_b32_dpp v162, v158 row_ror:8 row_mask:0xf bank_mask:0x3
	v_mov_b32_dpp v163, v159 row_ror:8 row_mask:0xf bank_mask:0x3
	v_mov_b32_dpp v156, v188 row_ror:8 row_mask:0xf bank_mask:0xc
	v_mov_b32_dpp v157, v189 row_ror:8 row_mask:0xf bank_mask:0xc
	v_mov_b32_dpp v158, v190 row_ror:8 row_mask:0xf bank_mask:0xc
	v_mov_b32_dpp v159, v191 row_ror:8 row_mask:0xf bank_mask:0xc
	global_store_dwordx4 v138, v[156:159], s[6:7] nt
	global_store_dwordx4 v139, v[160:163], s[6:7] nt
	s_branch .Lepi1_done
; __device__ __forceinline__ float sigm(float x) { return __builtin_amdgcn_rcpf(1.f + __expf(-x)); }
; __device__ __forceinline__ u32x4 pack8(const f32x4 v0, const f32x4 v1) { u32x4 w; w.x = cvt_pk_bf16(v0[0], v0[1]); w.y = cvt_pk_bf16(v0[2], v0[3]); w.z = cvt_pk_bf16(v1[0], v1[1]); w.w = cvt_pk_bf16(v1[2], v1[3]); return w; }
;     __device__ __forceinline__ void operator()(f32x4 (&acc)[2][2][4][2], const Unit& u, int wr, int wc, int fr, int fq) const {
;     ...
; #pragma unroll
;             for (int ai = 0; ai < 2; ++ai)
; #pragma unroll
;                 for (int m = 0; m < 4; ++m) { bf16_t* rowp = base + (size_t)(ai * HALF + m * 16) * LDZ;
; #pragma unroll
;                     for (int bj = 0; bj < 2; ++bj) { f32x4 v0 = acc[ai][bj][m][0], v1 = acc[ai][bj][m][1];
;                         if (kind == 1) {
; #pragma unroll
;                             for (int e = 0; e < 4; ++e) { v0[e] = v0[e] * sigm(v0[e]); v1[e] = v1[e] * sigm(v1[e]); } }
;                         else if (kind == 2) { v0 = v0 * (0.125f * LOG2E); v1 = v1 * (0.125f * LOG2E); }
;                         else if (kind == 3) {
; #pragma unroll
;                             for (int e = 0; e < 4; ++e) { v0[e] = sigm(v0[e] + bv[bj][0][e]); v1[e] = sigm(v1[e] + bv[bj][1][e]); } }
;                         __builtin_nontemporal_store(pack8(v0, v1), (u32x4*)(rowp + bj * HALF)); } }
.Lepi1_k3:
	s_mov_b64 s[6:7], s[50:51]
	v_pk_add_f32 v[172:173], v[126:127], v[222:223]
	v_pk_add_f32 v[174:175], v[128:129], v[224:225]
	v_pk_add_f32 v[176:177], v[122:123], v[226:227]
	v_pk_add_f32 v[178:179], v[124:125], v[228:229]
	v_pk_mul_f32 v[172:173], v[172:173], s[24:25] op_sel_hi:[1,0]
	v_pk_mul_f32 v[174:175], v[174:175], s[24:25] op_sel_hi:[1,0]
	v_pk_mul_f32 v[176:177], v[176:177], s[24:25] op_sel_hi:[1,0]
	v_pk_mul_f32 v[178:179], v[178:179], s[24:25] op_sel_hi:[1,0]
	v_exp_f32_e32 v172, v172
	v_exp_f32_e32 v173, v173
	v_exp_f32_e32 v174, v174
	v_exp_f32_e32 v175, v175
	v_exp_f32_e32 v176, v176
	v_exp_f32_e32 v177, v177
	v_exp_f32_e32 v178, v178
	v_exp_f32_e32 v179, v179
	v_pk_add_f32 v[172:173], v[172:173], 1.0 op_sel_hi:[1,0]
	v_pk_add_f32 v[174:175], v[174:175], 1.0 op_sel_hi:[1,0]
	v_pk_add_f32 v[176:177], v[176:177], 1.0 op_sel_hi:[1,0]
	v_pk_add_f32 v[178:179], v[178:179], 1.0 op_sel_hi:[1,0]
	v_rcp_f32_e32 v172, v172
	v_rcp_f32_e32 v173, v173
	v_rcp_f32_e32 v174, v174
	v_rcp_f32_e32 v175, v175
	v_rcp_f32_e32 v176, v176
	v_rcp_f32_e32 v177, v177
	v_rcp_f32_e32 v178, v178
	v_rcp_f32_e32 v179, v179
	v_pk_add_f32 v[180:181], v[62:63], v[238:239]
	v_pk_add_f32 v[182:183], v[64:65], v[240:241]
	v_pk_add_f32 v[184:185], v[58:59], v[242:243]
	v_pk_add_f32 v[186:187], v[60:61], v[244:245]
	v_pk_mul_f32 v[180:181], v[180:181], s[24:25] op_sel_hi:[1,0]
	v_pk_mul_f32 v[182:183], v[182:183], s[24:25] op_sel_hi:[1,0]
	v_pk_mul_f32 v[184:185], v[184:185], s[24:25] op_sel_hi:[1,0]
	v_pk_mul_f32 v[186:187], v[186:187], s[24:25] op_sel_hi:[1,0]
	v_exp_f32_e32 v180, v180
	v_exp_f32_e32 v181, v181
	v_exp_f32_e32 v182, v182
	v_exp_f32_e32 v183, v183
	v_exp_f32_e32 v184, v184
	v_exp_f32_e32 v185, v185
	v_exp_f32_e32 v186, v186
	v_exp_f32_e32 v187, v187
	v_pk_add_f32 v[180:181], v[180:181], 1.0 op_sel_hi:[1,0]
	v_pk_add_f32 v[182:183], v[182:183], 1.0 op_sel_hi:[1,0]
	v_pk_add_f32 v[184:185], v[184:185], 1.0 op_sel_hi:[1,0]
	v_pk_add_f32 v[186:187], v[186:187], 1.0 op_sel_hi:[1,0]
	v_rcp_f32_e32 v180, v180
	v_rcp_f32_e32 v181, v181
	v_rcp_f32_e32 v182, v182
	v_rcp_f32_e32 v183, v183
	v_rcp_f32_e32 v184, v184
	v_rcp_f32_e32 v185, v185
	v_rcp_f32_e32 v186, v186
	v_rcp_f32_e32 v187, v187
	v_cvt_pk_bf16_f32 v130, v172, v173
	v_cvt_pk_bf16_f32 v131, v174, v175
	v_cvt_pk_bf16_f32 v132, v176, v177
	v_cvt_pk_bf16_f32 v133, v178, v179
	v_cvt_pk_bf16_f32 v134, v180, v181
	v_cvt_pk_bf16_f32 v135, v182, v183
	v_cvt_pk_bf16_f32 v136, v184, v185
	v_cvt_pk_bf16_f32 v137, v186, v187
	v_mov_b32_e32 v140, v134
	v_mov_b32_e32 v141, v135
	v_mov_b32_e32 v142, v136
	v_mov_b32_e32 v143, v137
	v_mov_b32_dpp v134, v130 row_ror:8 row_mask:0xf bank_mask:0x3
	v_mov_b32_dpp v135, v131 row_ror:8 row_mask:0xf bank_mask:0x3
	v_mov_b32_dpp v136, v132 row_ror:8 row_mask:0xf bank_mask:0x3
	v_mov_b32_dpp v137, v133 row_ror:8 row_mask:0xf bank_mask:0x3
	v_mov_b32_dpp v130, v140 row_ror:8 row_mask:0xf bank_mask:0xc
	v_mov_b32_dpp v131, v141 row_ror:8 row_mask:0xf bank_mask:0xc
	v_mov_b32_dpp v132, v142 row_ror:8 row_mask:0xf bank_mask:0xc
	v_mov_b32_dpp v133, v143 row_ror:8 row_mask:0xf bank_mask:0xc
	global_store_dwordx4 v138, v[130:133], s[6:7] nt
	global_store_dwordx4 v139, v[134:137], s[6:7] nt
	s_add_u32 s6, s6, 0x8000
	s_addc_u32 s7, s7, 0
	v_pk_add_f32 v[206:207], v[118:119], v[222:223]
	v_pk_add_f32 v[208:209], v[120:121], v[224:225]
	v_pk_add_f32 v[210:211], v[114:115], v[226:227]
	v_pk_add_f32 v[212:213], v[116:117], v[228:229]
	v_pk_mul_f32 v[206:207], v[206:207], s[24:25] op_sel_hi:[1,0]
	v_pk_mul_f32 v[208:209], v[208:209], s[24:25] op_sel_hi:[1,0]
	v_pk_mul_f32 v[210:211], v[210:211], s[24:25] op_sel_hi:[1,0]
	v_pk_mul_f32 v[212:213], v[212:213], s[24:25] op_sel_hi:[1,0]
	v_exp_f32_e32 v206, v206
	v_exp_f32_e32 v207, v207
	v_exp_f32_e32 v208, v208
	v_exp_f32_e32 v209, v209
	v_exp_f32_e32 v210, v210
	v_exp_f32_e32 v211, v211
	v_exp_f32_e32 v212, v212
	v_exp_f32_e32 v213, v213
	v_pk_add_f32 v[206:207], v[206:207], 1.0 op_sel_hi:[1,0]
	v_pk_add_f32 v[208:209], v[208:209], 1.0 op_sel_hi:[1,0]
	v_pk_add_f32 v[210:211], v[210:211], 1.0 op_sel_hi:[1,0]
	v_pk_add_f32 v[212:213], v[212:213], 1.0 op_sel_hi:[1,0]
	v_rcp_f32_e32 v206, v206
	v_rcp_f32_e32 v207, v207
	v_rcp_f32_e32 v208, v208
	v_rcp_f32_e32 v209, v209
	v_rcp_f32_e32 v210, v210
	v_rcp_f32_e32 v211, v211
	v_rcp_f32_e32 v212, v212
	v_rcp_f32_e32 v213, v213
	v_pk_add_f32 v[214:215], v[54:55], v[238:239]
	v_pk_add_f32 v[216:217], v[56:57], v[240:241]
	v_pk_add_f32 v[218:219], v[50:51], v[242:243]
	v_pk_add_f32 v[220:221], v[52:53], v[244:245]
	v_pk_mul_f32 v[214:215], v[214:215], s[24:25] op_sel_hi:[1,0]
	v_pk_mul_f32 v[216:217], v[216:217], s[24:25] op_sel_hi:[1,0]
	v_pk_mul_f32 v[218:219], v[218:219], s[24:25] op_sel_hi:[1,0]
	v_pk_mul_f32 v[220:221], v[220:221], s[24:25] op_sel_hi:[1,0]
	v_exp_f32_e32 v214, v214
	v_exp_f32_e32 v215, v215
	v_exp_f32_e32 v216, v216
	v_exp_f32_e32 v217, v217
	v_exp_f32_e32 v218, v218
	v_exp_f32_e32 v219, v219
	v_exp_f32_e32 v220, v220
	v_exp_f32_e32 v221, v221
	v_pk_add_f32 v[214:215], v[214:215], 1.0 op_sel_hi:[1,0]
	v_pk_add_f32 v[216:217], v[216:217], 1.0 op_sel_hi:[1,0]
	v_pk_add_f32 v[218:219], v[218:219], 1.0 op_sel_hi:[1,0]
	v_pk_add_f32 v[220:221], v[220:221], 1.0 op_sel_hi:[1,0]
	v_rcp_f32_e32 v214, v214
	v_rcp_f32_e32 v215, v215
	v_rcp_f32_e32 v216, v216
	v_rcp_f32_e32 v217, v217
	v_rcp_f32_e32 v218, v218
	v_rcp_f32_e32 v219, v219
	v_rcp_f32_e32 v220, v220
	v_rcp_f32_e32 v221, v221
	v_cvt_pk_bf16_f32 v156, v206, v207
	v_cvt_pk_bf16_f32 v157, v208, v209
	v_cvt_pk_bf16_f32 v158, v210, v211
	v_cvt_pk_bf16_f32 v159, v212, v213
	v_cvt_pk_bf16_f32 v160, v214, v215
; __device__ __forceinline__ float sigm(float x) { return __builtin_amdgcn_rcpf(1.f + __expf(-x)); }
; __device__ __forceinline__ u32x4 pack8(const f32x4 v0, const f32x4 v1) { u32x4 w; w.x = cvt_pk_bf16(v0[0], v0[1]); w.y = cvt_pk_bf16(v0[2], v0[3]); w.z = cvt_pk_bf16(v1[0], v1[1]); w.w = cvt_pk_bf16(v1[2], v1[3]); return w; }
;     __device__ __forceinline__ void operator()(f32x4 (&acc)[2][2][4][2], const Unit& u, int wr, int wc, int fr, int fq) const {
;     ...
; #pragma unroll
;             for (int ai = 0; ai < 2; ++ai)
; #pragma unroll
;                 for (int m = 0; m < 4; ++m) { bf16_t* rowp = base + (size_t)(ai * HALF + m * 16) * LDZ;
; #pragma unroll
;                     for (int bj = 0; bj < 2; ++bj) { f32x4 v0 = acc[ai][bj][m][0], v1 = acc[ai][bj][m][1];
;                         if (kind == 1) {
; #pragma unroll
;                             for (int e = 0; e < 4; ++e) { v0[e] = v0[e] * sigm(v0[e]); v1[e] = v1[e] * sigm(v1[e]); } }
;                         else if (kind == 2) { v0 = v0 * (0.125f * LOG2E); v1 = v1 * (0.125f * LOG2E); }
;                         else if (kind == 3) {
; #pragma unroll
;                             for (int e = 0; e < 4; ++e) { v0[e] = sigm(v0[e] + bv[bj][0][e]); v1[e] = sigm(v1[e] + bv[bj][1][e]); } }
;                         __builtin_nontemporal_store(pack8(v0, v1), (u32x4*)(rowp + bj * HALF)); } }
	v_cvt_pk_bf16_f32 v161, v216, v217
	v_cvt_pk_bf16_f32 v162, v218, v219
	v_cvt_pk_bf16_f32 v163, v220, v221
	v_mov_b32_e32 v188, v160
	v_mov_b32_e32 v189, v161
	v_mov_b32_e32 v190, v162
	v_mov_b32_e32 v191, v163
	v_mov_b32_dpp v160, v156 row_ror:8 row_mask:0xf bank_mask:0x3
	v_mov_b32_dpp v161, v157 row_ror:8 row_mask:0xf bank_mask:0x3
	v_mov_b32_dpp v162, v158 row_ror:8 row_mask:0xf bank_mask:0x3
	v_mov_b32_dpp v163, v159 row_ror:8 row_mask:0xf bank_mask:0x3
	v_mov_b32_dpp v156, v188 row_ror:8 row_mask:0xf bank_mask:0xc
	v_mov_b32_dpp v157, v189 row_ror:8 row_mask:0xf bank_mask:0xc
	v_mov_b32_dpp v158, v190 row_ror:8 row_mask:0xf bank_mask:0xc
	v_mov_b32_dpp v159, v191 row_ror:8 row_mask:0xf bank_mask:0xc
	global_store_dwordx4 v138, v[156:159], s[6:7] nt
	global_store_dwordx4 v139, v[160:163], s[6:7] nt
	s_add_u32 s6, s6, 0x8000
	s_addc_u32 s7, s7, 0
	v_pk_add_f32 v[172:173], v[110:111], v[222:223]
	v_pk_add_f32 v[174:175], v[112:113], v[224:225]
	v_pk_add_f32 v[176:177], v[106:107], v[226:227]
	v_pk_add_f32 v[178:179], v[108:109], v[228:229]
	v_pk_mul_f32 v[172:173], v[172:173], s[24:25] op_sel_hi:[1,0]
	v_pk_mul_f32 v[174:175], v[174:175], s[24:25] op_sel_hi:[1,0]
	v_pk_mul_f32 v[176:177], v[176:177], s[24:25] op_sel_hi:[1,0]
	v_pk_mul_f32 v[178:179], v[178:179], s[24:25] op_sel_hi:[1,0]
	v_exp_f32_e32 v172, v172
	v_exp_f32_e32 v173, v173
	v_exp_f32_e32 v174, v174
	v_exp_f32_e32 v175, v175
	v_exp_f32_e32 v176, v176
	v_exp_f32_e32 v177, v177
	v_exp_f32_e32 v178, v178
	v_exp_f32_e32 v179, v179
	v_pk_add_f32 v[172:173], v[172:173], 1.0 op_sel_hi:[1,0]
	v_pk_add_f32 v[174:175], v[174:175], 1.0 op_sel_hi:[1,0]
	v_pk_add_f32 v[176:177], v[176:177], 1.0 op_sel_hi:[1,0]
	v_pk_add_f32 v[178:179], v[178:179], 1.0 op_sel_hi:[1,0]
	v_rcp_f32_e32 v172, v172
	v_rcp_f32_e32 v173, v173
	v_rcp_f32_e32 v174, v174
	v_rcp_f32_e32 v175, v175
	v_rcp_f32_e32 v176, v176
	v_rcp_f32_e32 v177, v177
	v_rcp_f32_e32 v178, v178
	v_rcp_f32_e32 v179, v179
	v_pk_add_f32 v[180:181], v[46:47], v[238:239]
	v_pk_add_f32 v[182:183], v[48:49], v[240:241]
	v_pk_add_f32 v[184:185], v[42:43], v[242:243]
	v_pk_add_f32 v[186:187], v[44:45], v[244:245]
	v_pk_mul_f32 v[180:181], v[180:181], s[24:25] op_sel_hi:[1,0]
	v_pk_mul_f32 v[182:183], v[182:183], s[24:25] op_sel_hi:[1,0]
	v_pk_mul_f32 v[184:185], v[184:185], s[24:25] op_sel_hi:[1,0]
	v_pk_mul_f32 v[186:187], v[186:187], s[24:25] op_sel_hi:[1,0]
	v_exp_f32_e32 v180, v180
	v_exp_f32_e32 v181, v181
	v_exp_f32_e32 v182, v182
	v_exp_f32_e32 v183, v183
	v_exp_f32_e32 v184, v184
	v_exp_f32_e32 v185, v185
	v_exp_f32_e32 v186, v186
	v_exp_f32_e32 v187, v187
	v_pk_add_f32 v[180:181], v[180:181], 1.0 op_sel_hi:[1,0]
	v_pk_add_f32 v[182:183], v[182:183], 1.0 op_sel_hi:[1,0]
	v_pk_add_f32 v[184:185], v[184:185], 1.0 op_sel_hi:[1,0]
	v_pk_add_f32 v[186:187], v[186:187], 1.0 op_sel_hi:[1,0]
	v_rcp_f32_e32 v180, v180
	v_rcp_f32_e32 v181, v181
	v_rcp_f32_e32 v182, v182
	v_rcp_f32_e32 v183, v183
	v_rcp_f32_e32 v184, v184
	v_rcp_f32_e32 v185, v185
	v_rcp_f32_e32 v186, v186
	v_rcp_f32_e32 v187, v187
	v_cvt_pk_bf16_f32 v130, v172, v173
	v_cvt_pk_bf16_f32 v131, v174, v175
	v_cvt_pk_bf16_f32 v132, v176, v177
	v_cvt_pk_bf16_f32 v133, v178, v179
	v_cvt_pk_bf16_f32 v134, v180, v181
	v_cvt_pk_bf16_f32 v135, v182, v183
	v_cvt_pk_bf16_f32 v136, v184, v185
	v_cvt_pk_bf16_f32 v137, v186, v187
	v_mov_b32_e32 v140, v134
	v_mov_b32_e32 v141, v135
	v_mov_b32_e32 v142, v136
	v_mov_b32_e32 v143, v137
	v_mov_b32_dpp v134, v130 row_ror:8 row_mask:0xf bank_mask:0x3
	v_mov_b32_dpp v135, v131 row_ror:8 row_mask:0xf bank_mask:0x3
	v_mov_b32_dpp v136, v132 row_ror:8 row_mask:0xf bank_mask:0x3
	v_mov_b32_dpp v137, v133 row_ror:8 row_mask:0xf bank_mask:0x3
	v_mov_b32_dpp v130, v140 row_ror:8 row_mask:0xf bank_mask:0xc
	v_mov_b32_dpp v131, v141 row_ror:8 row_mask:0xf bank_mask:0xc
	v_mov_b32_dpp v132, v142 row_ror:8 row_mask:0xf bank_mask:0xc
	v_mov_b32_dpp v133, v143 row_ror:8 row_mask:0xf bank_mask:0xc
	global_store_dwordx4 v138, v[130:133], s[6:7] nt
	global_store_dwordx4 v139, v[134:137], s[6:7] nt
	s_add_u32 s6, s6, 0x8000
	s_addc_u32 s7, s7, 0
	v_pk_add_f32 v[206:207], v[102:103], v[222:223]
	v_pk_add_f32 v[208:209], v[104:105], v[224:225]
	v_pk_add_f32 v[210:211], v[98:99], v[226:227]
	v_pk_add_f32 v[212:213], v[100:101], v[228:229]
	v_pk_mul_f32 v[206:207], v[206:207], s[24:25] op_sel_hi:[1,0]
	v_pk_mul_f32 v[208:209], v[208:209], s[24:25] op_sel_hi:[1,0]
	v_pk_mul_f32 v[210:211], v[210:211], s[24:25] op_sel_hi:[1,0]
	v_pk_mul_f32 v[212:213], v[212:213], s[24:25] op_sel_hi:[1,0]
	v_exp_f32_e32 v206, v206
	v_exp_f32_e32 v207, v207
	v_exp_f32_e32 v208, v208
	v_exp_f32_e32 v209, v209
	v_exp_f32_e32 v210, v210
	v_exp_f32_e32 v211, v211
	v_exp_f32_e32 v212, v212
	v_exp_f32_e32 v213, v213
	v_pk_add_f32 v[206:207], v[206:207], 1.0 op_sel_hi:[1,0]
	v_pk_add_f32 v[208:209], v[208:209], 1.0 op_sel_hi:[1,0]
	v_pk_add_f32 v[210:211], v[210:211], 1.0 op_sel_hi:[1,0]
	v_pk_add_f32 v[212:213], v[212:213], 1.0 op_sel_hi:[1,0]
	v_rcp_f32_e32 v206, v206
	v_rcp_f32_e32 v207, v207
	v_rcp_f32_e32 v208, v208
	v_rcp_f32_e32 v209, v209
	v_rcp_f32_e32 v210, v210
	v_rcp_f32_e32 v211, v211
	v_rcp_f32_e32 v212, v212
	v_rcp_f32_e32 v213, v213
	v_pk_add_f32 v[214:215], v[38:39], v[238:239]
	v_pk_add_f32 v[216:217], v[40:41], v[240:241]
	v_pk_add_f32 v[218:219], v[34:35], v[242:243]
	v_pk_add_f32 v[220:221], v[36:37], v[244:245]
	v_pk_mul_f32 v[214:215], v[214:215], s[24:25] op_sel_hi:[1,0]
	v_pk_mul_f32 v[216:217], v[216:217], s[24:25] op_sel_hi:[1,0]
	v_pk_mul_f32 v[218:219], v[218:219], s[24:25] op_sel_hi:[1,0]
	v_pk_mul_f32 v[220:221], v[220:221], s[24:25] op_sel_hi:[1,0]
	v_exp_f32_e32 v214, v214
; __device__ __forceinline__ float sigm(float x) { return __builtin_amdgcn_rcpf(1.f + __expf(-x)); }
; __device__ __forceinline__ u32x4 pack8(const f32x4 v0, const f32x4 v1) { u32x4 w; w.x = cvt_pk_bf16(v0[0], v0[1]); w.y = cvt_pk_bf16(v0[2], v0[3]); w.z = cvt_pk_bf16(v1[0], v1[1]); w.w = cvt_pk_bf16(v1[2], v1[3]); return w; }
;     __device__ __forceinline__ void operator()(f32x4 (&acc)[2][2][4][2], const Unit& u, int wr, int wc, int fr, int fq) const {
;     ...
; #pragma unroll
;             for (int ai = 0; ai < 2; ++ai)
; #pragma unroll
;                 for (int m = 0; m < 4; ++m) { bf16_t* rowp = base + (size_t)(ai * HALF + m * 16) * LDZ;
; #pragma unroll
;                     for (int bj = 0; bj < 2; ++bj) { f32x4 v0 = acc[ai][bj][m][0], v1 = acc[ai][bj][m][1];
;                         if (kind == 1) {
; #pragma unroll
;                             for (int e = 0; e < 4; ++e) { v0[e] = v0[e] * sigm(v0[e]); v1[e] = v1[e] * sigm(v1[e]); } }
;                         else if (kind == 2) { v0 = v0 * (0.125f * LOG2E); v1 = v1 * (0.125f * LOG2E); }
;                         else if (kind == 3) {
; #pragma unroll
;                             for (int e = 0; e < 4; ++e) { v0[e] = sigm(v0[e] + bv[bj][0][e]); v1[e] = sigm(v1[e] + bv[bj][1][e]); } }
;                         __builtin_nontemporal_store(pack8(v0, v1), (u32x4*)(rowp + bj * HALF)); } }
	v_exp_f32_e32 v215, v215
	v_exp_f32_e32 v216, v216
	v_exp_f32_e32 v217, v217
	v_exp_f32_e32 v218, v218
	v_exp_f32_e32 v219, v219
	v_exp_f32_e32 v220, v220
	v_exp_f32_e32 v221, v221
	v_pk_add_f32 v[214:215], v[214:215], 1.0 op_sel_hi:[1,0]
	v_pk_add_f32 v[216:217], v[216:217], 1.0 op_sel_hi:[1,0]
	v_pk_add_f32 v[218:219], v[218:219], 1.0 op_sel_hi:[1,0]
	v_pk_add_f32 v[220:221], v[220:221], 1.0 op_sel_hi:[1,0]
	v_rcp_f32_e32 v214, v214
	v_rcp_f32_e32 v215, v215
	v_rcp_f32_e32 v216, v216
	v_rcp_f32_e32 v217, v217
	v_rcp_f32_e32 v218, v218
	v_rcp_f32_e32 v219, v219
	v_rcp_f32_e32 v220, v220
	v_rcp_f32_e32 v221, v221
	v_cvt_pk_bf16_f32 v156, v206, v207
	v_cvt_pk_bf16_f32 v157, v208, v209
	v_cvt_pk_bf16_f32 v158, v210, v211
	v_cvt_pk_bf16_f32 v159, v212, v213
	v_cvt_pk_bf16_f32 v160, v214, v215
	v_cvt_pk_bf16_f32 v161, v216, v217
	v_cvt_pk_bf16_f32 v162, v218, v219
	v_cvt_pk_bf16_f32 v163, v220, v221
	v_mov_b32_e32 v188, v160
	v_mov_b32_e32 v189, v161
	v_mov_b32_e32 v190, v162
	v_mov_b32_e32 v191, v163
	v_mov_b32_dpp v160, v156 row_ror:8 row_mask:0xf bank_mask:0x3
	v_mov_b32_dpp v161, v157 row_ror:8 row_mask:0xf bank_mask:0x3
	v_mov_b32_dpp v162, v158 row_ror:8 row_mask:0xf bank_mask:0x3
	v_mov_b32_dpp v163, v159 row_ror:8 row_mask:0xf bank_mask:0x3
	v_mov_b32_dpp v156, v188 row_ror:8 row_mask:0xf bank_mask:0xc
	v_mov_b32_dpp v157, v189 row_ror:8 row_mask:0xf bank_mask:0xc
	v_mov_b32_dpp v158, v190 row_ror:8 row_mask:0xf bank_mask:0xc
	v_mov_b32_dpp v159, v191 row_ror:8 row_mask:0xf bank_mask:0xc
	global_store_dwordx4 v138, v[156:159], s[6:7] nt
	global_store_dwordx4 v139, v[160:163], s[6:7] nt
	s_add_u32 s6, s6, 0x28000
	s_addc_u32 s7, s7, 0
	v_pk_add_f32 v[172:173], v[94:95], v[222:223]
	v_pk_add_f32 v[174:175], v[96:97], v[224:225]
	v_pk_add_f32 v[176:177], v[90:91], v[226:227]
	v_pk_add_f32 v[178:179], v[92:93], v[228:229]
	v_pk_mul_f32 v[172:173], v[172:173], s[24:25] op_sel_hi:[1,0]
	v_pk_mul_f32 v[174:175], v[174:175], s[24:25] op_sel_hi:[1,0]
	v_pk_mul_f32 v[176:177], v[176:177], s[24:25] op_sel_hi:[1,0]
	v_pk_mul_f32 v[178:179], v[178:179], s[24:25] op_sel_hi:[1,0]
	v_exp_f32_e32 v172, v172
	v_exp_f32_e32 v173, v173
	v_exp_f32_e32 v174, v174
	v_exp_f32_e32 v175, v175
	v_exp_f32_e32 v176, v176
	v_exp_f32_e32 v177, v177
	v_exp_f32_e32 v178, v178
	v_exp_f32_e32 v179, v179
	v_pk_add_f32 v[172:173], v[172:173], 1.0 op_sel_hi:[1,0]
	v_pk_add_f32 v[174:175], v[174:175], 1.0 op_sel_hi:[1,0]
	v_pk_add_f32 v[176:177], v[176:177], 1.0 op_sel_hi:[1,0]
	v_pk_add_f32 v[178:179], v[178:179], 1.0 op_sel_hi:[1,0]
	v_rcp_f32_e32 v172, v172
	v_rcp_f32_e32 v173, v173
	v_rcp_f32_e32 v174, v174
	v_rcp_f32_e32 v175, v175
	v_rcp_f32_e32 v176, v176
	v_rcp_f32_e32 v177, v177
	v_rcp_f32_e32 v178, v178
	v_rcp_f32_e32 v179, v179
	v_pk_add_f32 v[180:181], v[30:31], v[238:239]
	v_pk_add_f32 v[182:183], v[32:33], v[240:241]
	v_pk_add_f32 v[184:185], v[26:27], v[242:243]
	v_pk_add_f32 v[186:187], v[28:29], v[244:245]
	v_pk_mul_f32 v[180:181], v[180:181], s[24:25] op_sel_hi:[1,0]
	v_pk_mul_f32 v[182:183], v[182:183], s[24:25] op_sel_hi:[1,0]
	v_pk_mul_f32 v[184:185], v[184:185], s[24:25] op_sel_hi:[1,0]
	v_pk_mul_f32 v[186:187], v[186:187], s[24:25] op_sel_hi:[1,0]
	v_exp_f32_e32 v180, v180
	v_exp_f32_e32 v181, v181
	v_exp_f32_e32 v182, v182
	v_exp_f32_e32 v183, v183
	v_exp_f32_e32 v184, v184
	v_exp_f32_e32 v185, v185
	v_exp_f32_e32 v186, v186
	v_exp_f32_e32 v187, v187
	v_pk_add_f32 v[180:181], v[180:181], 1.0 op_sel_hi:[1,0]
	v_pk_add_f32 v[182:183], v[182:183], 1.0 op_sel_hi:[1,0]
	v_pk_add_f32 v[184:185], v[184:185], 1.0 op_sel_hi:[1,0]
	v_pk_add_f32 v[186:187], v[186:187], 1.0 op_sel_hi:[1,0]
	v_rcp_f32_e32 v180, v180
	v_rcp_f32_e32 v181, v181
	v_rcp_f32_e32 v182, v182
	v_rcp_f32_e32 v183, v183
	v_rcp_f32_e32 v184, v184
	v_rcp_f32_e32 v185, v185
	v_rcp_f32_e32 v186, v186
	v_rcp_f32_e32 v187, v187
	v_cvt_pk_bf16_f32 v130, v172, v173
	v_cvt_pk_bf16_f32 v131, v174, v175
	v_cvt_pk_bf16_f32 v132, v176, v177
	v_cvt_pk_bf16_f32 v133, v178, v179
	v_cvt_pk_bf16_f32 v134, v180, v181
	v_cvt_pk_bf16_f32 v135, v182, v183
	v_cvt_pk_bf16_f32 v136, v184, v185
	v_cvt_pk_bf16_f32 v137, v186, v187
	v_mov_b32_e32 v140, v134
	v_mov_b32_e32 v141, v135
	v_mov_b32_e32 v142, v136
	v_mov_b32_e32 v143, v137
	v_mov_b32_dpp v134, v130 row_ror:8 row_mask:0xf bank_mask:0x3
	v_mov_b32_dpp v135, v131 row_ror:8 row_mask:0xf bank_mask:0x3
	v_mov_b32_dpp v136, v132 row_ror:8 row_mask:0xf bank_mask:0x3
	v_mov_b32_dpp v137, v133 row_ror:8 row_mask:0xf bank_mask:0x3
	v_mov_b32_dpp v130, v140 row_ror:8 row_mask:0xf bank_mask:0xc
	v_mov_b32_dpp v131, v141 row_ror:8 row_mask:0xf bank_mask:0xc
	v_mov_b32_dpp v132, v142 row_ror:8 row_mask:0xf bank_mask:0xc
	v_mov_b32_dpp v133, v143 row_ror:8 row_mask:0xf bank_mask:0xc
	global_store_dwordx4 v138, v[130:133], s[6:7] nt
	global_store_dwordx4 v139, v[134:137], s[6:7] nt
	s_add_u32 s6, s6, 0x8000
	s_addc_u32 s7, s7, 0
	v_pk_add_f32 v[206:207], v[86:87], v[222:223]
	v_pk_add_f32 v[208:209], v[88:89], v[224:225]
	v_pk_add_f32 v[210:211], v[82:83], v[226:227]
	v_pk_add_f32 v[212:213], v[84:85], v[228:229]
	v_pk_mul_f32 v[206:207], v[206:207], s[24:25] op_sel_hi:[1,0]
	v_pk_mul_f32 v[208:209], v[208:209], s[24:25] op_sel_hi:[1,0]
	v_pk_mul_f32 v[210:211], v[210:211], s[24:25] op_sel_hi:[1,0]
	v_pk_mul_f32 v[212:213], v[212:213], s[24:25] op_sel_hi:[1,0]
	v_exp_f32_e32 v206, v206
	v_exp_f32_e32 v207, v207
	v_exp_f32_e32 v208, v208
	v_exp_f32_e32 v209, v209
	v_exp_f32_e32 v210, v210
	v_exp_f32_e32 v211, v211
	v_exp_f32_e32 v212, v212
	v_exp_f32_e32 v213, v213
	v_pk_add_f32 v[206:207], v[206:207], 1.0 op_sel_hi:[1,0]
	v_pk_add_f32 v[208:209], v[208:209], 1.0 op_sel_hi:[1,0]
; __device__ __forceinline__ float sigm(float x) { return __builtin_amdgcn_rcpf(1.f + __expf(-x)); }
; __device__ __forceinline__ u32x4 pack8(const f32x4 v0, const f32x4 v1) { u32x4 w; w.x = cvt_pk_bf16(v0[0], v0[1]); w.y = cvt_pk_bf16(v0[2], v0[3]); w.z = cvt_pk_bf16(v1[0], v1[1]); w.w = cvt_pk_bf16(v1[2], v1[3]); return w; }
;     __device__ __forceinline__ void operator()(f32x4 (&acc)[2][2][4][2], const Unit& u, int wr, int wc, int fr, int fq) const {
;     ...
; #pragma unroll
;             for (int ai = 0; ai < 2; ++ai)
; #pragma unroll
;                 for (int m = 0; m < 4; ++m) { bf16_t* rowp = base + (size_t)(ai * HALF + m * 16) * LDZ;
; #pragma unroll
;                     for (int bj = 0; bj < 2; ++bj) { f32x4 v0 = acc[ai][bj][m][0], v1 = acc[ai][bj][m][1];
;                         if (kind == 1) {
; #pragma unroll
;                             for (int e = 0; e < 4; ++e) { v0[e] = v0[e] * sigm(v0[e]); v1[e] = v1[e] * sigm(v1[e]); } }
;                         else if (kind == 2) { v0 = v0 * (0.125f * LOG2E); v1 = v1 * (0.125f * LOG2E); }
;                         else if (kind == 3) {
; #pragma unroll
;                             for (int e = 0; e < 4; ++e) { v0[e] = sigm(v0[e] + bv[bj][0][e]); v1[e] = sigm(v1[e] + bv[bj][1][e]); } }
;                         __builtin_nontemporal_store(pack8(v0, v1), (u32x4*)(rowp + bj * HALF)); } }
	v_pk_add_f32 v[210:211], v[210:211], 1.0 op_sel_hi:[1,0]
	v_pk_add_f32 v[212:213], v[212:213], 1.0 op_sel_hi:[1,0]
	v_rcp_f32_e32 v206, v206
	v_rcp_f32_e32 v207, v207
	v_rcp_f32_e32 v208, v208
	v_rcp_f32_e32 v209, v209
	v_rcp_f32_e32 v210, v210
	v_rcp_f32_e32 v211, v211
	v_rcp_f32_e32 v212, v212
	v_rcp_f32_e32 v213, v213
	v_pk_add_f32 v[214:215], v[22:23], v[238:239]
	v_pk_add_f32 v[216:217], v[24:25], v[240:241]
	v_pk_add_f32 v[218:219], v[18:19], v[242:243]
	v_pk_add_f32 v[220:221], v[20:21], v[244:245]
	v_pk_mul_f32 v[214:215], v[214:215], s[24:25] op_sel_hi:[1,0]
	v_pk_mul_f32 v[216:217], v[216:217], s[24:25] op_sel_hi:[1,0]
	v_pk_mul_f32 v[218:219], v[218:219], s[24:25] op_sel_hi:[1,0]
	v_pk_mul_f32 v[220:221], v[220:221], s[24:25] op_sel_hi:[1,0]
	v_exp_f32_e32 v214, v214
	v_exp_f32_e32 v215, v215
	v_exp_f32_e32 v216, v216
	v_exp_f32_e32 v217, v217
	v_exp_f32_e32 v218, v218
	v_exp_f32_e32 v219, v219
	v_exp_f32_e32 v220, v220
	v_exp_f32_e32 v221, v221
	v_pk_add_f32 v[214:215], v[214:215], 1.0 op_sel_hi:[1,0]
	v_pk_add_f32 v[216:217], v[216:217], 1.0 op_sel_hi:[1,0]
	v_pk_add_f32 v[218:219], v[218:219], 1.0 op_sel_hi:[1,0]
	v_pk_add_f32 v[220:221], v[220:221], 1.0 op_sel_hi:[1,0]
	v_rcp_f32_e32 v214, v214
	v_rcp_f32_e32 v215, v215
	v_rcp_f32_e32 v216, v216
	v_rcp_f32_e32 v217, v217
	v_rcp_f32_e32 v218, v218
	v_rcp_f32_e32 v219, v219
	v_rcp_f32_e32 v220, v220
	v_rcp_f32_e32 v221, v221
	v_cvt_pk_bf16_f32 v156, v206, v207
	v_cvt_pk_bf16_f32 v157, v208, v209
	v_cvt_pk_bf16_f32 v158, v210, v211
	v_cvt_pk_bf16_f32 v159, v212, v213
	v_cvt_pk_bf16_f32 v160, v214, v215
	v_cvt_pk_bf16_f32 v161, v216, v217
	v_cvt_pk_bf16_f32 v162, v218, v219
	v_cvt_pk_bf16_f32 v163, v220, v221
	v_mov_b32_e32 v188, v160
	v_mov_b32_e32 v189, v161
	v_mov_b32_e32 v190, v162
	v_mov_b32_e32 v191, v163
	v_mov_b32_dpp v160, v156 row_ror:8 row_mask:0xf bank_mask:0x3
	v_mov_b32_dpp v161, v157 row_ror:8 row_mask:0xf bank_mask:0x3
	v_mov_b32_dpp v162, v158 row_ror:8 row_mask:0xf bank_mask:0x3
	v_mov_b32_dpp v163, v159 row_ror:8 row_mask:0xf bank_mask:0x3
	v_mov_b32_dpp v156, v188 row_ror:8 row_mask:0xf bank_mask:0xc
	v_mov_b32_dpp v157, v189 row_ror:8 row_mask:0xf bank_mask:0xc
	v_mov_b32_dpp v158, v190 row_ror:8 row_mask:0xf bank_mask:0xc
	v_mov_b32_dpp v159, v191 row_ror:8 row_mask:0xf bank_mask:0xc
	global_store_dwordx4 v138, v[156:159], s[6:7] nt
	global_store_dwordx4 v139, v[160:163], s[6:7] nt
	s_add_u32 s6, s6, 0x8000
	s_addc_u32 s7, s7, 0
	v_pk_add_f32 v[172:173], v[78:79], v[222:223]
	v_pk_add_f32 v[174:175], v[80:81], v[224:225]
	v_pk_add_f32 v[176:177], v[74:75], v[226:227]
	v_pk_add_f32 v[178:179], v[76:77], v[228:229]
	v_pk_mul_f32 v[172:173], v[172:173], s[24:25] op_sel_hi:[1,0]
	v_pk_mul_f32 v[174:175], v[174:175], s[24:25] op_sel_hi:[1,0]
	v_pk_mul_f32 v[176:177], v[176:177], s[24:25] op_sel_hi:[1,0]
	v_pk_mul_f32 v[178:179], v[178:179], s[24:25] op_sel_hi:[1,0]
	v_exp_f32_e32 v172, v172
	v_exp_f32_e32 v173, v173
	v_exp_f32_e32 v174, v174
	v_exp_f32_e32 v175, v175
	v_exp_f32_e32 v176, v176
	v_exp_f32_e32 v177, v177
	v_exp_f32_e32 v178, v178
	v_exp_f32_e32 v179, v179
	v_pk_add_f32 v[172:173], v[172:173], 1.0 op_sel_hi:[1,0]
	v_pk_add_f32 v[174:175], v[174:175], 1.0 op_sel_hi:[1,0]
	v_pk_add_f32 v[176:177], v[176:177], 1.0 op_sel_hi:[1,0]
	v_pk_add_f32 v[178:179], v[178:179], 1.0 op_sel_hi:[1,0]
	v_rcp_f32_e32 v172, v172
	v_rcp_f32_e32 v173, v173
	v_rcp_f32_e32 v174, v174
	v_rcp_f32_e32 v175, v175
	v_rcp_f32_e32 v176, v176
	v_rcp_f32_e32 v177, v177
	v_rcp_f32_e32 v178, v178
	v_rcp_f32_e32 v179, v179
	v_pk_add_f32 v[180:181], v[14:15], v[238:239]
	v_pk_add_f32 v[182:183], v[16:17], v[240:241]
	v_pk_add_f32 v[184:185], v[10:11], v[242:243]
	v_pk_add_f32 v[186:187], v[12:13], v[244:245]
	v_pk_mul_f32 v[180:181], v[180:181], s[24:25] op_sel_hi:[1,0]
	v_pk_mul_f32 v[182:183], v[182:183], s[24:25] op_sel_hi:[1,0]
	v_pk_mul_f32 v[184:185], v[184:185], s[24:25] op_sel_hi:[1,0]
	v_pk_mul_f32 v[186:187], v[186:187], s[24:25] op_sel_hi:[1,0]
	v_exp_f32_e32 v180, v180
	v_exp_f32_e32 v181, v181
	v_exp_f32_e32 v182, v182
	v_exp_f32_e32 v183, v183
	v_exp_f32_e32 v184, v184
	v_exp_f32_e32 v185, v185
	v_exp_f32_e32 v186, v186
	v_exp_f32_e32 v187, v187
	v_pk_add_f32 v[180:181], v[180:181], 1.0 op_sel_hi:[1,0]
	v_pk_add_f32 v[182:183], v[182:183], 1.0 op_sel_hi:[1,0]
	v_pk_add_f32 v[184:185], v[184:185], 1.0 op_sel_hi:[1,0]
	v_pk_add_f32 v[186:187], v[186:187], 1.0 op_sel_hi:[1,0]
	v_rcp_f32_e32 v180, v180
	v_rcp_f32_e32 v181, v181
	v_rcp_f32_e32 v182, v182
	v_rcp_f32_e32 v183, v183
	v_rcp_f32_e32 v184, v184
	v_rcp_f32_e32 v185, v185
	v_rcp_f32_e32 v186, v186
	v_rcp_f32_e32 v187, v187
	v_cvt_pk_bf16_f32 v130, v172, v173
	v_cvt_pk_bf16_f32 v131, v174, v175
	v_cvt_pk_bf16_f32 v132, v176, v177
	v_cvt_pk_bf16_f32 v133, v178, v179
	v_cvt_pk_bf16_f32 v134, v180, v181
	v_cvt_pk_bf16_f32 v135, v182, v183
	v_cvt_pk_bf16_f32 v136, v184, v185
	v_cvt_pk_bf16_f32 v137, v186, v187
	v_mov_b32_e32 v140, v134
	v_mov_b32_e32 v141, v135
	v_mov_b32_e32 v142, v136
	v_mov_b32_e32 v143, v137
	v_mov_b32_dpp v134, v130 row_ror:8 row_mask:0xf bank_mask:0x3
	v_mov_b32_dpp v135, v131 row_ror:8 row_mask:0xf bank_mask:0x3
	v_mov_b32_dpp v136, v132 row_ror:8 row_mask:0xf bank_mask:0x3
	v_mov_b32_dpp v137, v133 row_ror:8 row_mask:0xf bank_mask:0x3
	v_mov_b32_dpp v130, v140 row_ror:8 row_mask:0xf bank_mask:0xc
	v_mov_b32_dpp v131, v141 row_ror:8 row_mask:0xf bank_mask:0xc
	v_mov_b32_dpp v132, v142 row_ror:8 row_mask:0xf bank_mask:0xc
	v_mov_b32_dpp v133, v143 row_ror:8 row_mask:0xf bank_mask:0xc
	global_store_dwordx4 v138, v[130:133], s[6:7] nt
	global_store_dwordx4 v139, v[134:137], s[6:7] nt
; __device__ __forceinline__ float sigm(float x) { return __builtin_amdgcn_rcpf(1.f + __expf(-x)); }
; __device__ __forceinline__ u32x4 pack8(const f32x4 v0, const f32x4 v1) { u32x4 w; w.x = cvt_pk_bf16(v0[0], v0[1]); w.y = cvt_pk_bf16(v0[2], v0[3]); w.z = cvt_pk_bf16(v1[0], v1[1]); w.w = cvt_pk_bf16(v1[2], v1[3]); return w; }
;     __device__ __forceinline__ void operator()(f32x4 (&acc)[2][2][4][2], const Unit& u, int wr, int wc, int fr, int fq) const {
;     ...
; #pragma unroll
;             for (int ai = 0; ai < 2; ++ai)
; #pragma unroll
;                 for (int m = 0; m < 4; ++m) { bf16_t* rowp = base + (size_t)(ai * HALF + m * 16) * LDZ;
; #pragma unroll
;                     for (int bj = 0; bj < 2; ++bj) { f32x4 v0 = acc[ai][bj][m][0], v1 = acc[ai][bj][m][1];
;                         if (kind == 1) {
; #pragma unroll
;                             for (int e = 0; e < 4; ++e) { v0[e] = v0[e] * sigm(v0[e]); v1[e] = v1[e] * sigm(v1[e]); } }
;                         else if (kind == 2) { v0 = v0 * (0.125f * LOG2E); v1 = v1 * (0.125f * LOG2E); }
;                         else if (kind == 3) {
; #pragma unroll
;                             for (int e = 0; e < 4; ++e) { v0[e] = sigm(v0[e] + bv[bj][0][e]); v1[e] = sigm(v1[e] + bv[bj][1][e]); } }
;                         __builtin_nontemporal_store(pack8(v0, v1), (u32x4*)(rowp + bj * HALF)); } }
	s_add_u32 s6, s6, 0x8000
	s_addc_u32 s7, s7, 0
	v_pk_add_f32 v[206:207], v[70:71], v[222:223]
	v_pk_add_f32 v[208:209], v[72:73], v[224:225]
	v_pk_add_f32 v[210:211], v[66:67], v[226:227]
	v_pk_add_f32 v[212:213], v[68:69], v[228:229]
	v_pk_mul_f32 v[206:207], v[206:207], s[24:25] op_sel_hi:[1,0]
	v_pk_mul_f32 v[208:209], v[208:209], s[24:25] op_sel_hi:[1,0]
	v_pk_mul_f32 v[210:211], v[210:211], s[24:25] op_sel_hi:[1,0]
	v_pk_mul_f32 v[212:213], v[212:213], s[24:25] op_sel_hi:[1,0]
	v_exp_f32_e32 v206, v206
	v_exp_f32_e32 v207, v207
	v_exp_f32_e32 v208, v208
	v_exp_f32_e32 v209, v209
	v_exp_f32_e32 v210, v210
	v_exp_f32_e32 v211, v211
	v_exp_f32_e32 v212, v212
	v_exp_f32_e32 v213, v213
	v_pk_add_f32 v[206:207], v[206:207], 1.0 op_sel_hi:[1,0]
	v_pk_add_f32 v[208:209], v[208:209], 1.0 op_sel_hi:[1,0]
	v_pk_add_f32 v[210:211], v[210:211], 1.0 op_sel_hi:[1,0]
	v_pk_add_f32 v[212:213], v[212:213], 1.0 op_sel_hi:[1,0]
	v_rcp_f32_e32 v206, v206
	v_rcp_f32_e32 v207, v207
	v_rcp_f32_e32 v208, v208
	v_rcp_f32_e32 v209, v209
	v_rcp_f32_e32 v210, v210
	v_rcp_f32_e32 v211, v211
	v_rcp_f32_e32 v212, v212
	v_rcp_f32_e32 v213, v213
	v_pk_add_f32 v[214:215], v[6:7], v[238:239]
	v_pk_add_f32 v[216:217], v[8:9], v[240:241]
	v_pk_add_f32 v[218:219], v[2:3], v[242:243]
	v_pk_add_f32 v[220:221], v[4:5], v[244:245]
	v_pk_mul_f32 v[214:215], v[214:215], s[24:25] op_sel_hi:[1,0]
	v_pk_mul_f32 v[216:217], v[216:217], s[24:25] op_sel_hi:[1,0]
	v_pk_mul_f32 v[218:219], v[218:219], s[24:25] op_sel_hi:[1,0]
	v_pk_mul_f32 v[220:221], v[220:221], s[24:25] op_sel_hi:[1,0]
	v_exp_f32_e32 v214, v214
	v_exp_f32_e32 v215, v215
	v_exp_f32_e32 v216, v216
	v_exp_f32_e32 v217, v217
	v_exp_f32_e32 v218, v218
	v_exp_f32_e32 v219, v219
	v_exp_f32_e32 v220, v220
	v_exp_f32_e32 v221, v221
	v_pk_add_f32 v[214:215], v[214:215], 1.0 op_sel_hi:[1,0]
	v_pk_add_f32 v[216:217], v[216:217], 1.0 op_sel_hi:[1,0]
	v_pk_add_f32 v[218:219], v[218:219], 1.0 op_sel_hi:[1,0]
	v_pk_add_f32 v[220:221], v[220:221], 1.0 op_sel_hi:[1,0]
	v_rcp_f32_e32 v214, v214
	v_rcp_f32_e32 v215, v215
	v_rcp_f32_e32 v216, v216
	v_rcp_f32_e32 v217, v217
	v_rcp_f32_e32 v218, v218
	v_rcp_f32_e32 v219, v219
	v_rcp_f32_e32 v220, v220
	v_rcp_f32_e32 v221, v221
	v_cvt_pk_bf16_f32 v156, v206, v207
	v_cvt_pk_bf16_f32 v157, v208, v209
	v_cvt_pk_bf16_f32 v158, v210, v211
	v_cvt_pk_bf16_f32 v159, v212, v213
	v_cvt_pk_bf16_f32 v160, v214, v215
	v_cvt_pk_bf16_f32 v161, v216, v217
	v_cvt_pk_bf16_f32 v162, v218, v219
	v_cvt_pk_bf16_f32 v163, v220, v221
	v_mov_b32_e32 v188, v160
	v_mov_b32_e32 v189, v161
	v_mov_b32_e32 v190, v162
	v_mov_b32_e32 v191, v163
	v_mov_b32_dpp v160, v156 row_ror:8 row_mask:0xf bank_mask:0x3
	v_mov_b32_dpp v161, v157 row_ror:8 row_mask:0xf bank_mask:0x3
	v_mov_b32_dpp v162, v158 row_ror:8 row_mask:0xf bank_mask:0x3
	v_mov_b32_dpp v163, v159 row_ror:8 row_mask:0xf bank_mask:0x3
	v_mov_b32_dpp v156, v188 row_ror:8 row_mask:0xf bank_mask:0xc
	v_mov_b32_dpp v157, v189 row_ror:8 row_mask:0xf bank_mask:0xc
	v_mov_b32_dpp v158, v190 row_ror:8 row_mask:0xf bank_mask:0xc
	v_mov_b32_dpp v159, v191 row_ror:8 row_mask:0xf bank_mask:0xc
	global_store_dwordx4 v138, v[156:159], s[6:7] nt
	global_store_dwordx4 v139, v[160:163], s[6:7] nt
	s_branch .Lepi1_done
; __device__ __forceinline__ float shx(float v, int lane, int m) { return __builtin_bit_cast(float, __builtin_amdgcn_ds_bpermute((lane ^ m) << 2, __builtin_bit_cast(int, v))); }
;     __device__ __forceinline__ void operator()(f32x4 (&acc)[2][2][4][2], const Unit& u, int wr, int wc, int fr, int fq) const {
;     ...
;             if (pn >= 8 && pn < 16) {
;                 const float sc2 = (pn < 12) ? (0.125f * LOG2E) * (0.125f * LOG2E) : 1.f;
;                 const int tokb = tok0 + u.pm * BM, bg = tokb >> 13, qb = (tokb & (T - 1)) >> 8;
; #pragma unroll
;                 for (int bj = 0; bj < 2; ++bj) { float mx = 0.f;
; #pragma unroll
;                     for (int ai = 0; ai < 2; ++ai)
; #pragma unroll
;                         for (int m = 0; m < 4; ++m) { const f32x4 v0 = acc[ai][bj][m][0], v1 = acc[ai][bj][m][1];
;                             float q = (v0[0] * v0[0] + v0[1] * v0[1]) + (v0[2] * v0[2] + v0[3] * v0[3]) + (v1[0] * v1[0] + v1[1] * v1[1]) + (v1[2] * v1[2] + v1[3] * v1[3]);
;                             q += shx(q, lane_, 16); q += shx(q, lane_, 32); mx = fmaxf(mx, q); }
;                     mx = fmaxf(mx, shx(mx, lane_, 1)); mx = fmaxf(mx, shx(mx, lane_, 2)); mx = fmaxf(mx, shx(mx, lane_, 4)); mx = fmaxf(mx, shx(mx, lane_, 8));
;                     if (lane_ == 0) { const int head = (pn & 3) * 4 + 2 * bj + (wc >> 1), half = wc & 1;
;                         unsigned* w = (pn < 12) ? NRM + 1024 + ((bg * 16 + head) * 32 + qb) * 2 + half : NRM + (bg * 16 + head) * 2 + half;
;                         __hip_atomic_fetch_max(w, __builtin_bit_cast(unsigned, mx * sc2 * 1.02f), __ATOMIC_RELAXED, __HIP_MEMORY_SCOPE_AGENT); } }
.Lepi1_done:
	s_and_b32 s2, s56, -8
	s_cmp_lg_u32 s2, 8
	s_cbranch_scc1 .LBB0_346
	v_mul_f32_e32 v127, v127, v127
	v_mul_f32_e32 v119, v119, v119
	v_fmac_f32_e32 v127, v126, v126
	v_mul_f32_e32 v126, v129, v129
	v_fmac_f32_e32 v119, v118, v118
	v_mul_f32_e32 v118, v121, v121
	v_mul_f32_e32 v111, v111, v111
	v_mul_f32_e32 v103, v103, v103
	v_fmac_f32_e32 v126, v128, v128
	v_mul_f32_e32 v123, v123, v123
	v_fmac_f32_e32 v118, v120, v120
	v_mul_f32_e32 v115, v115, v115
	v_fmac_f32_e32 v111, v110, v110
	v_mul_f32_e32 v110, v113, v113
	v_fmac_f32_e32 v103, v102, v102
	v_mul_f32_e32 v102, v105, v105
	v_mul_f32_e32 v95, v95, v95
	v_mul_f32_e32 v87, v87, v87
	v_add_f32_e32 v126, v127, v126
	v_fmac_f32_e32 v123, v122, v122
	v_add_f32_e32 v118, v119, v118
	v_fmac_f32_e32 v115, v114, v114
	v_fmac_f32_e32 v110, v112, v112
	v_mul_f32_e32 v107, v107, v107
	v_fmac_f32_e32 v102, v104, v104
	v_mul_f32_e32 v99, v99, v99
	v_fmac_f32_e32 v95, v94, v94
	v_mul_f32_e32 v94, v97, v97
	v_fmac_f32_e32 v87, v86, v86
	v_mul_f32_e32 v86, v89, v89
	v_mul_f32_e32 v79, v79, v79
	v_mul_f32_e32 v71, v71, v71
	v_lshl_add_u32 v131, v171, 4, v170
	v_add_f32_e32 v122, v126, v123
	v_mul_f32_e32 v123, v125, v125
	v_add_f32_e32 v114, v118, v115
	v_mul_f32_e32 v115, v117, v117
	v_add_f32_e32 v110, v111, v110
	v_fmac_f32_e32 v107, v106, v106
	v_add_f32_e32 v102, v103, v102
	v_fmac_f32_e32 v99, v98, v98
	v_fmac_f32_e32 v94, v96, v96
	v_mul_f32_e32 v91, v91, v91
	v_fmac_f32_e32 v86, v88, v88
	v_mul_f32_e32 v83, v83, v83
	v_fmac_f32_e32 v79, v78, v78
	v_mul_f32_e32 v78, v81, v81
	v_fmac_f32_e32 v71, v70, v70
	v_mul_f32_e32 v70, v73, v73
	v_lshlrev_b32_e32 v132, 2, v131
	v_fmac_f32_e32 v123, v124, v124
	v_fmac_f32_e32 v115, v116, v116
	v_add_f32_e32 v106, v110, v107
	v_mul_f32_e32 v107, v109, v109
	v_add_f32_e32 v98, v102, v99
	v_mul_f32_e32 v99, v101, v101
	v_add_f32_e32 v94, v95, v94
	v_fmac_f32_e32 v91, v90, v90
	v_add_f32_e32 v86, v87, v86
	v_fmac_f32_e32 v83, v82, v82
	v_fmac_f32_e32 v78, v80, v80
	v_mul_f32_e32 v75, v75, v75
	v_fmac_f32_e32 v70, v72, v72
	v_mul_f32_e32 v67, v67, v67
	v_xor_b32_e32 v130, 64, v132
	v_add_f32_e32 v122, v123, v122
	v_add_f32_e32 v116, v115, v114
	v_fmac_f32_e32 v107, v108, v108
	v_fmac_f32_e32 v99, v100, v100
	v_add_f32_e32 v90, v94, v91
	v_mul_f32_e32 v91, v93, v93
	v_add_f32_e32 v82, v86, v83
	v_mul_f32_e32 v83, v85, v85
	v_add_f32_e32 v78, v79, v78
	v_fmac_f32_e32 v75, v74, v74
	v_add_f32_e32 v70, v71, v70
	v_fmac_f32_e32 v67, v66, v66
	ds_bpermute_b32 v123, v130, v122
	ds_bpermute_b32 v117, v130, v116
	v_add_f32_e32 v106, v107, v106
	v_add_f32_e32 v98, v99, v98
	v_fmac_f32_e32 v91, v92, v92
	v_fmac_f32_e32 v83, v84, v84
	v_add_f32_e32 v74, v78, v75
	v_mul_f32_e32 v75, v77, v77
	v_add_f32_e32 v66, v70, v67
	v_mul_f32_e32 v67, v69, v69
	ds_bpermute_b32 v107, v130, v106
	ds_bpermute_b32 v99, v130, v98
	v_add_f32_e32 v90, v91, v90
	v_add_f32_e32 v82, v83, v82
	v_fmac_f32_e32 v75, v76, v76
	v_fmac_f32_e32 v67, v68, v68
	ds_bpermute_b32 v91, v130, v90
	ds_bpermute_b32 v83, v130, v82
	v_add_f32_e32 v74, v75, v74
	v_add_f32_e32 v66, v67, v66
	ds_bpermute_b32 v75, v130, v74
	ds_bpermute_b32 v67, v130, v66
	v_xor_b32_e32 v115, 0x80, v132
	s_waitcnt lgkmcnt(7)
	v_add_f32_e32 v118, v122, v123
	s_waitcnt lgkmcnt(6)
	v_add_f32_e32 v116, v116, v117
	ds_bpermute_b32 v119, v115, v118
	ds_bpermute_b32 v117, v115, v116
	s_waitcnt lgkmcnt(7)
	v_add_f32_e32 v102, v106, v107
	s_waitcnt lgkmcnt(6)
	v_add_f32_e32 v98, v98, v99
	ds_bpermute_b32 v103, v115, v102
	ds_bpermute_b32 v99, v115, v98
	s_waitcnt lgkmcnt(7)
	v_add_f32_e32 v90, v90, v91
	s_waitcnt lgkmcnt(6)
	v_add_f32_e32 v68, v82, v83
	ds_bpermute_b32 v91, v115, v90
	ds_bpermute_b32 v69, v115, v68
	s_waitcnt lgkmcnt(7)
	v_add_f32_e32 v70, v74, v75
	s_waitcnt lgkmcnt(6)
	v_add_f32_e32 v66, v66, v67
	ds_bpermute_b32 v71, v115, v70
	ds_bpermute_b32 v67, v115, v66
	s_waitcnt lgkmcnt(7)
	v_add_f32_e32 v100, v118, v119
	s_waitcnt lgkmcnt(6)
	v_add_f32_e32 v101, v116, v117
	v_max3_f32 v92, v100, 0, v101
	s_waitcnt lgkmcnt(5)
	v_add_f32_e32 v93, v102, v103
	s_waitcnt lgkmcnt(4)
	v_add_f32_e32 v94, v98, v99
	v_max3_f32 v92, v92, v93, v94
	s_waitcnt lgkmcnt(3)
	v_add_f32_e32 v72, v90, v91
	s_waitcnt lgkmcnt(2)
	v_add_f32_e32 v68, v68, v69
	v_max3_f32 v68, v92, v72, v68
	s_waitcnt lgkmcnt(1)
	v_add_f32_e32 v69, v70, v71
	s_waitcnt lgkmcnt(0)
	v_add_f32_e32 v66, v66, v67
	v_xor_b32_e32 v114, 4, v132
	v_max3_f32 v66, v68, v69, v66
	ds_bpermute_b32 v68, v114, v66
	v_xor_b32_e32 v67, 8, v132
	s_cmp_gt_u32 s56, 11
	s_cselect_b64 s[50:51], -1, 0
	s_cmp_lt_u32 s56, 12
	s_waitcnt lgkmcnt(0)
	v_max_f32_e32 v68, v68, v68
	v_max_f32_e32 v69, v66, v68
	ds_bpermute_b32 v70, v67, v69
	v_xor_b32_e32 v68, 16, v132
	s_cselect_b64 vcc, -1, 0
	s_lshl_b32 s2, s48, 8
	s_add_i32 s6, s2, s76
	s_waitcnt lgkmcnt(0)
	v_max_f32_e32 v70, v70, v70
	v_max_f32_e32 v70, v69, v70
	ds_bpermute_b32 v71, v68, v70
	v_xor_b32_e32 v69, 32, v132
	s_lshl_b32 s39, s56, 2
	s_ashr_i32 s18, s6, 13
	s_and_b32 s39, s39, 12
	s_waitcnt lgkmcnt(0)
	v_max_f32_e32 v71, v71, v71
	v_max_f32_e32 v70, v70, v71
	ds_bpermute_b32 v71, v69, v70
	v_cndmask_b32_e32 v66, 1.0, v254, vcc
	v_cmp_eq_u32_e64 s[6:7], 0, v131
	s_lshl_b32 s41, s68, 1
	s_or_b32 s41, s41, s69
	s_or_b32 s41, s41, s39
	s_lshl_b32 s39, s18, 5
	s_and_saveexec_b64 s[48:49], s[6:7]
	s_cbranch_execz .LBB0_336
	s_mov_b64 s[54:55], -1
	s_and_b64 vcc, exec, s[50:51]
	s_cbranch_vccz .LBB0_330
	s_lshl_b32 s52, s41, 1
	s_or_b32 s52, s39, s52
	s_mov_b64 s[54:55], 0

; __device__ __forceinline__ float shx(float v, int lane, int m) { return __builtin_bit_cast(float, __builtin_amdgcn_ds_bpermute((lane ^ m) << 2, __builtin_bit_cast(int, v))); }
;     __device__ __forceinline__ void operator()(f32x4 (&acc)[2][2][4][2], const Unit& u, int wr, int wc, int fr, int fq) const {
;     ...
;                 for (int bj = 0; bj < 2; ++bj) { float mx = 0.f;
; #pragma unroll
;                     for (int ai = 0; ai < 2; ++ai)
; #pragma unroll
;                         for (int m = 0; m < 4; ++m) { const f32x4 v0 = acc[ai][bj][m][0], v1 = acc[ai][bj][m][1];
;                             float q = (v0[0] * v0[0] + v0[1] * v0[1]) + (v0[2] * v0[2] + v0[3] * v0[3]) + (v1[0] * v1[0] + v1[1] * v1[1]) + (v1[2] * v1[2] + v1[3] * v1[3]);
;                             q += shx(q, lane_, 16); q += shx(q, lane_, 32); mx = fmaxf(mx, q); }
;                     mx = fmaxf(mx, shx(mx, lane_, 1)); mx = fmaxf(mx, shx(mx, lane_, 2)); mx = fmaxf(mx, shx(mx, lane_, 4)); mx = fmaxf(mx, shx(mx, lane_, 8));
;                     if (lane_ == 0) { const int head = (pn & 3) * 4 + 2 * bj + (wc >> 1), half = wc & 1;
;                         unsigned* w = (pn < 12) ? NRM + 1024 + ((bg * 16 + head) * 32 + qb) * 2 + half : NRM + (bg * 16 + head) * 2 + half;
;                         __hip_atomic_fetch_max(w, __builtin_bit_cast(unsigned, mx * sc2 * 1.02f), __ATOMIC_RELAXED, __HIP_MEMORY_SCOPE_AGENT); } }
.LBB0_333:
	s_ff1_i32_b64 s53, s[56:57]
	v_readlane_b32 s75, v70, s53
	s_lshl_b64 s[84:85], 1, s53
	s_max_u32 s74, s74, s75
	s_andn2_b64 s[56:57], s[56:57], s[84:85]
	s_cmp_lg_u64 s[56:57], 0
	s_cbranch_scc1 .LBB0_333
	v_mbcnt_lo_u32_b32 v70, exec_lo, 0
	v_mbcnt_hi_u32_b32 v70, exec_hi, v70
	v_cmp_eq_u32_e32 vcc, 0, v70
	s_and_saveexec_b64 s[56:57], vcc
	s_xor_b64 s[56:57], exec, s[56:57]
	s_cbranch_execz .LBB0_336
	s_add_u32 s54, s36, s54
	s_addc_u32 s55, s37, s55
	s_ashr_i32 s53, s52, 31
	s_lshl_b64 s[52:53], s[52:53], 2
	s_add_u32 s52, s54, s52
	s_addc_u32 s53, s55, s53
	s_mov_b32 s54, 0
	v_mov_b32_e32 v70, s54
	v_mov_b32_e32 v71, s74
	global_atomic_umax v70, v71, s[52:53]
.LBB0_336:
	s_or_b64 exec, exec, s[48:49]
	v_mul_f32_e32 v63, v63, v63
	v_mul_f32_e32 v55, v55, v55
	v_fmac_f32_e32 v63, v62, v62
	v_mul_f32_e32 v62, v65, v65
	v_fmac_f32_e32 v55, v54, v54
	v_mul_f32_e32 v54, v57, v57
	v_mul_f32_e32 v47, v47, v47
	v_mul_f32_e32 v39, v39, v39
	v_fmac_f32_e32 v62, v64, v64
	v_mul_f32_e32 v59, v59, v59
	v_fmac_f32_e32 v54, v56, v56
	v_mul_f32_e32 v51, v51, v51
	v_fmac_f32_e32 v47, v46, v46
	v_mul_f32_e32 v46, v49, v49
	v_fmac_f32_e32 v39, v38, v38
	v_mul_f32_e32 v38, v41, v41
	v_mul_f32_e32 v31, v31, v31
	v_mul_f32_e32 v23, v23, v23
	v_add_f32_e32 v62, v63, v62
	v_fmac_f32_e32 v59, v58, v58
	v_add_f32_e32 v54, v55, v54
	v_fmac_f32_e32 v51, v50, v50
	v_fmac_f32_e32 v46, v48, v48
	v_mul_f32_e32 v43, v43, v43
	v_fmac_f32_e32 v38, v40, v40
	v_mul_f32_e32 v35, v35, v35
	v_fmac_f32_e32 v31, v30, v30
	v_mul_f32_e32 v30, v33, v33
	v_fmac_f32_e32 v23, v22, v22
	v_mul_f32_e32 v22, v25, v25
	v_mul_f32_e32 v15, v15, v15
	v_mul_f32_e32 v7, v7, v7
	v_add_f32_e32 v58, v62, v59
	v_mul_f32_e32 v59, v61, v61
	v_add_f32_e32 v50, v54, v51
	v_mul_f32_e32 v51, v53, v53
	v_add_f32_e32 v46, v47, v46
	v_fmac_f32_e32 v43, v42, v42
	v_add_f32_e32 v38, v39, v38
	v_fmac_f32_e32 v35, v34, v34
	v_fmac_f32_e32 v30, v32, v32
	v_mul_f32_e32 v27, v27, v27
	v_fmac_f32_e32 v22, v24, v24
	v_mul_f32_e32 v19, v19, v19
	v_fmac_f32_e32 v15, v14, v14
	v_mul_f32_e32 v14, v17, v17
	v_fmac_f32_e32 v7, v6, v6
	v_mul_f32_e32 v6, v9, v9
	v_fmac_f32_e32 v59, v60, v60
	v_fmac_f32_e32 v51, v52, v52
	v_add_f32_e32 v42, v46, v43
	v_mul_f32_e32 v43, v45, v45
	v_add_f32_e32 v34, v38, v35
	v_mul_f32_e32 v35, v37, v37
	v_add_f32_e32 v30, v31, v30
	v_fmac_f32_e32 v27, v26, v26
	v_add_f32_e32 v22, v23, v22
	v_fmac_f32_e32 v19, v18, v18
	v_fmac_f32_e32 v14, v16, v16
	v_mul_f32_e32 v11, v11, v11
	v_fmac_f32_e32 v6, v8, v8
	v_mul_f32_e32 v3, v3, v3
	v_add_f32_e32 v58, v59, v58
	v_add_f32_e32 v50, v51, v50
	v_fmac_f32_e32 v43, v44, v44
	v_fmac_f32_e32 v35, v36, v36
	v_add_f32_e32 v26, v30, v27
	v_mul_f32_e32 v27, v29, v29
	v_add_f32_e32 v18, v22, v19
	v_mul_f32_e32 v19, v21, v21
	v_add_f32_e32 v14, v15, v14
	v_fmac_f32_e32 v11, v10, v10
	v_add_f32_e32 v6, v7, v6
	v_fmac_f32_e32 v3, v2, v2
	ds_bpermute_b32 v59, v130, v58
	ds_bpermute_b32 v51, v130, v50
	v_add_f32_e32 v42, v43, v42
	v_add_f32_e32 v34, v35, v34
	v_fmac_f32_e32 v27, v28, v28
	v_fmac_f32_e32 v19, v20, v20
	v_add_f32_e32 v10, v14, v11
	v_mul_f32_e32 v11, v13, v13
	v_add_f32_e32 v2, v6, v3
	v_mul_f32_e32 v3, v5, v5
	ds_bpermute_b32 v43, v130, v42
	ds_bpermute_b32 v35, v130, v34
	v_add_f32_e32 v26, v27, v26
	v_add_f32_e32 v18, v19, v18
	v_fmac_f32_e32 v11, v12, v12
	v_fmac_f32_e32 v3, v4, v4
	ds_bpermute_b32 v27, v130, v26
	ds_bpermute_b32 v19, v130, v18
	v_add_f32_e32 v10, v11, v10
	v_add_f32_e32 v2, v3, v2
	ds_bpermute_b32 v11, v130, v10
	ds_bpermute_b32 v3, v130, v2
	s_waitcnt lgkmcnt(7)
	v_add_f32_e32 v52, v58, v59
	s_waitcnt lgkmcnt(6)
	v_add_f32_e32 v50, v50, v51
	ds_bpermute_b32 v53, v115, v52
	ds_bpermute_b32 v51, v115, v50
	s_waitcnt lgkmcnt(7)
	v_add_f32_e32 v38, v42, v43
	s_waitcnt lgkmcnt(6)
	v_add_f32_e32 v34, v34, v35
	ds_bpermute_b32 v39, v115, v38
	ds_bpermute_b32 v35, v115, v34
	s_waitcnt lgkmcnt(7)
	v_add_f32_e32 v26, v26, v27
	s_waitcnt lgkmcnt(6)
	v_add_f32_e32 v4, v18, v19
	ds_bpermute_b32 v27, v115, v26
	ds_bpermute_b32 v5, v115, v4
	s_waitcnt lgkmcnt(7)
	v_add_f32_e32 v6, v10, v11
	s_waitcnt lgkmcnt(6)
	v_add_f32_e32 v2, v2, v3
	ds_bpermute_b32 v7, v115, v6
	ds_bpermute_b32 v3, v115, v2
	s_waitcnt lgkmcnt(7)
	v_add_f32_e32 v36, v52, v53
	s_waitcnt lgkmcnt(6)
	v_add_f32_e32 v37, v50, v51
	v_max3_f32 v28, v36, 0, v37
	s_waitcnt lgkmcnt(5)
	v_add_f32_e32 v29, v38, v39
	s_waitcnt lgkmcnt(4)
	v_add_f32_e32 v30, v34, v35
	v_max3_f32 v28, v28, v29, v30
	s_waitcnt lgkmcnt(3)
	v_add_f32_e32 v8, v26, v27
	s_waitcnt lgkmcnt(2)
	v_add_f32_e32 v4, v4, v5
	v_max3_f32 v4, v28, v8, v4
	s_waitcnt lgkmcnt(1)
	v_add_f32_e32 v5, v6, v7
	s_waitcnt lgkmcnt(0)
	v_add_f32_e32 v2, v2, v3
	v_max3_f32 v2, v4, v5, v2
	ds_bpermute_b32 v3, v114, v2
	s_waitcnt lgkmcnt(0)
	v_max_f32_e32 v3, v3, v3
	v_max_f32_e32 v2, v2, v3
	ds_bpermute_b32 v3, v67, v2
	s_waitcnt lgkmcnt(0)
	v_max_f32_e32 v3, v3, v3
	v_max_f32_e32 v2, v2, v3
	ds_bpermute_b32 v3, v68, v2
	s_waitcnt lgkmcnt(0)
	v_max_f32_e32 v3, v3, v3
	v_max_f32_e32 v2, v2, v3
	ds_bpermute_b32 v3, v69, v2
	s_and_saveexec_b64 s[48:49], s[6:7]
	s_cbranch_execz .LBB0_345
	s_mov_b32 s7, s41
	s_andn2_b64 vcc, exec, s[50:51]
	s_mov_b64 s[50:51], -1
	s_cbranch_vccnz .LBB0_339
	s_lshl_b32 s6, s7, 1
	s_or_b32 s6, s39, s6
	s_mov_b64 s[50:51], 0

;     __device__ __forceinline__ void operator()(f32x4 (&acc)[2][2][4][2], const Unit& u, int wr, int wc, int fr, int fq) const {
;     ...
;                     if (lane_ == 0) { const int head = (pn & 3) * 4 + 2 * bj + (wc >> 1), half = wc & 1;
;                         unsigned* w = (pn < 12) ? NRM + 1024 + ((bg * 16 + head) * 32 + qb) * 2 + half : NRM + (bg * 16 + head) * 2 + half;
;                         __hip_atomic_fetch_max(w, __builtin_bit_cast(unsigned, mx * sc2 * 1.02f), __ATOMIC_RELAXED, __HIP_MEMORY_SCOPE_AGENT); } }
.LBB0_342:
	s_ff1_i32_b64 s7, s[52:53]
	v_readlane_b32 s18, v2, s7
	s_lshl_b64 s[54:55], 1, s7
	s_max_u32 s2, s2, s18
	s_andn2_b64 s[52:53], s[52:53], s[54:55]
	s_cmp_lg_u64 s[52:53], 0
	s_cbranch_scc1 .LBB0_342
	v_mbcnt_lo_u32_b32 v2, exec_lo, 0
	v_mbcnt_hi_u32_b32 v2, exec_hi, v2
	v_cmp_eq_u32_e32 vcc, 0, v2
	s_and_saveexec_b64 s[52:53], vcc
	s_xor_b64 s[52:53], exec, s[52:53]
	s_cbranch_execz .LBB0_345
	s_add_u32 s18, s36, s50
	s_addc_u32 s39, s37, s51
	s_ashr_i32 s7, s6, 31
	s_lshl_b64 s[6:7], s[6:7], 2
	s_add_u32 s6, s18, s6
	s_addc_u32 s7, s39, s7
	s_mov_b32 s18, 4
	v_mov_b32_e32 v2, s18
	v_mov_b32_e32 v3, s2
	global_atomic_umax v2, v3, s[6:7]

; __global__ void __launch_bounds__(NWAVES * 64, 2) hybrid_fwd(Args args) {
	.amdhsa_kernel _Z10hybrid_fwd4Args
		.amdhsa_group_segment_fixed_size 0
		.amdhsa_private_segment_fixed_size 0
		.amdhsa_kernarg_size 424
		.amdhsa_user_sgpr_count 2
		.amdhsa_user_sgpr_dispatch_ptr 0
		.amdhsa_user_sgpr_queue_ptr 0
		.amdhsa_user_sgpr_kernarg_segment_ptr 1
		.amdhsa_user_sgpr_dispatch_id 0
		.amdhsa_user_sgpr_kernarg_preload_length 0
		.amdhsa_user_sgpr_kernarg_preload_offset 0
		.amdhsa_user_sgpr_private_segment_size 0
		.amdhsa_uses_dynamic_stack 0
		.amdhsa_enable_private_segment 0
		.amdhsa_system_sgpr_workgroup_id_x 1
		.amdhsa_system_sgpr_workgroup_id_y 0
		.amdhsa_system_sgpr_workgroup_id_z 0
		.amdhsa_system_sgpr_workgroup_info 0
		.amdhsa_system_vgpr_workitem_id 2
		.amdhsa_next_free_vgpr 256
		.amdhsa_next_free_sgpr 102
		.amdhsa_accum_offset 256
		.amdhsa_reserve_vcc 1
		.amdhsa_float_round_mode_32 0
		.amdhsa_float_round_mode_16_64 0
		.amdhsa_float_denorm_mode_32 3
		.amdhsa_float_denorm_mode_16_64 3
		.amdhsa_dx10_clamp 1
		.amdhsa_ieee_mode 1
		.amdhsa_fp16_overflow 0
		.amdhsa_tg_split 0
		.amdhsa_exception_fp_ieee_invalid_op 0
		.amdhsa_exception_fp_denorm_src 0
		.amdhsa_exception_fp_ieee_div_zero 0
		.amdhsa_exception_fp_ieee_overflow 0
		.amdhsa_exception_fp_ieee_underflow 0
		.amdhsa_exception_fp_ieee_inexact 0
		.amdhsa_exception_int_div_zero 0
	.end_amdhsa_kernel

; __global__ void __launch_bounds__(NWAVES * 64, 2) hybrid_fwd(Args args) {
amdhsa.kernels:
  - .agpr_count:     0
    .args:
      - .offset:         0
        .size:           168
        .value_kind:     by_value
      - .offset:         168
        .size:           4
        .value_kind:     hidden_block_count_x
      - .offset:         172
        .size:           4
        .value_kind:     hidden_block_count_y
      - .offset:         176
        .size:           4
        .value_kind:     hidden_block_count_z
      - .offset:         180
        .size:           2
        .value_kind:     hidden_group_size_x
      - .offset:         182
        .size:           2
        .value_kind:     hidden_group_size_y
      - .offset:         184
        .size:           2
        .value_kind:     hidden_group_size_z
      - .offset:         186
        .size:           2
        .value_kind:     hidden_remainder_x
      - .offset:         188
        .size:           2
        .value_kind:     hidden_remainder_y
      - .offset:         190
        .size:           2
        .value_kind:     hidden_remainder_z
      - .offset:         208
        .size:           8
        .value_kind:     hidden_global_offset_x
      - .offset:         216
        .size:           8
        .value_kind:     hidden_global_offset_y
      - .offset:         224
        .size:           8
        .value_kind:     hidden_global_offset_z
      - .offset:         232
        .size:           2
        .value_kind:     hidden_grid_dims
      - .offset:         256
        .size:           8
        .value_kind:     hidden_multigrid_sync_arg
      - .offset:         288
        .size:           4
        .value_kind:     hidden_dynamic_lds_size
    .group_segment_fixed_size: 0
    .kernarg_segment_align: 8
    .kernarg_segment_size: 424
    .language:       OpenCL C
    .language_version:
      - 2
      - 0
    .max_flat_workgroup_size: 512
    .name:           _Z10hybrid_fwd4Args
    .private_segment_fixed_size: 0
    .sgpr_count:     108
    .sgpr_spill_count: 9
    .symbol:         _Z10hybrid_fwd4Args.kd
    .uniform_work_group_size: 1
    .uses_dynamic_stack: false
    .vgpr_count:     256
    .vgpr_spill_count: 0
    .wavefront_size: 64
